# setprio flips removed from the GEMM K-loops, no static raise (both halves at priority 0)
# baseline (speedup 1.0000x reference)
; #define PG8_STAGE(bufoff, gbase, voff) do { _Pragma("unroll") for (int _i = 0; _i < 2; ++_i) \
;         __builtin_amdgcn_global_load_lds((const unsigned*)((const char*)(gbase) + (voff)[_i]), (LAS unsigned*)(lds + (bufoff) + ldsw + _i * 8192), 16, 0, 0); } while (0)
; #define PG8_LDA(dst, b, h) do { _Pragma("unroll") for (int m = 0; m < 4; ++m) _Pragma("unroll") for (int k = 0; k < 2; ++k) dst[m][k] = *(const LAS bf16x8*)(lds + PG8_SA(b, h) + aoff + m * 2048 + k * 1024); } while (0)
; #define PG8_LDB(dst, b, h) do { _Pragma("unroll") for (int n = 0; n < 2; ++n) _Pragma("unroll") for (int k = 0; k < 2; ++k) dst[n][k] = *(const LAS bf16x8*)(lds + PG8_SB(b, h) + boff + n * 2048 + k * 1024); } while (0)
; #define PG8_MMA(ai, bj, At, Bt) do { __builtin_amdgcn_s_setprio(1); _Pragma("unroll") for (int m = 0; m < 4; ++m) _Pragma("unroll") for (int n = 0; n < 2; ++n) _Pragma("unroll") for (int k = 0; k < 2; ++k) \
;         acc[ai][bj][m][n] = __builtin_amdgcn_mfma_f32_16x16x32_bf16(Bt[n][k], At[m][k], acc[ai][bj][m][n], 0, 0, 0); __builtin_amdgcn_s_setprio(0); } while (0)
; #define PG8_WAIT_V(n) asm volatile("s_waitcnt vmcnt(" #n ")" ::: "memory")
; #define PG8_WAIT_L(n) asm volatile("s_waitcnt lgkmcnt(" #n ")" ::: "memory")
; #define PG8_BAR __builtin_amdgcn_s_barrier()
; template <class Sched, class Epi, bool ALIGN_EPI, bool SP2>
; __device__ __forceinline__ void gemm_phase(LAS unsigned char* lds, const int K, const int lda, const int ldb, const Sched& S, const Epi& E) {
;     ...
;         for (int t = 0; t < nt; t += 2) {
;             const bool last = (t == nt - 2);
;             const char* a1 = cA + (size_t)(t + 1) * kstep;
;             const char* a2 = last ? nA : cA + (size_t)(t + 2) * kstep; const char* b2 = last ? nB : cB + (size_t)(t + 2) * kstep;
;             const char* a3 = a2 + kstep; const char* b3 = b2 + kstep;
;             if constexpr (SP2) {
;             PG8_LDB(B0, 0, 0); PG8_LDB(B1, 0, 1); PG8_SCHED; PG8_LDA(At, 0, 0); PG8_STAGE(PG8_SA(1, 1), a1 + hstepA, voffA);
;             PG8_WAIT_V(8); PG8_WAIT_L(0); PG8_BAR; PG8_MMA(0, 0, At, B0); PG8_MMA(0, 1, At, B1); PG8_BAR; PG8_SCHED;
;             PG8_LDA(At, 0, 1); PG8_STAGE(PG8_SB(0, 0), b2, voffB); PG8_STAGE(PG8_SB(0, 1), b2 + hstepB, voffB); PG8_STAGE(PG8_SA(0, 0), a2, voffA);
;             PG8_WAIT_V(8); PG8_WAIT_L(0); PG8_BAR; PG8_MMA(1, 0, At, B0); PG8_MMA(1, 1, At, B1); PG8_BAR; PG8_SCHED;
.LBB0_155:
	ds_read_b128 v[140:143], v147
	ds_read_b128 v[150:153], v147 offset:1024
	ds_read_b128 v[154:157], v147 offset:2048
	ds_read_b128 v[158:161], v147 offset:3072
	ds_read_b128 v[162:165], v148
	ds_read_b128 v[166:169], v148 offset:1024
	ds_read_b128 v[170:173], v148 offset:2048
	ds_read_b128 v[180:183], v148 offset:3072
	s_add_u32 s22, s20, 0xfff80080
	s_addc_u32 s23, s21, -1
	s_cmp_eq_u32 s75, 28
	s_cselect_b32 s25, s15, s23
	s_cselect_b32 s24, s14, s22
	s_cselect_b32 s23, s17, s74
	s_cselect_b32 s22, s16, s13
	v_lshl_add_u64 v[174:175], s[20:21], 0, v[136:137]
	s_add_i32 m0, s3, 0xc000
	ds_read_b128 v[184:187], v149
	ds_read_b128 v[188:191], v149 offset:1024
	ds_read_b128 v[192:195], v149 offset:2048
	ds_read_b128 v[196:199], v149 offset:3072
	ds_read_b128 v[200:203], v149 offset:4096
	ds_read_b128 v[204:207], v149 offset:5120
	ds_read_b128 v[208:211], v149 offset:6144
	ds_read_b128 v[212:215], v149 offset:7168
	global_load_lds_dwordx4 v[174:175], off
	v_lshl_add_u64 v[174:175], s[20:21], 0, v[138:139]
	s_add_i32 m0, s3, 0xe000
	s_nop 0
	global_load_lds_dwordx4 v[174:175], off
	s_waitcnt vmcnt(8)
	s_waitcnt lgkmcnt(0)
	s_barrier
	s_waitcnt lgkmcnt(0)
	v_mfma_f32_16x16x32_bf16 v[124:127], v[140:143], v[184:187], v[124:127]
	v_mfma_f32_16x16x32_bf16 v[120:123], v[154:157], v[184:187], v[120:123]
	v_mfma_f32_16x16x32_bf16 v[108:111], v[140:143], v[192:195], v[108:111]
	v_mfma_f32_16x16x32_bf16 v[104:107], v[154:157], v[192:195], v[104:107]
	v_mfma_f32_16x16x32_bf16 v[92:95], v[140:143], v[200:203], v[92:95]
	v_mfma_f32_16x16x32_bf16 v[88:91], v[154:157], v[200:203], v[88:91]
	v_mfma_f32_16x16x32_bf16 v[76:79], v[140:143], v[208:211], v[76:79]
	v_mfma_f32_16x16x32_bf16 v[72:75], v[154:157], v[208:211], v[72:75]
	v_mfma_f32_16x16x32_bf16 v[124:127], v[150:153], v[188:191], v[124:127]
	v_mfma_f32_16x16x32_bf16 v[120:123], v[158:161], v[188:191], v[120:123]
	v_mfma_f32_16x16x32_bf16 v[108:111], v[150:153], v[196:199], v[108:111]
	v_mfma_f32_16x16x32_bf16 v[104:107], v[158:161], v[196:199], v[104:107]
	v_mfma_f32_16x16x32_bf16 v[92:95], v[150:153], v[204:207], v[92:95]
	v_mfma_f32_16x16x32_bf16 v[88:91], v[158:161], v[204:207], v[88:91]
	v_mfma_f32_16x16x32_bf16 v[76:79], v[150:153], v[212:215], v[76:79]
	v_mfma_f32_16x16x32_bf16 v[72:75], v[158:161], v[212:215], v[72:75]
	v_mfma_f32_16x16x32_bf16 v[116:119], v[162:165], v[184:187], v[116:119]
	v_mfma_f32_16x16x32_bf16 v[112:115], v[170:173], v[184:187], v[112:115]
	v_mfma_f32_16x16x32_bf16 v[100:103], v[162:165], v[192:195], v[100:103]
	v_mfma_f32_16x16x32_bf16 v[96:99], v[170:173], v[192:195], v[96:99]
	v_mfma_f32_16x16x32_bf16 v[84:87], v[162:165], v[200:203], v[84:87]
	v_mfma_f32_16x16x32_bf16 v[80:83], v[170:173], v[200:203], v[80:83]
	v_mfma_f32_16x16x32_bf16 v[68:71], v[162:165], v[208:211], v[68:71]
	v_mfma_f32_16x16x32_bf16 v[64:67], v[170:173], v[208:211], v[64:67]
	v_mfma_f32_16x16x32_bf16 v[116:119], v[166:169], v[188:191], v[116:119]
	v_mfma_f32_16x16x32_bf16 v[112:115], v[180:183], v[188:191], v[112:115]
	v_mfma_f32_16x16x32_bf16 v[100:103], v[166:169], v[196:199], v[100:103]
	v_mfma_f32_16x16x32_bf16 v[96:99], v[180:183], v[196:199], v[96:99]
	v_mfma_f32_16x16x32_bf16 v[84:87], v[166:169], v[204:207], v[84:87]
	v_mfma_f32_16x16x32_bf16 v[80:83], v[180:183], v[204:207], v[80:83]
	v_mfma_f32_16x16x32_bf16 v[68:71], v[166:169], v[212:215], v[68:71]
	v_mfma_f32_16x16x32_bf16 v[64:67], v[180:183], v[212:215], v[64:67]
	s_barrier
	s_add_i32 s78, s35, s2
	v_lshl_add_u64 v[174:175], s[22:23], 0, v[130:131]
	s_mov_b32 m0, s78
	ds_read_b128 v[184:187], v149 offset:16384
	ds_read_b128 v[188:191], v149 offset:17408
	ds_read_b128 v[192:195], v149 offset:18432
	ds_read_b128 v[196:199], v149 offset:19456
	ds_read_b128 v[200:203], v149 offset:20480
	ds_read_b128 v[204:207], v149 offset:21504
	ds_read_b128 v[208:211], v149 offset:22528
	ds_read_b128 v[212:215], v149 offset:23552
	global_load_lds_dwordx4 v[174:175], off
	s_add_i32 m0, s78, 0x2000
	s_add_u32 s78, s22, 0x80000
	v_lshl_add_u64 v[216:217], s[22:23], 0, v[134:135]
	s_addc_u32 s79, s23, 0
	s_add_i32 s84, s50, s2
	global_load_lds_dwordx4 v[216:217], off
	v_lshl_add_u64 v[218:219], s[78:79], 0, v[130:131]
	s_mov_b32 m0, s84
	v_lshl_add_u64 v[220:221], s[24:25], 0, v[132:133]
	global_load_lds_dwordx4 v[218:219], off
	v_lshl_add_u64 v[218:219], s[78:79], 0, v[134:135]
	s_add_i32 m0, s84, 0x2000
	s_nop 0
	global_load_lds_dwordx4 v[218:219], off
	v_lshl_add_u64 v[218:219], s[24:25], 0, v[128:129]
	s_mov_b32 m0, s3
	s_nop 0
	global_load_lds_dwordx4 v[218:219], off
	s_mov_b32 m0, s19
	s_nop 0
	global_load_lds_dwordx4 v[220:221], off
	s_waitcnt vmcnt(8)
	s_waitcnt lgkmcnt(0)
	s_barrier
; #define PG8_STAGE(bufoff, gbase, voff) do { _Pragma("unroll") for (int _i = 0; _i < 2; ++_i) \
;         __builtin_amdgcn_global_load_lds((const unsigned*)((const char*)(gbase) + (voff)[_i]), (LAS unsigned*)(lds + (bufoff) + ldsw + _i * 8192), 16, 0, 0); } while (0)
; #define PG8_LDA(dst, b, h) do { _Pragma("unroll") for (int m = 0; m < 4; ++m) _Pragma("unroll") for (int k = 0; k < 2; ++k) dst[m][k] = *(const LAS bf16x8*)(lds + PG8_SA(b, h) + aoff + m * 2048 + k * 1024); } while (0)
; #define PG8_LDB(dst, b, h) do { _Pragma("unroll") for (int n = 0; n < 2; ++n) _Pragma("unroll") for (int k = 0; k < 2; ++k) dst[n][k] = *(const LAS bf16x8*)(lds + PG8_SB(b, h) + boff + n * 2048 + k * 1024); } while (0)
; #define PG8_MMA(ai, bj, At, Bt) do { __builtin_amdgcn_s_setprio(1); _Pragma("unroll") for (int m = 0; m < 4; ++m) _Pragma("unroll") for (int n = 0; n < 2; ++n) _Pragma("unroll") for (int k = 0; k < 2; ++k) \
;         acc[ai][bj][m][n] = __builtin_amdgcn_mfma_f32_16x16x32_bf16(Bt[n][k], At[m][k], acc[ai][bj][m][n], 0, 0, 0); __builtin_amdgcn_s_setprio(0); } while (0)
; #define PG8_WAIT_V(n) asm volatile("s_waitcnt vmcnt(" #n ")" ::: "memory")
; #define PG8_WAIT_L(n) asm volatile("s_waitcnt lgkmcnt(" #n ")" ::: "memory")
; #define PG8_BAR __builtin_amdgcn_s_barrier()
; #define PG8_SCHED __builtin_amdgcn_sched_barrier(0)
; template <class Sched, class Epi, bool ALIGN_EPI, bool SP2>
; __device__ __forceinline__ void gemm_phase(LAS unsigned char* lds, const int K, const int lda, const int ldb, const Sched& S, const Epi& E) {
;     ...
;             PG8_WAIT_V(8); PG8_WAIT_L(0); PG8_BAR; PG8_MMA(1, 0, At, B0); PG8_MMA(1, 1, At, B1); PG8_BAR; PG8_SCHED;
;             PG8_LDB(B0, 1, 0); PG8_LDB(B1, 1, 1); PG8_SCHED; PG8_LDA(At, 1, 0); PG8_STAGE(PG8_SA(0, 1), a2 + hstepA, voffA);
;             PG8_WAIT_V(8); PG8_WAIT_L(0); PG8_BAR; PG8_MMA(0, 0, At, B0); PG8_MMA(0, 1, At, B1); PG8_BAR; PG8_SCHED;
;             PG8_LDA(At, 1, 1); PG8_STAGE(PG8_SB(1, 0), b3, voffB); PG8_STAGE(PG8_SB(1, 1), b3 + hstepB, voffB); PG8_STAGE(PG8_SA(1, 0), a3, voffA);
	s_waitcnt lgkmcnt(0)
	v_mfma_f32_16x16x32_bf16 v[60:63], v[140:143], v[184:187], v[60:63]
	v_mfma_f32_16x16x32_bf16 v[56:59], v[154:157], v[184:187], v[56:59]
	v_mfma_f32_16x16x32_bf16 v[44:47], v[140:143], v[192:195], v[44:47]
	v_mfma_f32_16x16x32_bf16 v[40:43], v[154:157], v[192:195], v[40:43]
	v_mfma_f32_16x16x32_bf16 v[28:31], v[140:143], v[200:203], v[28:31]
	v_mfma_f32_16x16x32_bf16 v[24:27], v[154:157], v[200:203], v[24:27]
	v_mfma_f32_16x16x32_bf16 v[12:15], v[140:143], v[208:211], v[12:15]
	v_mfma_f32_16x16x32_bf16 v[8:11], v[154:157], v[208:211], v[8:11]
	v_mfma_f32_16x16x32_bf16 v[60:63], v[150:153], v[188:191], v[60:63]
	v_mfma_f32_16x16x32_bf16 v[56:59], v[158:161], v[188:191], v[56:59]
	v_mfma_f32_16x16x32_bf16 v[44:47], v[150:153], v[196:199], v[44:47]
	v_mfma_f32_16x16x32_bf16 v[40:43], v[158:161], v[196:199], v[40:43]
	v_mfma_f32_16x16x32_bf16 v[28:31], v[150:153], v[204:207], v[28:31]
	v_mfma_f32_16x16x32_bf16 v[24:27], v[158:161], v[204:207], v[24:27]
	v_mfma_f32_16x16x32_bf16 v[12:15], v[150:153], v[212:215], v[12:15]
	v_mfma_f32_16x16x32_bf16 v[8:11], v[158:161], v[212:215], v[8:11]
	v_mfma_f32_16x16x32_bf16 v[52:55], v[162:165], v[184:187], v[52:55]
	v_mfma_f32_16x16x32_bf16 v[48:51], v[170:173], v[184:187], v[48:51]
	v_mfma_f32_16x16x32_bf16 v[36:39], v[162:165], v[192:195], v[36:39]
	v_mfma_f32_16x16x32_bf16 v[32:35], v[170:173], v[192:195], v[32:35]
	v_mfma_f32_16x16x32_bf16 v[20:23], v[162:165], v[200:203], v[20:23]
	v_mfma_f32_16x16x32_bf16 v[16:19], v[170:173], v[200:203], v[16:19]
	v_mfma_f32_16x16x32_bf16 v[4:7], v[162:165], v[208:211], v[4:7]
	v_mfma_f32_16x16x32_bf16 v[0:3], v[170:173], v[208:211], v[0:3]
	v_mfma_f32_16x16x32_bf16 v[52:55], v[166:169], v[188:191], v[52:55]
	v_mfma_f32_16x16x32_bf16 v[48:51], v[180:183], v[188:191], v[48:51]
	v_mfma_f32_16x16x32_bf16 v[36:39], v[166:169], v[196:199], v[36:39]
	v_mfma_f32_16x16x32_bf16 v[32:35], v[180:183], v[196:199], v[32:35]
	v_mfma_f32_16x16x32_bf16 v[20:23], v[166:169], v[204:207], v[20:23]
	v_mfma_f32_16x16x32_bf16 v[16:19], v[180:183], v[204:207], v[16:19]
	v_mfma_f32_16x16x32_bf16 v[4:7], v[166:169], v[212:215], v[4:7]
	v_mfma_f32_16x16x32_bf16 v[0:3], v[180:183], v[212:215], v[0:3]
	s_barrier
	s_add_i32 s78, 0, 0x18000
	s_add_i32 s79, 0, 0x1c000
	v_add_u32_e32 v158, s78, v145
	v_add_u32_e32 v177, s79, v145
	ds_read_b128 v[140:143], v158
	ds_read_b128 v[150:153], v158 offset:1024
	ds_read_b128 v[154:157], v158 offset:2048
	ds_read_b128 v[158:161], v158 offset:3072
	ds_read_b128 v[162:165], v177
	ds_read_b128 v[166:169], v177 offset:1024
	ds_read_b128 v[170:173], v177 offset:2048
	ds_read_b128 v[180:183], v177 offset:3072
	s_add_u32 s24, s24, 0x80000
	s_addc_u32 s25, s25, 0
	s_mov_b32 m0, s26
	v_lshl_add_u64 v[222:223], s[24:25], 0, v[128:129]
	ds_read_b128 v[184:187], v149 offset:32768
	ds_read_b128 v[188:191], v149 offset:33792
	ds_read_b128 v[192:195], v149 offset:34816
	ds_read_b128 v[196:199], v149 offset:35840
	ds_read_b128 v[200:203], v149 offset:36864
	ds_read_b128 v[204:207], v149 offset:37888
	ds_read_b128 v[208:211], v149 offset:38912
	ds_read_b128 v[212:215], v149 offset:39936
	global_load_lds_dwordx4 v[222:223], off
	v_lshl_add_u64 v[222:223], s[24:25], 0, v[132:133]
	s_mov_b32 m0, s27
	s_nop 0
	global_load_lds_dwordx4 v[222:223], off
	s_waitcnt vmcnt(8)
	s_waitcnt lgkmcnt(0)
	s_barrier
	s_waitcnt lgkmcnt(0)
	v_mfma_f32_16x16x32_bf16 v[124:127], v[140:143], v[184:187], v[124:127]
	v_mfma_f32_16x16x32_bf16 v[120:123], v[154:157], v[184:187], v[120:123]
	v_mfma_f32_16x16x32_bf16 v[108:111], v[140:143], v[192:195], v[108:111]
	v_mfma_f32_16x16x32_bf16 v[104:107], v[154:157], v[192:195], v[104:107]
	v_mfma_f32_16x16x32_bf16 v[92:95], v[140:143], v[200:203], v[92:95]
	v_mfma_f32_16x16x32_bf16 v[88:91], v[154:157], v[200:203], v[88:91]
	v_mfma_f32_16x16x32_bf16 v[76:79], v[140:143], v[208:211], v[76:79]
	v_mfma_f32_16x16x32_bf16 v[72:75], v[154:157], v[208:211], v[72:75]
	v_mfma_f32_16x16x32_bf16 v[124:127], v[150:153], v[188:191], v[124:127]
	v_mfma_f32_16x16x32_bf16 v[120:123], v[158:161], v[188:191], v[120:123]
	v_mfma_f32_16x16x32_bf16 v[108:111], v[150:153], v[196:199], v[108:111]
	v_mfma_f32_16x16x32_bf16 v[104:107], v[158:161], v[196:199], v[104:107]
	v_mfma_f32_16x16x32_bf16 v[92:95], v[150:153], v[204:207], v[92:95]
	v_mfma_f32_16x16x32_bf16 v[88:91], v[158:161], v[204:207], v[88:91]
	v_mfma_f32_16x16x32_bf16 v[76:79], v[150:153], v[212:215], v[76:79]
	v_mfma_f32_16x16x32_bf16 v[72:75], v[158:161], v[212:215], v[72:75]
	v_mfma_f32_16x16x32_bf16 v[116:119], v[162:165], v[184:187], v[116:119]
	v_mfma_f32_16x16x32_bf16 v[112:115], v[170:173], v[184:187], v[112:115]
	v_mfma_f32_16x16x32_bf16 v[100:103], v[162:165], v[192:195], v[100:103]
	v_mfma_f32_16x16x32_bf16 v[96:99], v[170:173], v[192:195], v[96:99]
	v_mfma_f32_16x16x32_bf16 v[84:87], v[162:165], v[200:203], v[84:87]
	v_mfma_f32_16x16x32_bf16 v[80:83], v[170:173], v[200:203], v[80:83]
	v_mfma_f32_16x16x32_bf16 v[68:71], v[162:165], v[208:211], v[68:71]
	v_mfma_f32_16x16x32_bf16 v[64:67], v[170:173], v[208:211], v[64:67]
	v_mfma_f32_16x16x32_bf16 v[116:119], v[166:169], v[188:191], v[116:119]
	v_mfma_f32_16x16x32_bf16 v[112:115], v[180:183], v[188:191], v[112:115]
	v_mfma_f32_16x16x32_bf16 v[100:103], v[166:169], v[196:199], v[100:103]
	v_mfma_f32_16x16x32_bf16 v[96:99], v[180:183], v[196:199], v[96:99]
	v_mfma_f32_16x16x32_bf16 v[84:87], v[166:169], v[204:207], v[84:87]
	v_mfma_f32_16x16x32_bf16 v[80:83], v[180:183], v[204:207], v[80:83]
	v_mfma_f32_16x16x32_bf16 v[68:71], v[166:169], v[212:215], v[68:71]
	v_mfma_f32_16x16x32_bf16 v[64:67], v[180:183], v[212:215], v[64:67]
	s_barrier
; #define PG8_STAGE(bufoff, gbase, voff) do { _Pragma("unroll") for (int _i = 0; _i < 2; ++_i) \
;         __builtin_amdgcn_global_load_lds((const unsigned*)((const char*)(gbase) + (voff)[_i]), (LAS unsigned*)(lds + (bufoff) + ldsw + _i * 8192), 16, 0, 0); } while (0)
; #define PG8_LDA(dst, b, h) do { _Pragma("unroll") for (int m = 0; m < 4; ++m) _Pragma("unroll") for (int k = 0; k < 2; ++k) dst[m][k] = *(const LAS bf16x8*)(lds + PG8_SA(b, h) + aoff + m * 2048 + k * 1024); } while (0)
; #define PG8_MMA(ai, bj, At, Bt) do { __builtin_amdgcn_s_setprio(1); _Pragma("unroll") for (int m = 0; m < 4; ++m) _Pragma("unroll") for (int n = 0; n < 2; ++n) _Pragma("unroll") for (int k = 0; k < 2; ++k) \
;         acc[ai][bj][m][n] = __builtin_amdgcn_mfma_f32_16x16x32_bf16(Bt[n][k], At[m][k], acc[ai][bj][m][n], 0, 0, 0); __builtin_amdgcn_s_setprio(0); } while (0)
; #define PG8_WAIT_V(n) asm volatile("s_waitcnt vmcnt(" #n ")" ::: "memory")
; #define PG8_WAIT_L(n) asm volatile("s_waitcnt lgkmcnt(" #n ")" ::: "memory")
; #define PG8_BAR __builtin_amdgcn_s_barrier()
; #define PG8_SCHED __builtin_amdgcn_sched_barrier(0)
; template <class Sched, class Epi, bool ALIGN_EPI, bool SP2>
; __device__ __forceinline__ void gemm_phase(LAS unsigned char* lds, const int K, const int lda, const int ldb, const Sched& S, const Epi& E) {
;     ...
;             PG8_LDA(At, 1, 1); PG8_STAGE(PG8_SB(1, 0), b3, voffB); PG8_STAGE(PG8_SB(1, 1), b3 + hstepB, voffB); PG8_STAGE(PG8_SA(1, 0), a3, voffA);
;             PG8_WAIT_V(8); PG8_WAIT_L(0); PG8_BAR; PG8_MMA(1, 0, At, B0); PG8_MMA(1, 1, At, B1); PG8_BAR; PG8_SCHED;
	s_add_i32 s24, s78, s2
	v_lshl_add_u64 v[174:175], v[174:175], 0, s[4:5]
	s_mov_b32 m0, s24
	ds_read_b128 v[184:187], v149 offset:49152
	ds_read_b128 v[188:191], v149 offset:50176
	ds_read_b128 v[192:195], v149 offset:51200
	ds_read_b128 v[196:199], v149 offset:52224
	ds_read_b128 v[200:203], v149 offset:53248
	ds_read_b128 v[204:207], v149 offset:54272
	ds_read_b128 v[208:211], v149 offset:55296
	ds_read_b128 v[212:215], v149 offset:56320
	global_load_lds_dwordx4 v[174:175], off
	s_add_i32 m0, s24, 0x2000
	s_add_u32 s22, s22, 0x80080
	v_lshl_add_u64 v[174:175], v[216:217], 0, s[4:5]
	s_addc_u32 s23, s23, 0
	s_add_i32 s24, s79, s2
	global_load_lds_dwordx4 v[174:175], off
	v_lshl_add_u64 v[174:175], s[22:23], 0, v[130:131]
	s_mov_b32 m0, s24
	s_nop 0
	global_load_lds_dwordx4 v[174:175], off
	v_lshl_add_u64 v[174:175], s[22:23], 0, v[134:135]
	s_add_i32 m0, s24, 0x2000
	s_nop 0
	global_load_lds_dwordx4 v[174:175], off
	v_lshl_add_u64 v[174:175], v[218:219], 0, s[4:5]
	s_mov_b32 m0, s29
	s_nop 0
	global_load_lds_dwordx4 v[174:175], off
	v_lshl_add_u64 v[174:175], v[220:221], 0, s[4:5]
	s_mov_b32 m0, s33
	s_nop 0
	global_load_lds_dwordx4 v[174:175], off
	s_waitcnt vmcnt(8)
	s_waitcnt lgkmcnt(0)
	s_barrier
	s_waitcnt lgkmcnt(0)
	v_mfma_f32_16x16x32_bf16 v[60:63], v[140:143], v[184:187], v[60:63]
	v_mfma_f32_16x16x32_bf16 v[56:59], v[154:157], v[184:187], v[56:59]
	v_mfma_f32_16x16x32_bf16 v[44:47], v[140:143], v[192:195], v[44:47]
	v_mfma_f32_16x16x32_bf16 v[40:43], v[154:157], v[192:195], v[40:43]
	v_mfma_f32_16x16x32_bf16 v[28:31], v[140:143], v[200:203], v[28:31]
	v_mfma_f32_16x16x32_bf16 v[24:27], v[154:157], v[200:203], v[24:27]
	v_mfma_f32_16x16x32_bf16 v[12:15], v[140:143], v[208:211], v[12:15]
	v_mfma_f32_16x16x32_bf16 v[8:11], v[154:157], v[208:211], v[8:11]
	v_mfma_f32_16x16x32_bf16 v[60:63], v[150:153], v[188:191], v[60:63]
	v_mfma_f32_16x16x32_bf16 v[56:59], v[158:161], v[188:191], v[56:59]
	v_mfma_f32_16x16x32_bf16 v[44:47], v[150:153], v[196:199], v[44:47]
	v_mfma_f32_16x16x32_bf16 v[40:43], v[158:161], v[196:199], v[40:43]
	v_mfma_f32_16x16x32_bf16 v[28:31], v[150:153], v[204:207], v[28:31]
	v_mfma_f32_16x16x32_bf16 v[24:27], v[158:161], v[204:207], v[24:27]
	v_mfma_f32_16x16x32_bf16 v[12:15], v[150:153], v[212:215], v[12:15]
	v_mfma_f32_16x16x32_bf16 v[8:11], v[158:161], v[212:215], v[8:11]
	v_mfma_f32_16x16x32_bf16 v[52:55], v[162:165], v[184:187], v[52:55]
	v_mfma_f32_16x16x32_bf16 v[48:51], v[170:173], v[184:187], v[48:51]
	v_mfma_f32_16x16x32_bf16 v[36:39], v[162:165], v[192:195], v[36:39]
	v_mfma_f32_16x16x32_bf16 v[32:35], v[170:173], v[192:195], v[32:35]
	v_mfma_f32_16x16x32_bf16 v[20:23], v[162:165], v[200:203], v[20:23]
	v_mfma_f32_16x16x32_bf16 v[16:19], v[170:173], v[200:203], v[16:19]
	v_mfma_f32_16x16x32_bf16 v[4:7], v[162:165], v[208:211], v[4:7]
	v_mfma_f32_16x16x32_bf16 v[0:3], v[170:173], v[208:211], v[0:3]
	v_mfma_f32_16x16x32_bf16 v[52:55], v[166:169], v[188:191], v[52:55]
	v_mfma_f32_16x16x32_bf16 v[48:51], v[180:183], v[188:191], v[48:51]
	v_mfma_f32_16x16x32_bf16 v[36:39], v[166:169], v[196:199], v[36:39]
	v_mfma_f32_16x16x32_bf16 v[32:35], v[180:183], v[196:199], v[32:35]
	v_mfma_f32_16x16x32_bf16 v[20:23], v[166:169], v[204:207], v[20:23]
	v_mfma_f32_16x16x32_bf16 v[16:19], v[180:183], v[204:207], v[16:19]
	v_mfma_f32_16x16x32_bf16 v[4:7], v[166:169], v[212:215], v[4:7]
	v_mfma_f32_16x16x32_bf16 v[0:3], v[180:183], v[212:215], v[0:3]
	s_barrier
	s_add_i32 s75, s75, 2
	s_add_u32 s20, s20, 0x100
	s_addc_u32 s21, s21, 0
	s_add_u32 s13, s13, 0x100
	s_addc_u32 s74, s74, 0
	s_cmp_gt_u32 s75, 29
	s_cbranch_scc0 .LBB0_155
	s_and_b64 vcc, exec, s[6:7]
	s_cbranch_vccz .LBB0_158
	s_barrier

; #define PG8_STAGE(bufoff, gbase, voff) do { _Pragma("unroll") for (int _i = 0; _i < 2; ++_i) \
;         __builtin_amdgcn_global_load_lds((const unsigned*)((const char*)(gbase) + (voff)[_i]), (LAS unsigned*)(lds + (bufoff) + ldsw + _i * 8192), 16, 0, 0); } while (0)
; #define PG8_LDA(dst, b, h) do { _Pragma("unroll") for (int m = 0; m < 4; ++m) _Pragma("unroll") for (int k = 0; k < 2; ++k) dst[m][k] = *(const LAS bf16x8*)(lds + PG8_SA(b, h) + aoff + m * 2048 + k * 1024); } while (0)
; #define PG8_LDB(dst, b, h) do { _Pragma("unroll") for (int n = 0; n < 2; ++n) _Pragma("unroll") for (int k = 0; k < 2; ++k) dst[n][k] = *(const LAS bf16x8*)(lds + PG8_SB(b, h) + boff + n * 2048 + k * 1024); } while (0)
; #define PG8_MMA(ai, bj, At, Bt) do { __builtin_amdgcn_s_setprio(1); _Pragma("unroll") for (int m = 0; m < 4; ++m) _Pragma("unroll") for (int n = 0; n < 2; ++n) _Pragma("unroll") for (int k = 0; k < 2; ++k) \
;         acc[ai][bj][m][n] = __builtin_amdgcn_mfma_f32_16x16x32_bf16(Bt[n][k], At[m][k], acc[ai][bj][m][n], 0, 0, 0); __builtin_amdgcn_s_setprio(0); } while (0)
; #define PG8_WAIT_V(n) asm volatile("s_waitcnt vmcnt(" #n ")" ::: "memory")
; #define PG8_WAIT_L(n) asm volatile("s_waitcnt lgkmcnt(" #n ")" ::: "memory")
; #define PG8_BAR __builtin_amdgcn_s_barrier()
; template <class Sched, class Epi, bool ALIGN_EPI, bool SP2>
; __device__ __forceinline__ void gemm_phase(LAS unsigned char* lds, const int K, const int lda, const int ldb, const Sched& S, const Epi& E) {
;     ...
;         for (int t = 0; t < nt; t += 2) {
;             const bool last = (t == nt - 2);
;             const char* a1 = cA + (size_t)(t + 1) * kstep;
;             const char* a2 = last ? nA : cA + (size_t)(t + 2) * kstep; const char* b2 = last ? nB : cB + (size_t)(t + 2) * kstep;
;             const char* a3 = a2 + kstep; const char* b3 = b2 + kstep;
;             if constexpr (SP2) {
;             PG8_LDB(B0, 0, 0); PG8_LDB(B1, 0, 1); PG8_SCHED; PG8_LDA(At, 0, 0); PG8_STAGE(PG8_SA(1, 1), a1 + hstepA, voffA);
;             PG8_WAIT_V(8); PG8_WAIT_L(0); PG8_BAR; PG8_MMA(0, 0, At, B0); PG8_MMA(0, 1, At, B1); PG8_BAR; PG8_SCHED;
;             PG8_LDA(At, 0, 1); PG8_STAGE(PG8_SB(0, 0), b2, voffB); PG8_STAGE(PG8_SB(0, 1), b2 + hstepB, voffB); PG8_STAGE(PG8_SA(0, 0), a2, voffA);
;             PG8_WAIT_V(8); PG8_WAIT_L(0); PG8_BAR; PG8_MMA(1, 0, At, B0); PG8_MMA(1, 1, At, B1); PG8_BAR; PG8_SCHED;
.LBB0_243:
	ds_read_b128 v[124:127], v169
	ds_read_b128 v[132:135], v169 offset:1024
	ds_read_b128 v[136:139], v169 offset:2048
	ds_read_b128 v[140:143], v169 offset:3072
	ds_read_b128 v[144:147], v170
	ds_read_b128 v[156:159], v170 offset:1024
	ds_read_b128 v[160:163], v170 offset:2048
	ds_read_b128 v[182:185], v170 offset:3072
	s_add_u32 s22, s20, 0x100
	s_addc_u32 s23, s21, 0
	s_cmpk_eq_i32 s91, 0x54
	s_cselect_b32 s27, s17, s23
	s_cselect_b32 s26, s16, s22
	s_cselect_b32 s25, s19, s90
	s_cselect_b32 s24, s18, s89
	s_mov_b32 m0, s78
	v_lshl_add_u64 v[164:165], s[20:21], 0, v[152:153]
	ds_read_b128 v[186:189], v171
	ds_read_b128 v[190:193], v171 offset:1024
	ds_read_b128 v[194:197], v171 offset:2048
	ds_read_b128 v[198:201], v171 offset:3072
	ds_read_b128 v[202:205], v171 offset:4096
	ds_read_b128 v[206:209], v171 offset:5120
	ds_read_b128 v[210:213], v171 offset:6144
	ds_read_b128 v[214:217], v171 offset:7168
	global_load_lds_dwordx4 v[164:165], off
	v_lshl_add_u64 v[164:165], s[20:21], 0, v[154:155]
	s_mov_b32 m0, s79
	s_nop 0
	global_load_lds_dwordx4 v[164:165], off
	s_waitcnt vmcnt(8)
	s_waitcnt lgkmcnt(0)
	s_barrier
	s_waitcnt lgkmcnt(0)
	v_mfma_f32_16x16x32_bf16 v[128:131], v[124:127], v[186:189], v[128:131]
	v_mfma_f32_16x16x32_bf16 v[120:123], v[136:139], v[186:189], v[120:123]
	v_mfma_f32_16x16x32_bf16 v[108:111], v[124:127], v[194:197], v[108:111]
	v_mfma_f32_16x16x32_bf16 v[104:107], v[136:139], v[194:197], v[104:107]
	v_mfma_f32_16x16x32_bf16 v[92:95], v[124:127], v[202:205], v[92:95]
	v_mfma_f32_16x16x32_bf16 v[88:91], v[136:139], v[202:205], v[88:91]
	v_mfma_f32_16x16x32_bf16 v[76:79], v[124:127], v[210:213], v[76:79]
	v_mfma_f32_16x16x32_bf16 v[72:75], v[136:139], v[210:213], v[72:75]
	v_mfma_f32_16x16x32_bf16 v[128:131], v[132:135], v[190:193], v[128:131]
	v_mfma_f32_16x16x32_bf16 v[120:123], v[140:143], v[190:193], v[120:123]
	v_mfma_f32_16x16x32_bf16 v[108:111], v[132:135], v[198:201], v[108:111]
	v_mfma_f32_16x16x32_bf16 v[104:107], v[140:143], v[198:201], v[104:107]
	v_mfma_f32_16x16x32_bf16 v[92:95], v[132:135], v[206:209], v[92:95]
	v_mfma_f32_16x16x32_bf16 v[88:91], v[140:143], v[206:209], v[88:91]
	v_mfma_f32_16x16x32_bf16 v[76:79], v[132:135], v[214:217], v[76:79]
	v_mfma_f32_16x16x32_bf16 v[72:75], v[140:143], v[214:217], v[72:75]
	v_mfma_f32_16x16x32_bf16 v[116:119], v[144:147], v[186:189], v[116:119]
	v_mfma_f32_16x16x32_bf16 v[112:115], v[160:163], v[186:189], v[112:115]
	v_mfma_f32_16x16x32_bf16 v[100:103], v[144:147], v[194:197], v[100:103]
	v_mfma_f32_16x16x32_bf16 v[96:99], v[160:163], v[194:197], v[96:99]
	v_mfma_f32_16x16x32_bf16 v[84:87], v[144:147], v[202:205], v[84:87]
	v_mfma_f32_16x16x32_bf16 v[80:83], v[160:163], v[202:205], v[80:83]
	v_mfma_f32_16x16x32_bf16 v[68:71], v[144:147], v[210:213], v[68:71]
	v_mfma_f32_16x16x32_bf16 v[64:67], v[160:163], v[210:213], v[64:67]
	v_mfma_f32_16x16x32_bf16 v[116:119], v[156:159], v[190:193], v[116:119]
	v_mfma_f32_16x16x32_bf16 v[112:115], v[182:185], v[190:193], v[112:115]
	v_mfma_f32_16x16x32_bf16 v[100:103], v[156:159], v[198:201], v[100:103]
	v_mfma_f32_16x16x32_bf16 v[96:99], v[182:185], v[198:201], v[96:99]
	v_mfma_f32_16x16x32_bf16 v[84:87], v[156:159], v[206:209], v[84:87]
	v_mfma_f32_16x16x32_bf16 v[80:83], v[182:185], v[206:209], v[80:83]
	v_mfma_f32_16x16x32_bf16 v[68:71], v[156:159], v[214:217], v[68:71]
	v_mfma_f32_16x16x32_bf16 v[64:67], v[182:185], v[214:217], v[64:67]
	s_barrier
	s_mov_b32 m0, s84
	v_lshl_add_u64 v[164:165], s[24:25], 0, v[148:149]
	ds_read_b128 v[186:189], v171 offset:16384
	ds_read_b128 v[190:193], v171 offset:17408
	ds_read_b128 v[194:197], v171 offset:18432
	ds_read_b128 v[198:201], v171 offset:19456
	ds_read_b128 v[202:205], v171 offset:20480
	ds_read_b128 v[206:209], v171 offset:21504
	ds_read_b128 v[210:213], v171 offset:22528
	ds_read_b128 v[214:217], v171 offset:23552
	global_load_lds_dwordx4 v[164:165], off
	s_add_i32 m0, s84, 0x2000
	s_add_u32 s20, s24, 0x160000
	v_lshl_add_u64 v[174:175], s[24:25], 0, v[150:151]
	s_addc_u32 s21, s25, 0
	s_add_i32 s96, s53, s13
	global_load_lds_dwordx4 v[174:175], off
	v_lshl_add_u64 v[218:219], s[20:21], 0, v[148:149]
	s_mov_b32 m0, s96
	v_lshl_add_u64 v[220:221], s[26:27], 0, v[150:151]
	global_load_lds_dwordx4 v[218:219], off
	v_lshl_add_u64 v[218:219], s[20:21], 0, v[150:151]
	s_add_i32 m0, s96, 0x2000
	s_nop 0
	global_load_lds_dwordx4 v[218:219], off
	v_lshl_add_u64 v[218:219], s[26:27], 0, v[148:149]
	s_mov_b32 m0, s28
	s_nop 0
	global_load_lds_dwordx4 v[218:219], off
	s_mov_b32 m0, s29
	s_nop 0
	global_load_lds_dwordx4 v[220:221], off
	s_waitcnt vmcnt(8)
	s_waitcnt lgkmcnt(0)
	s_barrier
; #define PG8_STAGE(bufoff, gbase, voff) do { _Pragma("unroll") for (int _i = 0; _i < 2; ++_i) \
;         __builtin_amdgcn_global_load_lds((const unsigned*)((const char*)(gbase) + (voff)[_i]), (LAS unsigned*)(lds + (bufoff) + ldsw + _i * 8192), 16, 0, 0); } while (0)
; #define PG8_LDA(dst, b, h) do { _Pragma("unroll") for (int m = 0; m < 4; ++m) _Pragma("unroll") for (int k = 0; k < 2; ++k) dst[m][k] = *(const LAS bf16x8*)(lds + PG8_SA(b, h) + aoff + m * 2048 + k * 1024); } while (0)
; #define PG8_LDB(dst, b, h) do { _Pragma("unroll") for (int n = 0; n < 2; ++n) _Pragma("unroll") for (int k = 0; k < 2; ++k) dst[n][k] = *(const LAS bf16x8*)(lds + PG8_SB(b, h) + boff + n * 2048 + k * 1024); } while (0)
; #define PG8_MMA(ai, bj, At, Bt) do { __builtin_amdgcn_s_setprio(1); _Pragma("unroll") for (int m = 0; m < 4; ++m) _Pragma("unroll") for (int n = 0; n < 2; ++n) _Pragma("unroll") for (int k = 0; k < 2; ++k) \
;         acc[ai][bj][m][n] = __builtin_amdgcn_mfma_f32_16x16x32_bf16(Bt[n][k], At[m][k], acc[ai][bj][m][n], 0, 0, 0); __builtin_amdgcn_s_setprio(0); } while (0)
; #define PG8_WAIT_V(n) asm volatile("s_waitcnt vmcnt(" #n ")" ::: "memory")
; #define PG8_WAIT_L(n) asm volatile("s_waitcnt lgkmcnt(" #n ")" ::: "memory")
; #define PG8_BAR __builtin_amdgcn_s_barrier()
; #define PG8_SCHED __builtin_amdgcn_sched_barrier(0)
; template <class Sched, class Epi, bool ALIGN_EPI, bool SP2>
; __device__ __forceinline__ void gemm_phase(LAS unsigned char* lds, const int K, const int lda, const int ldb, const Sched& S, const Epi& E) {
;     ...
;             PG8_WAIT_V(8); PG8_WAIT_L(0); PG8_BAR; PG8_MMA(1, 0, At, B0); PG8_MMA(1, 1, At, B1); PG8_BAR; PG8_SCHED;
;             PG8_LDB(B0, 1, 0); PG8_LDB(B1, 1, 1); PG8_SCHED; PG8_LDA(At, 1, 0); PG8_STAGE(PG8_SA(0, 1), a2 + hstepA, voffA);
;             PG8_WAIT_V(8); PG8_WAIT_L(0); PG8_BAR; PG8_MMA(0, 0, At, B0); PG8_MMA(0, 1, At, B1); PG8_BAR; PG8_SCHED;
;             PG8_LDA(At, 1, 1); PG8_STAGE(PG8_SB(1, 0), b3, voffB); PG8_STAGE(PG8_SB(1, 1), b3 + hstepB, voffB); PG8_STAGE(PG8_SA(1, 0), a3, voffA);
	s_waitcnt lgkmcnt(0)
	v_mfma_f32_16x16x32_bf16 v[60:63], v[124:127], v[186:189], v[60:63]
	v_mfma_f32_16x16x32_bf16 v[56:59], v[136:139], v[186:189], v[56:59]
	v_mfma_f32_16x16x32_bf16 v[44:47], v[124:127], v[194:197], v[44:47]
	v_mfma_f32_16x16x32_bf16 v[40:43], v[136:139], v[194:197], v[40:43]
	v_mfma_f32_16x16x32_bf16 v[28:31], v[124:127], v[202:205], v[28:31]
	v_mfma_f32_16x16x32_bf16 v[24:27], v[136:139], v[202:205], v[24:27]
	v_mfma_f32_16x16x32_bf16 v[12:15], v[124:127], v[210:213], v[12:15]
	v_mfma_f32_16x16x32_bf16 v[8:11], v[136:139], v[210:213], v[8:11]
	v_mfma_f32_16x16x32_bf16 v[60:63], v[132:135], v[190:193], v[60:63]
	v_mfma_f32_16x16x32_bf16 v[56:59], v[140:143], v[190:193], v[56:59]
	v_mfma_f32_16x16x32_bf16 v[44:47], v[132:135], v[198:201], v[44:47]
	v_mfma_f32_16x16x32_bf16 v[40:43], v[140:143], v[198:201], v[40:43]
	v_mfma_f32_16x16x32_bf16 v[28:31], v[132:135], v[206:209], v[28:31]
	v_mfma_f32_16x16x32_bf16 v[24:27], v[140:143], v[206:209], v[24:27]
	v_mfma_f32_16x16x32_bf16 v[12:15], v[132:135], v[214:217], v[12:15]
	v_mfma_f32_16x16x32_bf16 v[8:11], v[140:143], v[214:217], v[8:11]
	v_mfma_f32_16x16x32_bf16 v[52:55], v[144:147], v[186:189], v[52:55]
	v_mfma_f32_16x16x32_bf16 v[48:51], v[160:163], v[186:189], v[48:51]
	v_mfma_f32_16x16x32_bf16 v[36:39], v[144:147], v[194:197], v[36:39]
	v_mfma_f32_16x16x32_bf16 v[32:35], v[160:163], v[194:197], v[32:35]
	v_mfma_f32_16x16x32_bf16 v[20:23], v[144:147], v[202:205], v[20:23]
	v_mfma_f32_16x16x32_bf16 v[16:19], v[160:163], v[202:205], v[16:19]
	v_mfma_f32_16x16x32_bf16 v[4:7], v[144:147], v[210:213], v[4:7]
	v_mfma_f32_16x16x32_bf16 v[0:3], v[160:163], v[210:213], v[0:3]
	v_mfma_f32_16x16x32_bf16 v[52:55], v[156:159], v[190:193], v[52:55]
	v_mfma_f32_16x16x32_bf16 v[48:51], v[182:185], v[190:193], v[48:51]
	v_mfma_f32_16x16x32_bf16 v[36:39], v[156:159], v[198:201], v[36:39]
	v_mfma_f32_16x16x32_bf16 v[32:35], v[182:185], v[198:201], v[32:35]
	v_mfma_f32_16x16x32_bf16 v[20:23], v[156:159], v[206:209], v[20:23]
	v_mfma_f32_16x16x32_bf16 v[16:19], v[182:185], v[206:209], v[16:19]
	v_mfma_f32_16x16x32_bf16 v[4:7], v[156:159], v[214:217], v[4:7]
	v_mfma_f32_16x16x32_bf16 v[0:3], v[182:185], v[214:217], v[0:3]
	s_barrier
	s_add_i32 s96, 0, 0x18000
	s_add_i32 s97, 0, 0x1c000
	v_add_u32_e32 v140, s96, v167
	v_add_u32_e32 v173, s97, v167
	ds_read_b128 v[124:127], v140
	ds_read_b128 v[132:135], v140 offset:1024
	ds_read_b128 v[136:139], v140 offset:2048
	ds_read_b128 v[140:143], v140 offset:3072
	ds_read_b128 v[144:147], v173
	ds_read_b128 v[156:159], v173 offset:1024
	ds_read_b128 v[160:163], v173 offset:2048
	ds_read_b128 v[182:185], v173 offset:3072
	s_add_u32 s20, s26, 0x160000
	s_addc_u32 s21, s27, 0
	s_mov_b32 m0, s33
	v_lshl_add_u64 v[222:223], s[20:21], 0, v[148:149]
	ds_read_b128 v[186:189], v171 offset:32768
	ds_read_b128 v[190:193], v171 offset:33792
	ds_read_b128 v[194:197], v171 offset:34816
	ds_read_b128 v[198:201], v171 offset:35840
	ds_read_b128 v[202:205], v171 offset:36864
	ds_read_b128 v[206:209], v171 offset:37888
	ds_read_b128 v[210:213], v171 offset:38912
	ds_read_b128 v[214:217], v171 offset:39936
	global_load_lds_dwordx4 v[222:223], off
	v_lshl_add_u64 v[222:223], s[20:21], 0, v[150:151]
	s_mov_b32 m0, s35
	s_nop 0
	global_load_lds_dwordx4 v[222:223], off
	s_waitcnt vmcnt(8)
	s_waitcnt lgkmcnt(0)
	s_barrier
	s_waitcnt lgkmcnt(0)
	v_mfma_f32_16x16x32_bf16 v[128:131], v[124:127], v[186:189], v[128:131]
	v_mfma_f32_16x16x32_bf16 v[120:123], v[136:139], v[186:189], v[120:123]
	v_mfma_f32_16x16x32_bf16 v[108:111], v[124:127], v[194:197], v[108:111]
	v_mfma_f32_16x16x32_bf16 v[104:107], v[136:139], v[194:197], v[104:107]
	v_mfma_f32_16x16x32_bf16 v[92:95], v[124:127], v[202:205], v[92:95]
	v_mfma_f32_16x16x32_bf16 v[88:91], v[136:139], v[202:205], v[88:91]
	v_mfma_f32_16x16x32_bf16 v[76:79], v[124:127], v[210:213], v[76:79]
	v_mfma_f32_16x16x32_bf16 v[72:75], v[136:139], v[210:213], v[72:75]
	v_mfma_f32_16x16x32_bf16 v[128:131], v[132:135], v[190:193], v[128:131]
	v_mfma_f32_16x16x32_bf16 v[120:123], v[140:143], v[190:193], v[120:123]
	v_mfma_f32_16x16x32_bf16 v[108:111], v[132:135], v[198:201], v[108:111]
	v_mfma_f32_16x16x32_bf16 v[104:107], v[140:143], v[198:201], v[104:107]
	v_mfma_f32_16x16x32_bf16 v[92:95], v[132:135], v[206:209], v[92:95]
	v_mfma_f32_16x16x32_bf16 v[88:91], v[140:143], v[206:209], v[88:91]
	v_mfma_f32_16x16x32_bf16 v[76:79], v[132:135], v[214:217], v[76:79]
	v_mfma_f32_16x16x32_bf16 v[72:75], v[140:143], v[214:217], v[72:75]
	v_mfma_f32_16x16x32_bf16 v[116:119], v[144:147], v[186:189], v[116:119]
	v_mfma_f32_16x16x32_bf16 v[112:115], v[160:163], v[186:189], v[112:115]
	v_mfma_f32_16x16x32_bf16 v[100:103], v[144:147], v[194:197], v[100:103]
	v_mfma_f32_16x16x32_bf16 v[96:99], v[160:163], v[194:197], v[96:99]
	v_mfma_f32_16x16x32_bf16 v[84:87], v[144:147], v[202:205], v[84:87]
	v_mfma_f32_16x16x32_bf16 v[80:83], v[160:163], v[202:205], v[80:83]
	v_mfma_f32_16x16x32_bf16 v[68:71], v[144:147], v[210:213], v[68:71]
	v_mfma_f32_16x16x32_bf16 v[64:67], v[160:163], v[210:213], v[64:67]
	v_mfma_f32_16x16x32_bf16 v[116:119], v[156:159], v[190:193], v[116:119]
	v_mfma_f32_16x16x32_bf16 v[112:115], v[182:185], v[190:193], v[112:115]
	v_mfma_f32_16x16x32_bf16 v[100:103], v[156:159], v[198:201], v[100:103]
	v_mfma_f32_16x16x32_bf16 v[96:99], v[182:185], v[198:201], v[96:99]
	v_mfma_f32_16x16x32_bf16 v[84:87], v[156:159], v[206:209], v[84:87]
	v_mfma_f32_16x16x32_bf16 v[80:83], v[182:185], v[206:209], v[80:83]
	v_mfma_f32_16x16x32_bf16 v[68:71], v[156:159], v[214:217], v[68:71]
	v_mfma_f32_16x16x32_bf16 v[64:67], v[182:185], v[214:217], v[64:67]
	s_barrier
; #define PG8_STAGE(bufoff, gbase, voff) do { _Pragma("unroll") for (int _i = 0; _i < 2; ++_i) \
;         __builtin_amdgcn_global_load_lds((const unsigned*)((const char*)(gbase) + (voff)[_i]), (LAS unsigned*)(lds + (bufoff) + ldsw + _i * 8192), 16, 0, 0); } while (0)
; #define PG8_LDA(dst, b, h) do { _Pragma("unroll") for (int m = 0; m < 4; ++m) _Pragma("unroll") for (int k = 0; k < 2; ++k) dst[m][k] = *(const LAS bf16x8*)(lds + PG8_SA(b, h) + aoff + m * 2048 + k * 1024); } while (0)
; #define PG8_MMA(ai, bj, At, Bt) do { __builtin_amdgcn_s_setprio(1); _Pragma("unroll") for (int m = 0; m < 4; ++m) _Pragma("unroll") for (int n = 0; n < 2; ++n) _Pragma("unroll") for (int k = 0; k < 2; ++k) \
;         acc[ai][bj][m][n] = __builtin_amdgcn_mfma_f32_16x16x32_bf16(Bt[n][k], At[m][k], acc[ai][bj][m][n], 0, 0, 0); __builtin_amdgcn_s_setprio(0); } while (0)
; #define PG8_WAIT_V(n) asm volatile("s_waitcnt vmcnt(" #n ")" ::: "memory")
; #define PG8_WAIT_L(n) asm volatile("s_waitcnt lgkmcnt(" #n ")" ::: "memory")
; #define PG8_BAR __builtin_amdgcn_s_barrier()
; #define PG8_SCHED __builtin_amdgcn_sched_barrier(0)
; template <class Sched, class Epi, bool ALIGN_EPI, bool SP2>
; __device__ __forceinline__ void gemm_phase(LAS unsigned char* lds, const int K, const int lda, const int ldb, const Sched& S, const Epi& E) {
;     ...
;             PG8_LDA(At, 1, 1); PG8_STAGE(PG8_SB(1, 0), b3, voffB); PG8_STAGE(PG8_SB(1, 1), b3 + hstepB, voffB); PG8_STAGE(PG8_SA(1, 0), a3, voffA);
;             PG8_WAIT_V(8); PG8_WAIT_L(0); PG8_BAR; PG8_MMA(1, 0, At, B0); PG8_MMA(1, 1, At, B1); PG8_BAR; PG8_SCHED;
	s_add_i32 s20, s96, s13
	v_lshl_add_u64 v[164:165], v[164:165], 0, s[6:7]
	s_mov_b32 m0, s20
	ds_read_b128 v[186:189], v171 offset:49152
	ds_read_b128 v[190:193], v171 offset:50176
	ds_read_b128 v[194:197], v171 offset:51200
	ds_read_b128 v[198:201], v171 offset:52224
	ds_read_b128 v[202:205], v171 offset:53248
	ds_read_b128 v[206:209], v171 offset:54272
	ds_read_b128 v[210:213], v171 offset:55296
	ds_read_b128 v[214:217], v171 offset:56320
	global_load_lds_dwordx4 v[164:165], off
	s_add_i32 m0, s20, 0x2000
	s_add_u32 s20, s24, 0x160080
	v_lshl_add_u64 v[164:165], v[174:175], 0, s[6:7]
	s_addc_u32 s21, s25, 0
	s_add_i32 s24, s97, s13
	global_load_lds_dwordx4 v[164:165], off
	v_lshl_add_u64 v[164:165], s[20:21], 0, v[148:149]
	s_mov_b32 m0, s24
	s_nop 0
	global_load_lds_dwordx4 v[164:165], off
	v_lshl_add_u64 v[164:165], s[20:21], 0, v[150:151]
	s_add_i32 m0, s24, 0x2000
	s_nop 0
	global_load_lds_dwordx4 v[164:165], off
	v_lshl_add_u64 v[164:165], v[218:219], 0, s[6:7]
	s_mov_b32 m0, s51
	s_nop 0
	global_load_lds_dwordx4 v[164:165], off
	v_lshl_add_u64 v[164:165], v[220:221], 0, s[6:7]
	s_mov_b32 m0, s52
	s_nop 0
	global_load_lds_dwordx4 v[164:165], off
	s_waitcnt vmcnt(8)
	s_waitcnt lgkmcnt(0)
	s_barrier
	s_waitcnt lgkmcnt(0)
	v_mfma_f32_16x16x32_bf16 v[60:63], v[124:127], v[186:189], v[60:63]
	v_mfma_f32_16x16x32_bf16 v[56:59], v[136:139], v[186:189], v[56:59]
	v_mfma_f32_16x16x32_bf16 v[44:47], v[124:127], v[194:197], v[44:47]
	v_mfma_f32_16x16x32_bf16 v[40:43], v[136:139], v[194:197], v[40:43]
	v_mfma_f32_16x16x32_bf16 v[28:31], v[124:127], v[202:205], v[28:31]
	v_mfma_f32_16x16x32_bf16 v[24:27], v[136:139], v[202:205], v[24:27]
	v_mfma_f32_16x16x32_bf16 v[12:15], v[124:127], v[210:213], v[12:15]
	v_mfma_f32_16x16x32_bf16 v[8:11], v[136:139], v[210:213], v[8:11]
	v_mfma_f32_16x16x32_bf16 v[60:63], v[132:135], v[190:193], v[60:63]
	v_mfma_f32_16x16x32_bf16 v[56:59], v[140:143], v[190:193], v[56:59]
	v_mfma_f32_16x16x32_bf16 v[44:47], v[132:135], v[198:201], v[44:47]
	v_mfma_f32_16x16x32_bf16 v[40:43], v[140:143], v[198:201], v[40:43]
	v_mfma_f32_16x16x32_bf16 v[28:31], v[132:135], v[206:209], v[28:31]
	v_mfma_f32_16x16x32_bf16 v[24:27], v[140:143], v[206:209], v[24:27]
	v_mfma_f32_16x16x32_bf16 v[12:15], v[132:135], v[214:217], v[12:15]
	v_mfma_f32_16x16x32_bf16 v[8:11], v[140:143], v[214:217], v[8:11]
	v_mfma_f32_16x16x32_bf16 v[52:55], v[144:147], v[186:189], v[52:55]
	v_mfma_f32_16x16x32_bf16 v[48:51], v[160:163], v[186:189], v[48:51]
	v_mfma_f32_16x16x32_bf16 v[36:39], v[144:147], v[194:197], v[36:39]
	v_mfma_f32_16x16x32_bf16 v[32:35], v[160:163], v[194:197], v[32:35]
	v_mfma_f32_16x16x32_bf16 v[20:23], v[144:147], v[202:205], v[20:23]
	v_mfma_f32_16x16x32_bf16 v[16:19], v[160:163], v[202:205], v[16:19]
	v_mfma_f32_16x16x32_bf16 v[4:7], v[144:147], v[210:213], v[4:7]
	v_mfma_f32_16x16x32_bf16 v[0:3], v[160:163], v[210:213], v[0:3]
	v_mfma_f32_16x16x32_bf16 v[52:55], v[156:159], v[190:193], v[52:55]
	v_mfma_f32_16x16x32_bf16 v[48:51], v[182:185], v[190:193], v[48:51]
	v_mfma_f32_16x16x32_bf16 v[36:39], v[156:159], v[198:201], v[36:39]
	v_mfma_f32_16x16x32_bf16 v[32:35], v[182:185], v[198:201], v[32:35]
	v_mfma_f32_16x16x32_bf16 v[20:23], v[156:159], v[206:209], v[20:23]
	v_mfma_f32_16x16x32_bf16 v[16:19], v[182:185], v[206:209], v[16:19]
	v_mfma_f32_16x16x32_bf16 v[4:7], v[156:159], v[214:217], v[4:7]
	v_mfma_f32_16x16x32_bf16 v[0:3], v[182:185], v[214:217], v[0:3]
	s_barrier
	s_add_i32 s91, s91, 2
	s_add_u32 s89, s89, 0x100
	s_addc_u32 s90, s90, 0
	s_cmpk_gt_u32 s91, 0x55
	s_mov_b64 s[20:21], s[22:23]
	s_cbranch_scc0 .LBB0_243
	s_and_b64 vcc, exec, s[10:11]
	s_cbranch_vccz .LBB0_246
	s_barrier

; #define PG8_STAGE(bufoff, gbase, voff) do { _Pragma("unroll") for (int _i = 0; _i < 2; ++_i) \
;         __builtin_amdgcn_global_load_lds((const unsigned*)((const char*)(gbase) + (voff)[_i]), (LAS unsigned*)(lds + (bufoff) + ldsw + _i * 8192), 16, 0, 0); } while (0)
; #define PG8_LDA(dst, b, h) do { _Pragma("unroll") for (int m = 0; m < 4; ++m) _Pragma("unroll") for (int k = 0; k < 2; ++k) dst[m][k] = *(const LAS bf16x8*)(lds + PG8_SA(b, h) + aoff + m * 2048 + k * 1024); } while (0)
; #define PG8_LDB(dst, b, h) do { _Pragma("unroll") for (int n = 0; n < 2; ++n) _Pragma("unroll") for (int k = 0; k < 2; ++k) dst[n][k] = *(const LAS bf16x8*)(lds + PG8_SB(b, h) + boff + n * 2048 + k * 1024); } while (0)
; #define PG8_MMA(ai, bj, At, Bt) do { __builtin_amdgcn_s_setprio(1); _Pragma("unroll") for (int m = 0; m < 4; ++m) _Pragma("unroll") for (int n = 0; n < 2; ++n) _Pragma("unroll") for (int k = 0; k < 2; ++k) \
;         acc[ai][bj][m][n] = __builtin_amdgcn_mfma_f32_16x16x32_bf16(Bt[n][k], At[m][k], acc[ai][bj][m][n], 0, 0, 0); __builtin_amdgcn_s_setprio(0); } while (0)
; #define PG8_WAIT_V(n) asm volatile("s_waitcnt vmcnt(" #n ")" ::: "memory")
; #define PG8_WAIT_L(n) asm volatile("s_waitcnt lgkmcnt(" #n ")" ::: "memory")
; #define PG8_BAR __builtin_amdgcn_s_barrier()
; template <class Sched, class Epi, bool ALIGN_EPI, bool SP2>
; __device__ __forceinline__ void gemm_phase(LAS unsigned char* lds, const int K, const int lda, const int ldb, const Sched& S, const Epi& E) {
;     ...
;         for (int t = 0; t < nt; t += 2) {
;             const bool last = (t == nt - 2);
;             const char* a1 = cA + (size_t)(t + 1) * kstep;
;             const char* a2 = last ? nA : cA + (size_t)(t + 2) * kstep; const char* b2 = last ? nB : cB + (size_t)(t + 2) * kstep;
;             const char* a3 = a2 + kstep; const char* b3 = b2 + kstep;
;             if constexpr (SP2) {
;             PG8_LDB(B0, 0, 0); PG8_LDB(B1, 0, 1); PG8_SCHED; PG8_LDA(At, 0, 0); PG8_STAGE(PG8_SA(1, 1), a1 + hstepA, voffA);
;             PG8_WAIT_V(8); PG8_WAIT_L(0); PG8_BAR; PG8_MMA(0, 0, At, B0); PG8_MMA(0, 1, At, B1); PG8_BAR; PG8_SCHED;
;             PG8_LDA(At, 0, 1); PG8_STAGE(PG8_SB(0, 0), b2, voffB); PG8_STAGE(PG8_SB(0, 1), b2 + hstepB, voffB); PG8_STAGE(PG8_SA(0, 0), a2, voffA);
;             PG8_WAIT_V(8); PG8_WAIT_L(0); PG8_BAR; PG8_MMA(1, 0, At, B0); PG8_MMA(1, 1, At, B1); PG8_BAR; PG8_SCHED;
.LBB0_353:
	s_waitcnt lgkmcnt(0)
	ds_read_b128 v[32:35], v211
	ds_read_b128 v[36:39], v211 offset:1024
	ds_read_b128 v[48:51], v211 offset:2048
	ds_read_b128 v[52:55], v211 offset:3072
	ds_read_b128 v[56:59], v212
	ds_read_b128 v[60:63], v212 offset:1024
	ds_read_b128 v[64:67], v212 offset:2048
	ds_read_b128 v[68:71], v212 offset:3072
	s_add_u32 s8, s26, 0xfff80080
	s_addc_u32 s9, s27, -1
	s_cmp_eq_u32 s7, 28
	s_cselect_b32 s37, s1, s9
	s_cselect_b32 s36, s4, s8
	s_cselect_b32 s29, s21, s6
	s_cselect_b32 s28, vcc_lo, vcc_hi
	v_lshl_add_u64 v[208:209], s[26:27], 0, v[192:193]
	s_add_i32 m0, s89, 0xc000
	ds_read_b128 v[76:79], v213
	ds_read_b128 v[80:83], v213 offset:1024
	ds_read_b128 v[88:91], v213 offset:2048
	ds_read_b128 v[92:95], v213 offset:3072
	ds_read_b128 v[196:199], v213 offset:4096
	ds_read_b128 v[200:203], v213 offset:5120
	ds_read_b128 v[204:207], v213 offset:6144
	ds_read_b128 v[216:219], v213 offset:7168
	global_load_lds_dwordx4 v[208:209], off
	v_lshl_add_u64 v[208:209], s[26:27], 0, v[194:195]
	s_add_i32 m0, s89, 0xe000
	s_nop 0
	global_load_lds_dwordx4 v[208:209], off
	s_waitcnt vmcnt(8)
	s_waitcnt lgkmcnt(0)
	s_barrier
	s_waitcnt lgkmcnt(0)
	v_mfma_f32_16x16x32_bf16 v[172:175], v[32:35], v[76:79], v[172:175]
	v_mfma_f32_16x16x32_bf16 v[168:171], v[48:51], v[76:79], v[168:171]
	v_mfma_f32_16x16x32_bf16 v[156:159], v[32:35], v[88:91], v[156:159]
	v_mfma_f32_16x16x32_bf16 v[152:155], v[48:51], v[88:91], v[152:155]
	v_mfma_f32_16x16x32_bf16 v[140:143], v[32:35], v[196:199], v[140:143]
	v_mfma_f32_16x16x32_bf16 v[136:139], v[48:51], v[196:199], v[136:139]
	v_mfma_f32_16x16x32_bf16 v[124:127], v[32:35], v[204:207], v[124:127]
	v_mfma_f32_16x16x32_bf16 v[120:123], v[48:51], v[204:207], v[120:123]
	v_mfma_f32_16x16x32_bf16 v[172:175], v[36:39], v[80:83], v[172:175]
	v_mfma_f32_16x16x32_bf16 v[168:171], v[52:55], v[80:83], v[168:171]
	v_mfma_f32_16x16x32_bf16 v[156:159], v[36:39], v[92:95], v[156:159]
	v_mfma_f32_16x16x32_bf16 v[152:155], v[52:55], v[92:95], v[152:155]
	v_mfma_f32_16x16x32_bf16 v[140:143], v[36:39], v[200:203], v[140:143]
	v_mfma_f32_16x16x32_bf16 v[136:139], v[52:55], v[200:203], v[136:139]
	v_mfma_f32_16x16x32_bf16 v[124:127], v[36:39], v[216:219], v[124:127]
	v_mfma_f32_16x16x32_bf16 v[120:123], v[52:55], v[216:219], v[120:123]
	v_mfma_f32_16x16x32_bf16 v[164:167], v[56:59], v[76:79], v[164:167]
	v_mfma_f32_16x16x32_bf16 v[76:79], v[64:67], v[76:79], v[160:163]
	v_mfma_f32_16x16x32_bf16 v[164:167], v[60:63], v[80:83], v[164:167]
	v_mfma_f32_16x16x32_bf16 v[76:79], v[68:71], v[80:83], v[76:79]
	v_mfma_f32_16x16x32_bf16 v[80:83], v[56:59], v[88:91], v[148:151]
	v_mfma_f32_16x16x32_bf16 v[88:91], v[64:67], v[88:91], v[144:147]
	v_mfma_f32_16x16x32_bf16 v[128:131], v[64:67], v[196:199], v[128:131]
	v_mfma_f32_16x16x32_bf16 v[116:119], v[56:59], v[204:207], v[116:119]
	v_mfma_f32_16x16x32_bf16 v[112:115], v[64:67], v[204:207], v[112:115]
	v_mfma_f32_16x16x32_bf16 v[80:83], v[60:63], v[92:95], v[80:83]
	v_mfma_f32_16x16x32_bf16 v[88:91], v[68:71], v[92:95], v[88:91]
	v_mfma_f32_16x16x32_bf16 v[92:95], v[56:59], v[196:199], v[132:135]
	v_mfma_f32_16x16x32_bf16 v[128:131], v[68:71], v[200:203], v[128:131]
	v_mfma_f32_16x16x32_bf16 v[116:119], v[60:63], v[216:219], v[116:119]
	v_mfma_f32_16x16x32_bf16 v[112:115], v[68:71], v[216:219], v[112:115]
	v_mfma_f32_16x16x32_bf16 v[92:95], v[60:63], v[200:203], v[92:95]
	s_barrier
	s_add_i32 s8, s85, s88
	v_lshl_add_u64 v[208:209], s[28:29], 0, v[186:187]
	s_mov_b32 m0, s8
	ds_read_b128 v[132:135], v213 offset:16384
	ds_read_b128 v[144:147], v213 offset:17408
	ds_read_b128 v[148:151], v213 offset:18432
	ds_read_b128 v[160:163], v213 offset:19456
	ds_read_b128 v[196:199], v213 offset:20480
	ds_read_b128 v[200:203], v213 offset:21504
	ds_read_b128 v[204:207], v213 offset:22528
	ds_read_b128 v[216:219], v213 offset:23552
	global_load_lds_dwordx4 v[208:209], off
	s_add_i32 m0, s8, 0x2000
	s_add_u32 s8, s28, 0x80000
	v_lshl_add_u64 v[228:229], s[28:29], 0, v[190:191]
	s_addc_u32 s9, s29, 0
	s_add_i32 s51, s50, s88
	global_load_lds_dwordx4 v[228:229], off
	v_lshl_add_u64 v[220:221], s[8:9], 0, v[186:187]
	s_mov_b32 m0, s51
	v_lshl_add_u64 v[230:231], s[36:37], 0, v[184:185]
	global_load_lds_dwordx4 v[220:221], off
	v_lshl_add_u64 v[220:221], s[8:9], 0, v[190:191]
	s_add_i32 m0, s51, 0x2000
	v_lshl_add_u64 v[232:233], s[36:37], 0, v[188:189]
	global_load_lds_dwordx4 v[220:221], off
	s_mov_b32 m0, s89
	s_nop 0
	global_load_lds_dwordx4 v[230:231], off
	s_mov_b32 m0, s90
	s_nop 0
	global_load_lds_dwordx4 v[232:233], off
	s_waitcnt vmcnt(8)
	s_waitcnt lgkmcnt(0)
	s_barrier
; #define PG8_STAGE(bufoff, gbase, voff) do { _Pragma("unroll") for (int _i = 0; _i < 2; ++_i) \
;         __builtin_amdgcn_global_load_lds((const unsigned*)((const char*)(gbase) + (voff)[_i]), (LAS unsigned*)(lds + (bufoff) + ldsw + _i * 8192), 16, 0, 0); } while (0)
; #define PG8_LDA(dst, b, h) do { _Pragma("unroll") for (int m = 0; m < 4; ++m) _Pragma("unroll") for (int k = 0; k < 2; ++k) dst[m][k] = *(const LAS bf16x8*)(lds + PG8_SA(b, h) + aoff + m * 2048 + k * 1024); } while (0)
; #define PG8_LDB(dst, b, h) do { _Pragma("unroll") for (int n = 0; n < 2; ++n) _Pragma("unroll") for (int k = 0; k < 2; ++k) dst[n][k] = *(const LAS bf16x8*)(lds + PG8_SB(b, h) + boff + n * 2048 + k * 1024); } while (0)
; #define PG8_MMA(ai, bj, At, Bt) do { __builtin_amdgcn_s_setprio(1); _Pragma("unroll") for (int m = 0; m < 4; ++m) _Pragma("unroll") for (int n = 0; n < 2; ++n) _Pragma("unroll") for (int k = 0; k < 2; ++k) \
;         acc[ai][bj][m][n] = __builtin_amdgcn_mfma_f32_16x16x32_bf16(Bt[n][k], At[m][k], acc[ai][bj][m][n], 0, 0, 0); __builtin_amdgcn_s_setprio(0); } while (0)
; #define PG8_WAIT_V(n) asm volatile("s_waitcnt vmcnt(" #n ")" ::: "memory")
; #define PG8_WAIT_L(n) asm volatile("s_waitcnt lgkmcnt(" #n ")" ::: "memory")
; #define PG8_BAR __builtin_amdgcn_s_barrier()
; #define PG8_SCHED __builtin_amdgcn_sched_barrier(0)
; template <class Sched, class Epi, bool ALIGN_EPI, bool SP2>
; __device__ __forceinline__ void gemm_phase(LAS unsigned char* lds, const int K, const int lda, const int ldb, const Sched& S, const Epi& E) {
;     ...
;             PG8_WAIT_V(8); PG8_WAIT_L(0); PG8_BAR; PG8_MMA(1, 0, At, B0); PG8_MMA(1, 1, At, B1); PG8_BAR; PG8_SCHED;
;             PG8_LDB(B0, 1, 0); PG8_LDB(B1, 1, 1); PG8_SCHED; PG8_LDA(At, 1, 0); PG8_STAGE(PG8_SA(0, 1), a2 + hstepA, voffA);
;             PG8_WAIT_V(8); PG8_WAIT_L(0); PG8_BAR; PG8_MMA(0, 0, At, B0); PG8_MMA(0, 1, At, B1); PG8_BAR; PG8_SCHED;
;             PG8_LDA(At, 1, 1); PG8_STAGE(PG8_SB(1, 0), b3, voffB); PG8_STAGE(PG8_SB(1, 1), b3 + hstepB, voffB); PG8_STAGE(PG8_SA(1, 0), a3, voffA);
	s_waitcnt lgkmcnt(0)
	v_mfma_f32_16x16x32_bf16 v[108:111], v[32:35], v[132:135], v[108:111]
	v_mfma_f32_16x16x32_bf16 v[104:107], v[48:51], v[132:135], v[104:107]
	v_mfma_f32_16x16x32_bf16 v[84:87], v[32:35], v[148:151], v[84:87]
	v_mfma_f32_16x16x32_bf16 v[72:75], v[48:51], v[148:151], v[72:75]
	v_mfma_f32_16x16x32_bf16 v[28:31], v[32:35], v[196:199], v[28:31]
	v_mfma_f32_16x16x32_bf16 v[24:27], v[48:51], v[196:199], v[24:27]
	v_mfma_f32_16x16x32_bf16 v[12:15], v[32:35], v[204:207], v[12:15]
	v_mfma_f32_16x16x32_bf16 v[8:11], v[48:51], v[204:207], v[8:11]
	v_mfma_f32_16x16x32_bf16 v[108:111], v[36:39], v[144:147], v[108:111]
	v_mfma_f32_16x16x32_bf16 v[104:107], v[52:55], v[144:147], v[104:107]
	v_mfma_f32_16x16x32_bf16 v[84:87], v[36:39], v[160:163], v[84:87]
	v_mfma_f32_16x16x32_bf16 v[72:75], v[52:55], v[160:163], v[72:75]
	v_mfma_f32_16x16x32_bf16 v[28:31], v[36:39], v[200:203], v[28:31]
	v_mfma_f32_16x16x32_bf16 v[24:27], v[52:55], v[200:203], v[24:27]
	v_mfma_f32_16x16x32_bf16 v[12:15], v[36:39], v[216:219], v[12:15]
	v_mfma_f32_16x16x32_bf16 v[8:11], v[52:55], v[216:219], v[8:11]
	v_mfma_f32_16x16x32_bf16 v[44:47], v[56:59], v[148:151], v[44:47]
	v_mfma_f32_16x16x32_bf16 v[40:43], v[64:67], v[148:151], v[40:43]
	v_mfma_f32_16x16x32_bf16 v[20:23], v[56:59], v[196:199], v[20:23]
	v_mfma_f32_16x16x32_bf16 v[16:19], v[64:67], v[196:199], v[16:19]
	v_mfma_f32_16x16x32_bf16 v[4:7], v[56:59], v[204:207], v[4:7]
	v_mfma_f32_16x16x32_bf16 v[0:3], v[64:67], v[204:207], v[0:3]
	v_mfma_f32_16x16x32_bf16 v[32:35], v[56:59], v[132:135], v[100:103]
	v_mfma_f32_16x16x32_bf16 v[36:39], v[64:67], v[132:135], v[96:99]
	v_mfma_f32_16x16x32_bf16 v[44:47], v[60:63], v[160:163], v[44:47]
	v_mfma_f32_16x16x32_bf16 v[40:43], v[68:71], v[160:163], v[40:43]
	v_mfma_f32_16x16x32_bf16 v[20:23], v[60:63], v[200:203], v[20:23]
	v_mfma_f32_16x16x32_bf16 v[16:19], v[68:71], v[200:203], v[16:19]
	v_mfma_f32_16x16x32_bf16 v[4:7], v[60:63], v[216:219], v[4:7]
	v_mfma_f32_16x16x32_bf16 v[0:3], v[68:71], v[216:219], v[0:3]
	v_mfma_f32_16x16x32_bf16 v[32:35], v[60:63], v[144:147], v[32:35]
	v_mfma_f32_16x16x32_bf16 v[36:39], v[68:71], v[144:147], v[36:39]
	s_barrier
	s_add_i32 s51, 0, 0x18000
	s_add_i32 s17, 0, 0x1c000
	v_add_u32_e32 v60, s51, v183
	v_add_u32_e32 v96, s17, v183
	ds_read_b128 v[48:51], v60
	ds_read_b128 v[52:55], v60 offset:1024
	ds_read_b128 v[56:59], v60 offset:2048
	ds_read_b128 v[60:63], v60 offset:3072
	ds_read_b128 v[64:67], v96
	ds_read_b128 v[68:71], v96 offset:1024
	ds_read_b128 v[196:199], v96 offset:2048
	ds_read_b128 v[200:203], v96 offset:3072
	s_add_u32 s8, s36, 0x80000
	s_addc_u32 s9, s37, 0
	s_mov_b32 m0, s91
	v_lshl_add_u64 v[148:149], s[8:9], 0, v[184:185]
	ds_read_b128 v[96:99], v213 offset:32768
	ds_read_b128 v[100:103], v213 offset:33792
	ds_read_b128 v[132:135], v213 offset:34816
	ds_read_b128 v[144:147], v213 offset:35840
	ds_read_b128 v[204:207], v213 offset:36864
	ds_read_b128 v[216:219], v213 offset:37888
	ds_read_b128 v[220:223], v213 offset:38912
	ds_read_b128 v[224:227], v213 offset:39936
	global_load_lds_dwordx4 v[148:149], off
	v_lshl_add_u64 v[148:149], s[8:9], 0, v[188:189]
	s_mov_b32 m0, s96
	s_nop 0
	global_load_lds_dwordx4 v[148:149], off
	s_waitcnt vmcnt(8)
	s_waitcnt lgkmcnt(0)
	s_barrier
	s_waitcnt lgkmcnt(0)
	v_mfma_f32_16x16x32_bf16 v[148:151], v[48:51], v[96:99], v[172:175]
	v_mfma_f32_16x16x32_bf16 v[172:175], v[52:55], v[100:103], v[148:151]
	v_mfma_f32_16x16x32_bf16 v[148:151], v[56:59], v[96:99], v[168:171]
	v_mfma_f32_16x16x32_bf16 v[168:171], v[60:63], v[100:103], v[148:151]
	v_mfma_f32_16x16x32_bf16 v[148:151], v[48:51], v[132:135], v[156:159]
	v_mfma_f32_16x16x32_bf16 v[156:159], v[52:55], v[144:147], v[148:151]
	v_mfma_f32_16x16x32_bf16 v[148:151], v[56:59], v[132:135], v[152:155]
	v_mfma_f32_16x16x32_bf16 v[140:143], v[48:51], v[204:207], v[140:143]
	v_mfma_f32_16x16x32_bf16 v[136:139], v[56:59], v[204:207], v[136:139]
	v_mfma_f32_16x16x32_bf16 v[124:127], v[48:51], v[220:223], v[124:127]
	v_mfma_f32_16x16x32_bf16 v[120:123], v[56:59], v[220:223], v[120:123]
	v_mfma_f32_16x16x32_bf16 v[152:155], v[60:63], v[144:147], v[148:151]
	v_mfma_f32_16x16x32_bf16 v[140:143], v[52:55], v[216:219], v[140:143]
	v_mfma_f32_16x16x32_bf16 v[136:139], v[60:63], v[216:219], v[136:139]
	v_mfma_f32_16x16x32_bf16 v[124:127], v[52:55], v[224:227], v[124:127]
	v_mfma_f32_16x16x32_bf16 v[120:123], v[60:63], v[224:227], v[120:123]
	v_mfma_f32_16x16x32_bf16 v[76:79], v[196:199], v[96:99], v[76:79]
	v_mfma_f32_16x16x32_bf16 v[148:151], v[64:67], v[96:99], v[164:167]
	v_mfma_f32_16x16x32_bf16 v[160:163], v[200:203], v[100:103], v[76:79]
	v_mfma_f32_16x16x32_bf16 v[76:79], v[64:67], v[132:135], v[80:83]
	v_mfma_f32_16x16x32_bf16 v[164:167], v[68:71], v[100:103], v[148:151]
	v_mfma_f32_16x16x32_bf16 v[148:151], v[68:71], v[144:147], v[76:79]
	v_mfma_f32_16x16x32_bf16 v[76:79], v[196:199], v[132:135], v[88:91]
	v_mfma_f32_16x16x32_bf16 v[144:147], v[200:203], v[144:147], v[76:79]
	v_mfma_f32_16x16x32_bf16 v[76:79], v[64:67], v[204:207], v[92:95]
	v_mfma_f32_16x16x32_bf16 v[132:135], v[68:71], v[216:219], v[76:79]
	v_mfma_f32_16x16x32_bf16 v[76:79], v[196:199], v[204:207], v[128:131]
	v_mfma_f32_16x16x32_bf16 v[128:131], v[200:203], v[216:219], v[76:79]
	v_mfma_f32_16x16x32_bf16 v[76:79], v[64:67], v[220:223], v[116:119]
	v_mfma_f32_16x16x32_bf16 v[116:119], v[68:71], v[224:227], v[76:79]
	v_mfma_f32_16x16x32_bf16 v[76:79], v[196:199], v[220:223], v[112:115]
	v_mfma_f32_16x16x32_bf16 v[112:115], v[200:203], v[224:227], v[76:79]
	s_barrier
; #define PG8_STAGE(bufoff, gbase, voff) do { _Pragma("unroll") for (int _i = 0; _i < 2; ++_i) \
;         __builtin_amdgcn_global_load_lds((const unsigned*)((const char*)(gbase) + (voff)[_i]), (LAS unsigned*)(lds + (bufoff) + ldsw + _i * 8192), 16, 0, 0); } while (0)
; #define PG8_LDA(dst, b, h) do { _Pragma("unroll") for (int m = 0; m < 4; ++m) _Pragma("unroll") for (int k = 0; k < 2; ++k) dst[m][k] = *(const LAS bf16x8*)(lds + PG8_SA(b, h) + aoff + m * 2048 + k * 1024); } while (0)
; #define PG8_MMA(ai, bj, At, Bt) do { __builtin_amdgcn_s_setprio(1); _Pragma("unroll") for (int m = 0; m < 4; ++m) _Pragma("unroll") for (int n = 0; n < 2; ++n) _Pragma("unroll") for (int k = 0; k < 2; ++k) \
;         acc[ai][bj][m][n] = __builtin_amdgcn_mfma_f32_16x16x32_bf16(Bt[n][k], At[m][k], acc[ai][bj][m][n], 0, 0, 0); __builtin_amdgcn_s_setprio(0); } while (0)
; #define PG8_WAIT_V(n) asm volatile("s_waitcnt vmcnt(" #n ")" ::: "memory")
; #define PG8_WAIT_L(n) asm volatile("s_waitcnt lgkmcnt(" #n ")" ::: "memory")
; #define PG8_BAR __builtin_amdgcn_s_barrier()
; #define PG8_SCHED __builtin_amdgcn_sched_barrier(0)
; template <class Sched, class Epi, bool ALIGN_EPI, bool SP2>
; __device__ __forceinline__ void gemm_phase(LAS unsigned char* lds, const int K, const int lda, const int ldb, const Sched& S, const Epi& E) {
;     ...
;             PG8_LDA(At, 1, 1); PG8_STAGE(PG8_SB(1, 0), b3, voffB); PG8_STAGE(PG8_SB(1, 1), b3 + hstepB, voffB); PG8_STAGE(PG8_SA(1, 0), a3, voffA);
;             PG8_WAIT_V(8); PG8_WAIT_L(0); PG8_BAR; PG8_MMA(1, 0, At, B0); PG8_MMA(1, 1, At, B1); PG8_BAR; PG8_SCHED;
	s_add_i32 s8, s51, s88
	v_lshl_add_u64 v[96:97], v[208:209], 0, s[10:11]
	s_mov_b32 m0, s8
	s_nop 1
	ds_read_b128 v[76:79], v213 offset:49152
	ds_read_b128 v[80:83], v213 offset:50176
	ds_read_b128 v[88:91], v213 offset:51200
	ds_read_b128 v[92:95], v213 offset:52224
	ds_read_b128 v[204:207], v213 offset:53248
	ds_read_b128 v[216:219], v213 offset:54272
	ds_read_b128 v[220:223], v213 offset:55296
	ds_read_b128 v[224:227], v213 offset:56320
	global_load_lds_dwordx4 v[96:97], off
	s_add_i32 m0, s8, 0x2000
	s_add_u32 s8, s28, 0x80080
	v_lshl_add_u64 v[96:97], v[228:229], 0, s[10:11]
	s_addc_u32 s9, s29, 0
	s_add_i32 s17, s17, s88
	global_load_lds_dwordx4 v[96:97], off
	v_lshl_add_u64 v[96:97], s[8:9], 0, v[186:187]
	s_mov_b32 m0, s17
	s_nop 0
	global_load_lds_dwordx4 v[96:97], off
	v_lshl_add_u64 v[96:97], s[8:9], 0, v[190:191]
	s_add_i32 m0, s17, 0x2000
	s_nop 0
	global_load_lds_dwordx4 v[96:97], off
	v_lshl_add_u64 v[96:97], v[230:231], 0, s[10:11]
	s_mov_b32 m0, s97
	s_nop 0
	global_load_lds_dwordx4 v[96:97], off
	v_lshl_add_u64 v[96:97], v[232:233], 0, s[10:11]
	s_mov_b32 m0, s84
	s_nop 0
	global_load_lds_dwordx4 v[96:97], off
	s_waitcnt vmcnt(8)
	s_waitcnt lgkmcnt(0)
	s_barrier
	s_waitcnt lgkmcnt(0)
	v_mfma_f32_16x16x32_bf16 v[96:99], v[48:51], v[76:79], v[108:111]
	v_mfma_f32_16x16x32_bf16 v[108:111], v[52:55], v[80:83], v[96:99]
	v_mfma_f32_16x16x32_bf16 v[96:99], v[56:59], v[76:79], v[104:107]
	v_mfma_f32_16x16x32_bf16 v[84:87], v[48:51], v[88:91], v[84:87]
	v_mfma_f32_16x16x32_bf16 v[72:75], v[56:59], v[88:91], v[72:75]
	v_mfma_f32_16x16x32_bf16 v[28:31], v[48:51], v[204:207], v[28:31]
	v_mfma_f32_16x16x32_bf16 v[24:27], v[56:59], v[204:207], v[24:27]
	v_mfma_f32_16x16x32_bf16 v[12:15], v[48:51], v[220:223], v[12:15]
	v_mfma_f32_16x16x32_bf16 v[8:11], v[56:59], v[220:223], v[8:11]
	v_mfma_f32_16x16x32_bf16 v[104:107], v[60:63], v[80:83], v[96:99]
	v_mfma_f32_16x16x32_bf16 v[84:87], v[52:55], v[92:95], v[84:87]
	v_mfma_f32_16x16x32_bf16 v[72:75], v[60:63], v[92:95], v[72:75]
	v_mfma_f32_16x16x32_bf16 v[28:31], v[52:55], v[216:219], v[28:31]
	v_mfma_f32_16x16x32_bf16 v[24:27], v[60:63], v[216:219], v[24:27]
	v_mfma_f32_16x16x32_bf16 v[12:15], v[52:55], v[224:227], v[12:15]
	v_mfma_f32_16x16x32_bf16 v[8:11], v[60:63], v[224:227], v[8:11]
	v_mfma_f32_16x16x32_bf16 v[32:35], v[64:67], v[76:79], v[32:35]
	v_mfma_f32_16x16x32_bf16 v[100:103], v[68:71], v[80:83], v[32:35]
	v_mfma_f32_16x16x32_bf16 v[32:35], v[196:199], v[76:79], v[36:39]
	v_mfma_f32_16x16x32_bf16 v[96:99], v[200:203], v[80:83], v[32:35]
	v_mfma_f32_16x16x32_bf16 v[32:35], v[64:67], v[88:91], v[44:47]
	v_mfma_f32_16x16x32_bf16 v[44:47], v[68:71], v[92:95], v[32:35]
	v_mfma_f32_16x16x32_bf16 v[32:35], v[196:199], v[88:91], v[40:43]
	v_mfma_f32_16x16x32_bf16 v[20:23], v[64:67], v[204:207], v[20:23]
	v_mfma_f32_16x16x32_bf16 v[16:19], v[196:199], v[204:207], v[16:19]
	v_mfma_f32_16x16x32_bf16 v[4:7], v[64:67], v[220:223], v[4:7]
	v_mfma_f32_16x16x32_bf16 v[0:3], v[196:199], v[220:223], v[0:3]
	v_mfma_f32_16x16x32_bf16 v[40:43], v[200:203], v[92:95], v[32:35]
	v_mfma_f32_16x16x32_bf16 v[20:23], v[68:71], v[216:219], v[20:23]
	v_mfma_f32_16x16x32_bf16 v[16:19], v[200:203], v[216:219], v[16:19]
	v_mfma_f32_16x16x32_bf16 v[4:7], v[68:71], v[224:227], v[4:7]
	v_mfma_f32_16x16x32_bf16 v[0:3], v[200:203], v[224:227], v[0:3]
	s_barrier
	s_add_i32 s7, s7, 2
	s_add_u32 s26, s26, 0x100
	s_addc_u32 s27, s27, 0
	s_add_u32 vcc_hi, vcc_hi, 0x100
	s_addc_u32 s6, s6, 0
	s_cmp_gt_u32 s7, 29
	s_cbranch_scc0 .LBB0_353
	s_and_b64 vcc, exec, s[12:13]
	s_cbranch_vccz .LBB0_356
	s_barrier

; #define PG8_STAGE(bufoff, gbase, voff) do { _Pragma("unroll") for (int _i = 0; _i < 2; ++_i) \
;         __builtin_amdgcn_global_load_lds((const unsigned*)((const char*)(gbase) + (voff)[_i]), (LAS unsigned*)(lds + (bufoff) + ldsw + _i * 8192), 16, 0, 0); } while (0)
; #define PG8_LDA(dst, b, h) do { _Pragma("unroll") for (int m = 0; m < 4; ++m) _Pragma("unroll") for (int k = 0; k < 2; ++k) dst[m][k] = *(const LAS bf16x8*)(lds + PG8_SA(b, h) + aoff + m * 2048 + k * 1024); } while (0)
; #define PG8_LDB(dst, b, h) do { _Pragma("unroll") for (int n = 0; n < 2; ++n) _Pragma("unroll") for (int k = 0; k < 2; ++k) dst[n][k] = *(const LAS bf16x8*)(lds + PG8_SB(b, h) + boff + n * 2048 + k * 1024); } while (0)
; #define PG8_MMA(ai, bj, At, Bt) do { __builtin_amdgcn_s_setprio(1); _Pragma("unroll") for (int m = 0; m < 4; ++m) _Pragma("unroll") for (int n = 0; n < 2; ++n) _Pragma("unroll") for (int k = 0; k < 2; ++k) \
;         acc[ai][bj][m][n] = __builtin_amdgcn_mfma_f32_16x16x32_bf16(Bt[n][k], At[m][k], acc[ai][bj][m][n], 0, 0, 0); __builtin_amdgcn_s_setprio(0); } while (0)
; #define PG8_WAIT_V(n) asm volatile("s_waitcnt vmcnt(" #n ")" ::: "memory")
; #define PG8_WAIT_L(n) asm volatile("s_waitcnt lgkmcnt(" #n ")" ::: "memory")
; #define PG8_BAR __builtin_amdgcn_s_barrier()
; template <class Sched, class Epi, bool ALIGN_EPI, bool SP2>
; __device__ __forceinline__ void gemm_phase(LAS unsigned char* lds, const int K, const int lda, const int ldb, const Sched& S, const Epi& E) {
;     ...
;         for (int t = 0; t < nt; t += 2) {
;             const bool last = (t == nt - 2);
;             const char* a1 = cA + (size_t)(t + 1) * kstep;
;             const char* a2 = last ? nA : cA + (size_t)(t + 2) * kstep; const char* b2 = last ? nB : cB + (size_t)(t + 2) * kstep;
;             const char* a3 = a2 + kstep; const char* b3 = b2 + kstep;
;             if constexpr (SP2) {
;             PG8_LDB(B0, 0, 0); PG8_LDB(B1, 0, 1); PG8_SCHED; PG8_LDA(At, 0, 0); PG8_STAGE(PG8_SA(1, 1), a1 + hstepA, voffA);
;             PG8_WAIT_V(8); PG8_WAIT_L(0); PG8_BAR; PG8_MMA(0, 0, At, B0); PG8_MMA(0, 1, At, B1); PG8_BAR; PG8_SCHED;
;             PG8_LDA(At, 0, 1); PG8_STAGE(PG8_SB(0, 0), b2, voffB); PG8_STAGE(PG8_SB(0, 1), b2 + hstepB, voffB); PG8_STAGE(PG8_SA(0, 0), a2, voffA);
;             PG8_WAIT_V(8); PG8_WAIT_L(0); PG8_BAR; PG8_MMA(1, 0, At, B0); PG8_MMA(1, 1, At, B1); PG8_BAR; PG8_SCHED;
.LBB0_821:
	v_add_u32_e32 v140, s44, v181
	v_add_u32_e32 v170, s45, v181
	ds_read_b128 v[128:131], v140
	ds_read_b128 v[132:135], v140 offset:1024
	ds_read_b128 v[136:139], v140 offset:2048
	ds_read_b128 v[140:143], v140 offset:3072
	ds_read_b128 v[144:147], v170
	ds_read_b128 v[148:151], v170 offset:1024
	ds_read_b128 v[166:169], v170 offset:2048
	ds_read_b128 v[170:173], v170 offset:3072
	s_add_u32 s20, s4, 0x100
	s_addc_u32 s21, s5, 0
	s_cmp_eq_u32 s61, 12
	s_cselect_b32 s25, s15, s21
	s_cselect_b32 s24, s14, s20
	s_cselect_b32 s23, s17, s60
	s_cselect_b32 s22, s16, s53
	v_lshl_add_u64 v[174:175], s[4:5], 0, v[162:163]
	s_add_i32 m0, s29, 0xc000
	ds_read_b128 v[184:187], v183
	ds_read_b128 v[188:191], v183 offset:1024
	ds_read_b128 v[192:195], v183 offset:2048
	ds_read_b128 v[196:199], v183 offset:3072
	ds_read_b128 v[200:203], v183 offset:4096
	ds_read_b128 v[204:207], v183 offset:5120
	ds_read_b128 v[208:211], v183 offset:6144
	ds_read_b128 v[212:215], v183 offset:7168
	global_load_lds_dwordx4 v[174:175], off
	v_lshl_add_u64 v[174:175], s[4:5], 0, v[164:165]
	s_add_i32 m0, s29, 0xe000
	s_nop 0
	global_load_lds_dwordx4 v[174:175], off
	s_waitcnt vmcnt(8)
	s_waitcnt lgkmcnt(0)
	s_barrier
	s_waitcnt lgkmcnt(0)
	v_mfma_f32_16x16x32_bf16 v[124:127], v[128:131], v[184:187], v[124:127]
	v_mfma_f32_16x16x32_bf16 v[120:123], v[136:139], v[184:187], v[120:123]
	v_mfma_f32_16x16x32_bf16 v[116:119], v[128:131], v[192:195], v[116:119]
	v_mfma_f32_16x16x32_bf16 v[112:115], v[136:139], v[192:195], v[112:115]
	v_mfma_f32_16x16x32_bf16 v[108:111], v[128:131], v[200:203], v[108:111]
	v_mfma_f32_16x16x32_bf16 v[104:107], v[136:139], v[200:203], v[104:107]
	v_mfma_f32_16x16x32_bf16 v[100:103], v[128:131], v[208:211], v[100:103]
	v_mfma_f32_16x16x32_bf16 v[96:99], v[136:139], v[208:211], v[96:99]
	v_mfma_f32_16x16x32_bf16 v[124:127], v[132:135], v[188:191], v[124:127]
	v_mfma_f32_16x16x32_bf16 v[120:123], v[140:143], v[188:191], v[120:123]
	v_mfma_f32_16x16x32_bf16 v[116:119], v[132:135], v[196:199], v[116:119]
	v_mfma_f32_16x16x32_bf16 v[112:115], v[140:143], v[196:199], v[112:115]
	v_mfma_f32_16x16x32_bf16 v[108:111], v[132:135], v[204:207], v[108:111]
	v_mfma_f32_16x16x32_bf16 v[104:107], v[140:143], v[204:207], v[104:107]
	v_mfma_f32_16x16x32_bf16 v[100:103], v[132:135], v[212:215], v[100:103]
	v_mfma_f32_16x16x32_bf16 v[96:99], v[140:143], v[212:215], v[96:99]
	v_mfma_f32_16x16x32_bf16 v[92:95], v[144:147], v[184:187], v[92:95]
	v_mfma_f32_16x16x32_bf16 v[88:91], v[166:169], v[184:187], v[88:91]
	v_mfma_f32_16x16x32_bf16 v[84:87], v[144:147], v[192:195], v[84:87]
	v_mfma_f32_16x16x32_bf16 v[80:83], v[166:169], v[192:195], v[80:83]
	v_mfma_f32_16x16x32_bf16 v[76:79], v[144:147], v[200:203], v[76:79]
	v_mfma_f32_16x16x32_bf16 v[72:75], v[166:169], v[200:203], v[72:75]
	v_mfma_f32_16x16x32_bf16 v[68:71], v[144:147], v[208:211], v[68:71]
	v_mfma_f32_16x16x32_bf16 v[64:67], v[166:169], v[208:211], v[64:67]
	v_mfma_f32_16x16x32_bf16 v[92:95], v[148:151], v[188:191], v[92:95]
	v_mfma_f32_16x16x32_bf16 v[88:91], v[170:173], v[188:191], v[88:91]
	v_mfma_f32_16x16x32_bf16 v[84:87], v[148:151], v[196:199], v[84:87]
	v_mfma_f32_16x16x32_bf16 v[80:83], v[170:173], v[196:199], v[80:83]
	v_mfma_f32_16x16x32_bf16 v[76:79], v[148:151], v[204:207], v[76:79]
	v_mfma_f32_16x16x32_bf16 v[72:75], v[170:173], v[204:207], v[72:75]
	v_mfma_f32_16x16x32_bf16 v[68:71], v[148:151], v[212:215], v[68:71]
	v_mfma_f32_16x16x32_bf16 v[64:67], v[170:173], v[212:215], v[64:67]
	s_barrier
	s_add_i32 s4, s44, s28
	v_lshl_add_u64 v[174:175], s[22:23], 0, v[156:157]
	s_mov_b32 m0, s4
	ds_read_b128 v[184:187], v183 offset:16384
	ds_read_b128 v[188:191], v183 offset:17408
	ds_read_b128 v[192:195], v183 offset:18432
	ds_read_b128 v[196:199], v183 offset:19456
	ds_read_b128 v[200:203], v183 offset:20480
	ds_read_b128 v[204:207], v183 offset:21504
	ds_read_b128 v[208:211], v183 offset:22528
	ds_read_b128 v[212:215], v183 offset:23552
	global_load_lds_dwordx4 v[174:175], off
	s_add_i32 m0, s4, 0x2000
	s_add_u32 s4, s22, 0x40000
	v_lshl_add_u64 v[216:217], s[22:23], 0, v[160:161]
	s_addc_u32 s5, s23, 0
	s_add_i32 s62, s45, s28
	global_load_lds_dwordx4 v[216:217], off
	v_lshl_add_u64 v[218:219], s[4:5], 0, v[156:157]
	s_mov_b32 m0, s62
	v_lshl_add_u64 v[220:221], s[24:25], 0, v[158:159]
	global_load_lds_dwordx4 v[218:219], off
	v_lshl_add_u64 v[218:219], s[4:5], 0, v[160:161]
	s_add_i32 m0, s62, 0x2000
	s_nop 0
	global_load_lds_dwordx4 v[218:219], off
	v_lshl_add_u64 v[218:219], s[24:25], 0, v[154:155]
	s_mov_b32 m0, s29
	s_nop 0
	global_load_lds_dwordx4 v[218:219], off
	s_mov_b32 m0, s33
	s_nop 0
	global_load_lds_dwordx4 v[220:221], off
	s_waitcnt vmcnt(8)
	s_waitcnt lgkmcnt(0)
	s_barrier
; #define PG8_STAGE(bufoff, gbase, voff) do { _Pragma("unroll") for (int _i = 0; _i < 2; ++_i) \
;         __builtin_amdgcn_global_load_lds((const unsigned*)((const char*)(gbase) + (voff)[_i]), (LAS unsigned*)(lds + (bufoff) + ldsw + _i * 8192), 16, 0, 0); } while (0)
; #define PG8_LDA(dst, b, h) do { _Pragma("unroll") for (int m = 0; m < 4; ++m) _Pragma("unroll") for (int k = 0; k < 2; ++k) dst[m][k] = *(const LAS bf16x8*)(lds + PG8_SA(b, h) + aoff + m * 2048 + k * 1024); } while (0)
; #define PG8_LDB(dst, b, h) do { _Pragma("unroll") for (int n = 0; n < 2; ++n) _Pragma("unroll") for (int k = 0; k < 2; ++k) dst[n][k] = *(const LAS bf16x8*)(lds + PG8_SB(b, h) + boff + n * 2048 + k * 1024); } while (0)
; #define PG8_MMA(ai, bj, At, Bt) do { __builtin_amdgcn_s_setprio(1); _Pragma("unroll") for (int m = 0; m < 4; ++m) _Pragma("unroll") for (int n = 0; n < 2; ++n) _Pragma("unroll") for (int k = 0; k < 2; ++k) \
;         acc[ai][bj][m][n] = __builtin_amdgcn_mfma_f32_16x16x32_bf16(Bt[n][k], At[m][k], acc[ai][bj][m][n], 0, 0, 0); __builtin_amdgcn_s_setprio(0); } while (0)
; #define PG8_WAIT_V(n) asm volatile("s_waitcnt vmcnt(" #n ")" ::: "memory")
; #define PG8_WAIT_L(n) asm volatile("s_waitcnt lgkmcnt(" #n ")" ::: "memory")
; #define PG8_BAR __builtin_amdgcn_s_barrier()
; #define PG8_SCHED __builtin_amdgcn_sched_barrier(0)
; template <class Sched, class Epi, bool ALIGN_EPI, bool SP2>
; __device__ __forceinline__ void gemm_phase(LAS unsigned char* lds, const int K, const int lda, const int ldb, const Sched& S, const Epi& E) {
;     ...
;             PG8_WAIT_V(8); PG8_WAIT_L(0); PG8_BAR; PG8_MMA(1, 0, At, B0); PG8_MMA(1, 1, At, B1); PG8_BAR; PG8_SCHED;
;             PG8_LDB(B0, 1, 0); PG8_LDB(B1, 1, 1); PG8_SCHED; PG8_LDA(At, 1, 0); PG8_STAGE(PG8_SA(0, 1), a2 + hstepA, voffA);
;             PG8_WAIT_V(8); PG8_WAIT_L(0); PG8_BAR; PG8_MMA(0, 0, At, B0); PG8_MMA(0, 1, At, B1); PG8_BAR; PG8_SCHED;
;             PG8_LDA(At, 1, 1); PG8_STAGE(PG8_SB(1, 0), b3, voffB); PG8_STAGE(PG8_SB(1, 1), b3 + hstepB, voffB); PG8_STAGE(PG8_SA(1, 0), a3, voffA);
	s_waitcnt lgkmcnt(0)
	v_mfma_f32_16x16x32_bf16 v[60:63], v[128:131], v[184:187], v[60:63]
	v_mfma_f32_16x16x32_bf16 v[56:59], v[136:139], v[184:187], v[56:59]
	v_mfma_f32_16x16x32_bf16 v[52:55], v[128:131], v[192:195], v[52:55]
	v_mfma_f32_16x16x32_bf16 v[48:51], v[136:139], v[192:195], v[48:51]
	v_mfma_f32_16x16x32_bf16 v[44:47], v[128:131], v[200:203], v[44:47]
	v_mfma_f32_16x16x32_bf16 v[40:43], v[136:139], v[200:203], v[40:43]
	v_mfma_f32_16x16x32_bf16 v[36:39], v[128:131], v[208:211], v[36:39]
	v_mfma_f32_16x16x32_bf16 v[32:35], v[136:139], v[208:211], v[32:35]
	v_mfma_f32_16x16x32_bf16 v[60:63], v[132:135], v[188:191], v[60:63]
	v_mfma_f32_16x16x32_bf16 v[56:59], v[140:143], v[188:191], v[56:59]
	v_mfma_f32_16x16x32_bf16 v[52:55], v[132:135], v[196:199], v[52:55]
	v_mfma_f32_16x16x32_bf16 v[48:51], v[140:143], v[196:199], v[48:51]
	v_mfma_f32_16x16x32_bf16 v[44:47], v[132:135], v[204:207], v[44:47]
	v_mfma_f32_16x16x32_bf16 v[40:43], v[140:143], v[204:207], v[40:43]
	v_mfma_f32_16x16x32_bf16 v[36:39], v[132:135], v[212:215], v[36:39]
	v_mfma_f32_16x16x32_bf16 v[32:35], v[140:143], v[212:215], v[32:35]
	v_mfma_f32_16x16x32_bf16 v[28:31], v[144:147], v[184:187], v[28:31]
	v_mfma_f32_16x16x32_bf16 v[24:27], v[166:169], v[184:187], v[24:27]
	v_mfma_f32_16x16x32_bf16 v[20:23], v[144:147], v[192:195], v[20:23]
	v_mfma_f32_16x16x32_bf16 v[16:19], v[166:169], v[192:195], v[16:19]
	v_mfma_f32_16x16x32_bf16 v[12:15], v[144:147], v[200:203], v[12:15]
	v_mfma_f32_16x16x32_bf16 v[8:11], v[166:169], v[200:203], v[8:11]
	v_mfma_f32_16x16x32_bf16 v[4:7], v[144:147], v[208:211], v[4:7]
	v_mfma_f32_16x16x32_bf16 v[0:3], v[166:169], v[208:211], v[0:3]
	v_mfma_f32_16x16x32_bf16 v[28:31], v[148:151], v[188:191], v[28:31]
	v_mfma_f32_16x16x32_bf16 v[24:27], v[170:173], v[188:191], v[24:27]
	v_mfma_f32_16x16x32_bf16 v[20:23], v[148:151], v[196:199], v[20:23]
	v_mfma_f32_16x16x32_bf16 v[16:19], v[170:173], v[196:199], v[16:19]
	v_mfma_f32_16x16x32_bf16 v[12:15], v[148:151], v[204:207], v[12:15]
	v_mfma_f32_16x16x32_bf16 v[8:11], v[170:173], v[204:207], v[8:11]
	v_mfma_f32_16x16x32_bf16 v[4:7], v[148:151], v[212:215], v[4:7]
	v_mfma_f32_16x16x32_bf16 v[0:3], v[170:173], v[212:215], v[0:3]
	s_barrier
	s_add_i32 s62, 0, 0x18000
	s_add_i32 s63, 0, 0x1c000
	v_add_u32_e32 v140, s62, v181
	v_add_u32_e32 v170, s63, v181
	ds_read_b128 v[128:131], v140
	ds_read_b128 v[132:135], v140 offset:1024
	ds_read_b128 v[136:139], v140 offset:2048
	ds_read_b128 v[140:143], v140 offset:3072
	ds_read_b128 v[144:147], v170
	ds_read_b128 v[148:151], v170 offset:1024
	ds_read_b128 v[166:169], v170 offset:2048
	ds_read_b128 v[170:173], v170 offset:3072
	s_add_u32 s4, s24, 0xc0000
	s_addc_u32 s5, s25, 0
	s_mov_b32 m0, s35
	v_lshl_add_u64 v[222:223], s[4:5], 0, v[154:155]
	ds_read_b128 v[184:187], v183 offset:32768
	ds_read_b128 v[188:191], v183 offset:33792
	ds_read_b128 v[192:195], v183 offset:34816
	ds_read_b128 v[196:199], v183 offset:35840
	ds_read_b128 v[200:203], v183 offset:36864
	ds_read_b128 v[204:207], v183 offset:37888
	ds_read_b128 v[208:211], v183 offset:38912
	ds_read_b128 v[212:215], v183 offset:39936
	global_load_lds_dwordx4 v[222:223], off
	v_lshl_add_u64 v[222:223], s[4:5], 0, v[158:159]
	s_mov_b32 m0, s36
	s_nop 0
	global_load_lds_dwordx4 v[222:223], off
	s_waitcnt vmcnt(8)
	s_waitcnt lgkmcnt(0)
	s_barrier
	s_waitcnt lgkmcnt(0)
	v_mfma_f32_16x16x32_bf16 v[124:127], v[128:131], v[184:187], v[124:127]
	v_mfma_f32_16x16x32_bf16 v[120:123], v[136:139], v[184:187], v[120:123]
	v_mfma_f32_16x16x32_bf16 v[116:119], v[128:131], v[192:195], v[116:119]
	v_mfma_f32_16x16x32_bf16 v[112:115], v[136:139], v[192:195], v[112:115]
	v_mfma_f32_16x16x32_bf16 v[108:111], v[128:131], v[200:203], v[108:111]
	v_mfma_f32_16x16x32_bf16 v[104:107], v[136:139], v[200:203], v[104:107]
	v_mfma_f32_16x16x32_bf16 v[100:103], v[128:131], v[208:211], v[100:103]
	v_mfma_f32_16x16x32_bf16 v[96:99], v[136:139], v[208:211], v[96:99]
	v_mfma_f32_16x16x32_bf16 v[124:127], v[132:135], v[188:191], v[124:127]
	v_mfma_f32_16x16x32_bf16 v[120:123], v[140:143], v[188:191], v[120:123]
	v_mfma_f32_16x16x32_bf16 v[116:119], v[132:135], v[196:199], v[116:119]
	v_mfma_f32_16x16x32_bf16 v[112:115], v[140:143], v[196:199], v[112:115]
	v_mfma_f32_16x16x32_bf16 v[108:111], v[132:135], v[204:207], v[108:111]
	v_mfma_f32_16x16x32_bf16 v[104:107], v[140:143], v[204:207], v[104:107]
	v_mfma_f32_16x16x32_bf16 v[100:103], v[132:135], v[212:215], v[100:103]
	v_mfma_f32_16x16x32_bf16 v[96:99], v[140:143], v[212:215], v[96:99]
	v_mfma_f32_16x16x32_bf16 v[92:95], v[144:147], v[184:187], v[92:95]
	v_mfma_f32_16x16x32_bf16 v[88:91], v[166:169], v[184:187], v[88:91]
	v_mfma_f32_16x16x32_bf16 v[84:87], v[144:147], v[192:195], v[84:87]
	v_mfma_f32_16x16x32_bf16 v[80:83], v[166:169], v[192:195], v[80:83]
	v_mfma_f32_16x16x32_bf16 v[76:79], v[144:147], v[200:203], v[76:79]
	v_mfma_f32_16x16x32_bf16 v[72:75], v[166:169], v[200:203], v[72:75]
	v_mfma_f32_16x16x32_bf16 v[68:71], v[144:147], v[208:211], v[68:71]
	v_mfma_f32_16x16x32_bf16 v[64:67], v[166:169], v[208:211], v[64:67]
	v_mfma_f32_16x16x32_bf16 v[92:95], v[148:151], v[188:191], v[92:95]
	v_mfma_f32_16x16x32_bf16 v[88:91], v[170:173], v[188:191], v[88:91]
	v_mfma_f32_16x16x32_bf16 v[84:87], v[148:151], v[196:199], v[84:87]
	v_mfma_f32_16x16x32_bf16 v[80:83], v[170:173], v[196:199], v[80:83]
	v_mfma_f32_16x16x32_bf16 v[76:79], v[148:151], v[204:207], v[76:79]
	v_mfma_f32_16x16x32_bf16 v[72:75], v[170:173], v[204:207], v[72:75]
	v_mfma_f32_16x16x32_bf16 v[68:71], v[148:151], v[212:215], v[68:71]
	v_mfma_f32_16x16x32_bf16 v[64:67], v[170:173], v[212:215], v[64:67]
	s_barrier
; #define PG8_STAGE(bufoff, gbase, voff) do { _Pragma("unroll") for (int _i = 0; _i < 2; ++_i) \
;         __builtin_amdgcn_global_load_lds((const unsigned*)((const char*)(gbase) + (voff)[_i]), (LAS unsigned*)(lds + (bufoff) + ldsw + _i * 8192), 16, 0, 0); } while (0)
; #define PG8_LDA(dst, b, h) do { _Pragma("unroll") for (int m = 0; m < 4; ++m) _Pragma("unroll") for (int k = 0; k < 2; ++k) dst[m][k] = *(const LAS bf16x8*)(lds + PG8_SA(b, h) + aoff + m * 2048 + k * 1024); } while (0)
; #define PG8_MMA(ai, bj, At, Bt) do { __builtin_amdgcn_s_setprio(1); _Pragma("unroll") for (int m = 0; m < 4; ++m) _Pragma("unroll") for (int n = 0; n < 2; ++n) _Pragma("unroll") for (int k = 0; k < 2; ++k) \
;         acc[ai][bj][m][n] = __builtin_amdgcn_mfma_f32_16x16x32_bf16(Bt[n][k], At[m][k], acc[ai][bj][m][n], 0, 0, 0); __builtin_amdgcn_s_setprio(0); } while (0)
; #define PG8_WAIT_V(n) asm volatile("s_waitcnt vmcnt(" #n ")" ::: "memory")
; #define PG8_WAIT_L(n) asm volatile("s_waitcnt lgkmcnt(" #n ")" ::: "memory")
; #define PG8_BAR __builtin_amdgcn_s_barrier()
; #define PG8_SCHED __builtin_amdgcn_sched_barrier(0)
; template <class Sched, class Epi, bool ALIGN_EPI, bool SP2>
; __device__ __forceinline__ void gemm_phase(LAS unsigned char* lds, const int K, const int lda, const int ldb, const Sched& S, const Epi& E) {
;     ...
;             PG8_LDA(At, 1, 1); PG8_STAGE(PG8_SB(1, 0), b3, voffB); PG8_STAGE(PG8_SB(1, 1), b3 + hstepB, voffB); PG8_STAGE(PG8_SA(1, 0), a3, voffA);
;             PG8_WAIT_V(8); PG8_WAIT_L(0); PG8_BAR; PG8_MMA(1, 0, At, B0); PG8_MMA(1, 1, At, B1); PG8_BAR; PG8_SCHED;
	s_add_i32 s4, s62, s28
	v_lshl_add_u64 v[174:175], v[174:175], 0, s[8:9]
	s_mov_b32 m0, s4
	ds_read_b128 v[184:187], v183 offset:49152
	ds_read_b128 v[188:191], v183 offset:50176
	ds_read_b128 v[192:195], v183 offset:51200
	ds_read_b128 v[196:199], v183 offset:52224
	ds_read_b128 v[200:203], v183 offset:53248
	ds_read_b128 v[204:207], v183 offset:54272
	ds_read_b128 v[208:211], v183 offset:55296
	ds_read_b128 v[212:215], v183 offset:56320
	global_load_lds_dwordx4 v[174:175], off
	s_add_i32 m0, s4, 0x2000
	s_add_u32 s4, s22, 0x40080
	v_lshl_add_u64 v[174:175], v[216:217], 0, s[8:9]
	s_addc_u32 s5, s23, 0
	s_add_i32 s22, s63, s28
	global_load_lds_dwordx4 v[174:175], off
	v_lshl_add_u64 v[174:175], s[4:5], 0, v[156:157]
	s_mov_b32 m0, s22
	s_nop 0
	global_load_lds_dwordx4 v[174:175], off
	v_lshl_add_u64 v[174:175], s[4:5], 0, v[160:161]
	s_add_i32 m0, s22, 0x2000
	s_nop 0
	global_load_lds_dwordx4 v[174:175], off
	v_lshl_add_u64 v[174:175], v[218:219], 0, s[8:9]
	s_mov_b32 m0, s42
	s_nop 0
	global_load_lds_dwordx4 v[174:175], off
	v_lshl_add_u64 v[174:175], v[220:221], 0, s[8:9]
	s_mov_b32 m0, s43
	s_nop 0
	global_load_lds_dwordx4 v[174:175], off
	s_waitcnt vmcnt(8)
	s_waitcnt lgkmcnt(0)
	s_barrier
	s_waitcnt lgkmcnt(0)
	v_mfma_f32_16x16x32_bf16 v[60:63], v[128:131], v[184:187], v[60:63]
	v_mfma_f32_16x16x32_bf16 v[56:59], v[136:139], v[184:187], v[56:59]
	v_mfma_f32_16x16x32_bf16 v[52:55], v[128:131], v[192:195], v[52:55]
	v_mfma_f32_16x16x32_bf16 v[48:51], v[136:139], v[192:195], v[48:51]
	v_mfma_f32_16x16x32_bf16 v[44:47], v[128:131], v[200:203], v[44:47]
	v_mfma_f32_16x16x32_bf16 v[40:43], v[136:139], v[200:203], v[40:43]
	v_mfma_f32_16x16x32_bf16 v[36:39], v[128:131], v[208:211], v[36:39]
	v_mfma_f32_16x16x32_bf16 v[32:35], v[136:139], v[208:211], v[32:35]
	v_mfma_f32_16x16x32_bf16 v[60:63], v[132:135], v[188:191], v[60:63]
	v_mfma_f32_16x16x32_bf16 v[56:59], v[140:143], v[188:191], v[56:59]
	v_mfma_f32_16x16x32_bf16 v[52:55], v[132:135], v[196:199], v[52:55]
	v_mfma_f32_16x16x32_bf16 v[48:51], v[140:143], v[196:199], v[48:51]
	v_mfma_f32_16x16x32_bf16 v[44:47], v[132:135], v[204:207], v[44:47]
	v_mfma_f32_16x16x32_bf16 v[40:43], v[140:143], v[204:207], v[40:43]
	v_mfma_f32_16x16x32_bf16 v[36:39], v[132:135], v[212:215], v[36:39]
	v_mfma_f32_16x16x32_bf16 v[32:35], v[140:143], v[212:215], v[32:35]
	v_mfma_f32_16x16x32_bf16 v[28:31], v[144:147], v[184:187], v[28:31]
	v_mfma_f32_16x16x32_bf16 v[24:27], v[166:169], v[184:187], v[24:27]
	v_mfma_f32_16x16x32_bf16 v[20:23], v[144:147], v[192:195], v[20:23]
	v_mfma_f32_16x16x32_bf16 v[16:19], v[166:169], v[192:195], v[16:19]
	v_mfma_f32_16x16x32_bf16 v[12:15], v[144:147], v[200:203], v[12:15]
	v_mfma_f32_16x16x32_bf16 v[8:11], v[166:169], v[200:203], v[8:11]
	v_mfma_f32_16x16x32_bf16 v[4:7], v[144:147], v[208:211], v[4:7]
	v_mfma_f32_16x16x32_bf16 v[0:3], v[166:169], v[208:211], v[0:3]
	v_mfma_f32_16x16x32_bf16 v[28:31], v[148:151], v[188:191], v[28:31]
	v_mfma_f32_16x16x32_bf16 v[24:27], v[170:173], v[188:191], v[24:27]
	v_mfma_f32_16x16x32_bf16 v[20:23], v[148:151], v[196:199], v[20:23]
	v_mfma_f32_16x16x32_bf16 v[16:19], v[170:173], v[196:199], v[16:19]
	v_mfma_f32_16x16x32_bf16 v[12:15], v[148:151], v[204:207], v[12:15]
	v_mfma_f32_16x16x32_bf16 v[8:11], v[170:173], v[204:207], v[8:11]
	v_mfma_f32_16x16x32_bf16 v[4:7], v[148:151], v[212:215], v[4:7]
	v_mfma_f32_16x16x32_bf16 v[0:3], v[170:173], v[212:215], v[0:3]
	s_barrier
	s_add_i32 s61, s61, 2
	s_add_u32 s53, s53, 0x100
	s_addc_u32 s60, s60, 0
	s_cmp_gt_u32 s61, 13
	s_mov_b64 s[4:5], s[20:21]
	s_cbranch_scc0 .LBB0_821
	s_and_b64 vcc, exec, s[10:11]
	s_cbranch_vccz .LBB0_824
	s_barrier

; #define PG8_STAGE(bufoff, gbase, voff) do { _Pragma("unroll") for (int _i = 0; _i < 2; ++_i) \
;         __builtin_amdgcn_global_load_lds((const unsigned*)((const char*)(gbase) + (voff)[_i]), (LAS unsigned*)(lds + (bufoff) + ldsw + _i * 8192), 16, 0, 0); } while (0)
; #define PG8_LDA(dst, b, h) do { _Pragma("unroll") for (int m = 0; m < 4; ++m) _Pragma("unroll") for (int k = 0; k < 2; ++k) dst[m][k] = *(const LAS bf16x8*)(lds + PG8_SA(b, h) + aoff + m * 2048 + k * 1024); } while (0)
; #define PG8_LDB(dst, b, h) do { _Pragma("unroll") for (int n = 0; n < 2; ++n) _Pragma("unroll") for (int k = 0; k < 2; ++k) dst[n][k] = *(const LAS bf16x8*)(lds + PG8_SB(b, h) + boff + n * 2048 + k * 1024); } while (0)
; #define PG8_MMA(ai, bj, At, Bt) do { __builtin_amdgcn_s_setprio(1); _Pragma("unroll") for (int m = 0; m < 4; ++m) _Pragma("unroll") for (int n = 0; n < 2; ++n) _Pragma("unroll") for (int k = 0; k < 2; ++k) \
;         acc[ai][bj][m][n] = __builtin_amdgcn_mfma_f32_16x16x32_bf16(Bt[n][k], At[m][k], acc[ai][bj][m][n], 0, 0, 0); __builtin_amdgcn_s_setprio(0); } while (0)
; #define PG8_WAIT_V(n) asm volatile("s_waitcnt vmcnt(" #n ")" ::: "memory")
; #define PG8_WAIT_L(n) asm volatile("s_waitcnt lgkmcnt(" #n ")" ::: "memory")
; #define PG8_BAR __builtin_amdgcn_s_barrier()
; template <class Sched, class Epi, bool ALIGN_EPI, bool SP2>
; __device__ __forceinline__ void gemm_phase(LAS unsigned char* lds, const int K, const int lda, const int ldb, const Sched& S, const Epi& E) {
;     ...
;         for (int t = 0; t < nt; t += 2) {
;             const bool last = (t == nt - 2);
;             const char* a1 = cA + (size_t)(t + 1) * kstep;
;             const char* a2 = last ? nA : cA + (size_t)(t + 2) * kstep; const char* b2 = last ? nB : cB + (size_t)(t + 2) * kstep;
;             const char* a3 = a2 + kstep; const char* b3 = b2 + kstep;
;             if constexpr (SP2) {
;             PG8_LDB(B0, 0, 0); PG8_LDB(B1, 0, 1); PG8_SCHED; PG8_LDA(At, 0, 0); PG8_STAGE(PG8_SA(1, 1), a1 + hstepA, voffA);
;             PG8_WAIT_V(8); PG8_WAIT_L(0); PG8_BAR; PG8_MMA(0, 0, At, B0); PG8_MMA(0, 1, At, B1); PG8_BAR; PG8_SCHED;
;             PG8_LDA(At, 0, 1); PG8_STAGE(PG8_SB(0, 0), b2, voffB); PG8_STAGE(PG8_SB(0, 1), b2 + hstepB, voffB); PG8_STAGE(PG8_SA(0, 0), a2, voffA);
;             PG8_WAIT_V(8); PG8_WAIT_L(0); PG8_BAR; PG8_MMA(1, 0, At, B0); PG8_MMA(1, 1, At, B1); PG8_BAR; PG8_SCHED;
.LBB0_945:
	ds_read_b128 v[52:55], v209
	ds_read_b128 v[56:59], v209 offset:1024
	ds_read_b128 v[64:67], v209 offset:2048
	ds_read_b128 v[68:71], v209 offset:3072
	ds_read_b128 v[72:75], v210
	ds_read_b128 v[76:79], v210 offset:1024
	ds_read_b128 v[88:91], v210 offset:2048
	ds_read_b128 v[92:95], v210 offset:3072
	s_add_u32 s42, s36, 0xfff80080
	s_addc_u32 s43, s37, -1
	s_cmp_eq_u32 s61, 28
	s_cselect_b32 s45, s27, s43
	s_cselect_b32 s44, s26, s42
	s_cselect_b32 s43, s29, s25
	s_cselect_b32 s42, s28, s1
	v_lshl_add_u64 v[206:207], s[36:37], 0, v[186:187]
	s_add_i32 m0, s21, 0xc000
	ds_read_b128 v[160:163], v211
	ds_read_b128 v[164:167], v211 offset:1024
	ds_read_b128 v[168:171], v211 offset:2048
	ds_read_b128 v[172:175], v211 offset:3072
	ds_read_b128 v[190:193], v211 offset:4096
	ds_read_b128 v[194:197], v211 offset:5120
	ds_read_b128 v[198:201], v211 offset:6144
	ds_read_b128 v[202:205], v211 offset:7168
	global_load_lds_dwordx4 v[206:207], off
	v_lshl_add_u64 v[206:207], s[36:37], 0, v[188:189]
	s_add_i32 m0, s21, 0xe000
	s_nop 0
	global_load_lds_dwordx4 v[206:207], off
	s_waitcnt vmcnt(8)
	s_waitcnt lgkmcnt(0)
	s_barrier
	s_waitcnt lgkmcnt(0)
	v_mfma_f32_16x16x32_bf16 v[156:159], v[52:55], v[160:163], v[156:159]
	v_mfma_f32_16x16x32_bf16 v[152:155], v[64:67], v[160:163], v[152:155]
	v_mfma_f32_16x16x32_bf16 v[140:143], v[52:55], v[168:171], v[140:143]
	v_mfma_f32_16x16x32_bf16 v[136:139], v[64:67], v[168:171], v[136:139]
	v_mfma_f32_16x16x32_bf16 v[124:127], v[52:55], v[190:193], v[124:127]
	v_mfma_f32_16x16x32_bf16 v[120:123], v[64:67], v[190:193], v[120:123]
	v_mfma_f32_16x16x32_bf16 v[108:111], v[52:55], v[198:201], v[108:111]
	v_mfma_f32_16x16x32_bf16 v[104:107], v[64:67], v[198:201], v[104:107]
	v_mfma_f32_16x16x32_bf16 v[156:159], v[56:59], v[164:167], v[156:159]
	v_mfma_f32_16x16x32_bf16 v[152:155], v[68:71], v[164:167], v[152:155]
	v_mfma_f32_16x16x32_bf16 v[140:143], v[56:59], v[172:175], v[140:143]
	v_mfma_f32_16x16x32_bf16 v[136:139], v[68:71], v[172:175], v[136:139]
	v_mfma_f32_16x16x32_bf16 v[124:127], v[56:59], v[194:197], v[124:127]
	v_mfma_f32_16x16x32_bf16 v[120:123], v[68:71], v[194:197], v[120:123]
	v_mfma_f32_16x16x32_bf16 v[108:111], v[56:59], v[202:205], v[108:111]
	v_mfma_f32_16x16x32_bf16 v[104:107], v[68:71], v[202:205], v[104:107]
	v_mfma_f32_16x16x32_bf16 v[148:151], v[72:75], v[160:163], v[148:151]
	v_mfma_f32_16x16x32_bf16 v[144:147], v[88:91], v[160:163], v[144:147]
	v_mfma_f32_16x16x32_bf16 v[132:135], v[72:75], v[168:171], v[132:135]
	v_mfma_f32_16x16x32_bf16 v[128:131], v[88:91], v[168:171], v[128:131]
	v_mfma_f32_16x16x32_bf16 v[116:119], v[72:75], v[190:193], v[116:119]
	v_mfma_f32_16x16x32_bf16 v[112:115], v[88:91], v[190:193], v[112:115]
	v_mfma_f32_16x16x32_bf16 v[100:103], v[72:75], v[198:201], v[100:103]
	v_mfma_f32_16x16x32_bf16 v[96:99], v[88:91], v[198:201], v[96:99]
	v_mfma_f32_16x16x32_bf16 v[148:151], v[76:79], v[164:167], v[148:151]
	v_mfma_f32_16x16x32_bf16 v[144:147], v[92:95], v[164:167], v[144:147]
	v_mfma_f32_16x16x32_bf16 v[132:135], v[76:79], v[172:175], v[132:135]
	v_mfma_f32_16x16x32_bf16 v[128:131], v[92:95], v[172:175], v[128:131]
	v_mfma_f32_16x16x32_bf16 v[116:119], v[76:79], v[194:197], v[116:119]
	v_mfma_f32_16x16x32_bf16 v[112:115], v[92:95], v[194:197], v[112:115]
	v_mfma_f32_16x16x32_bf16 v[100:103], v[76:79], v[202:205], v[100:103]
	v_mfma_f32_16x16x32_bf16 v[96:99], v[92:95], v[202:205], v[96:99]
	s_barrier
	s_add_i32 s62, s50, s19
	v_lshl_add_u64 v[206:207], s[42:43], 0, v[182:183]
	s_mov_b32 m0, s62
	ds_read_b128 v[160:163], v211 offset:16384
	ds_read_b128 v[164:167], v211 offset:17408
	ds_read_b128 v[168:171], v211 offset:18432
	ds_read_b128 v[172:175], v211 offset:19456
	ds_read_b128 v[190:193], v211 offset:20480
	ds_read_b128 v[194:197], v211 offset:21504
	ds_read_b128 v[198:201], v211 offset:22528
	ds_read_b128 v[202:205], v211 offset:23552
	global_load_lds_dwordx4 v[206:207], off
	s_add_i32 m0, s62, 0x2000
	s_add_u32 s62, s42, 0x80000
	v_lshl_add_u64 v[214:215], s[42:43], 0, v[184:185]
	s_addc_u32 s63, s43, 0
	s_add_i32 s64, s51, s19
	global_load_lds_dwordx4 v[214:215], off
	v_lshl_add_u64 v[216:217], s[62:63], 0, v[182:183]
	s_mov_b32 m0, s64
	v_lshl_add_u64 v[218:219], s[44:45], 0, v[184:185]
	global_load_lds_dwordx4 v[216:217], off
	v_lshl_add_u64 v[216:217], s[62:63], 0, v[184:185]
	s_add_i32 m0, s64, 0x2000
	s_nop 0
	global_load_lds_dwordx4 v[216:217], off
	v_lshl_add_u64 v[216:217], s[44:45], 0, v[182:183]
	s_mov_b32 m0, s21
	s_nop 0
	global_load_lds_dwordx4 v[216:217], off
	s_mov_b32 m0, s33
	s_nop 0
	global_load_lds_dwordx4 v[218:219], off
	s_waitcnt vmcnt(8)
	s_waitcnt lgkmcnt(0)
	s_barrier
; #define PG8_STAGE(bufoff, gbase, voff) do { _Pragma("unroll") for (int _i = 0; _i < 2; ++_i) \
;         __builtin_amdgcn_global_load_lds((const unsigned*)((const char*)(gbase) + (voff)[_i]), (LAS unsigned*)(lds + (bufoff) + ldsw + _i * 8192), 16, 0, 0); } while (0)
; #define PG8_LDA(dst, b, h) do { _Pragma("unroll") for (int m = 0; m < 4; ++m) _Pragma("unroll") for (int k = 0; k < 2; ++k) dst[m][k] = *(const LAS bf16x8*)(lds + PG8_SA(b, h) + aoff + m * 2048 + k * 1024); } while (0)
; #define PG8_LDB(dst, b, h) do { _Pragma("unroll") for (int n = 0; n < 2; ++n) _Pragma("unroll") for (int k = 0; k < 2; ++k) dst[n][k] = *(const LAS bf16x8*)(lds + PG8_SB(b, h) + boff + n * 2048 + k * 1024); } while (0)
; #define PG8_MMA(ai, bj, At, Bt) do { __builtin_amdgcn_s_setprio(1); _Pragma("unroll") for (int m = 0; m < 4; ++m) _Pragma("unroll") for (int n = 0; n < 2; ++n) _Pragma("unroll") for (int k = 0; k < 2; ++k) \
;         acc[ai][bj][m][n] = __builtin_amdgcn_mfma_f32_16x16x32_bf16(Bt[n][k], At[m][k], acc[ai][bj][m][n], 0, 0, 0); __builtin_amdgcn_s_setprio(0); } while (0)
; #define PG8_WAIT_V(n) asm volatile("s_waitcnt vmcnt(" #n ")" ::: "memory")
; #define PG8_WAIT_L(n) asm volatile("s_waitcnt lgkmcnt(" #n ")" ::: "memory")
; #define PG8_BAR __builtin_amdgcn_s_barrier()
; #define PG8_SCHED __builtin_amdgcn_sched_barrier(0)
; template <class Sched, class Epi, bool ALIGN_EPI, bool SP2>
; __device__ __forceinline__ void gemm_phase(LAS unsigned char* lds, const int K, const int lda, const int ldb, const Sched& S, const Epi& E) {
;     ...
;             PG8_WAIT_V(8); PG8_WAIT_L(0); PG8_BAR; PG8_MMA(1, 0, At, B0); PG8_MMA(1, 1, At, B1); PG8_BAR; PG8_SCHED;
;             PG8_LDB(B0, 1, 0); PG8_LDB(B1, 1, 1); PG8_SCHED; PG8_LDA(At, 1, 0); PG8_STAGE(PG8_SA(0, 1), a2 + hstepA, voffA);
;             PG8_WAIT_V(8); PG8_WAIT_L(0); PG8_BAR; PG8_MMA(0, 0, At, B0); PG8_MMA(0, 1, At, B1); PG8_BAR; PG8_SCHED;
;             PG8_LDA(At, 1, 1); PG8_STAGE(PG8_SB(1, 0), b3, voffB); PG8_STAGE(PG8_SB(1, 1), b3 + hstepB, voffB); PG8_STAGE(PG8_SA(1, 0), a3, voffA);
	s_waitcnt lgkmcnt(0)
	v_mfma_f32_16x16x32_bf16 v[84:87], v[52:55], v[160:163], v[84:87]
	v_mfma_f32_16x16x32_bf16 v[80:83], v[64:67], v[160:163], v[80:83]
	v_mfma_f32_16x16x32_bf16 v[44:47], v[52:55], v[168:171], v[44:47]
	v_mfma_f32_16x16x32_bf16 v[40:43], v[64:67], v[168:171], v[40:43]
	v_mfma_f32_16x16x32_bf16 v[28:31], v[52:55], v[190:193], v[28:31]
	v_mfma_f32_16x16x32_bf16 v[24:27], v[64:67], v[190:193], v[24:27]
	v_mfma_f32_16x16x32_bf16 v[12:15], v[52:55], v[198:201], v[12:15]
	v_mfma_f32_16x16x32_bf16 v[8:11], v[64:67], v[198:201], v[8:11]
	v_mfma_f32_16x16x32_bf16 v[84:87], v[56:59], v[164:167], v[84:87]
	v_mfma_f32_16x16x32_bf16 v[80:83], v[68:71], v[164:167], v[80:83]
	v_mfma_f32_16x16x32_bf16 v[44:47], v[56:59], v[172:175], v[44:47]
	v_mfma_f32_16x16x32_bf16 v[40:43], v[68:71], v[172:175], v[40:43]
	v_mfma_f32_16x16x32_bf16 v[28:31], v[56:59], v[194:197], v[28:31]
	v_mfma_f32_16x16x32_bf16 v[24:27], v[68:71], v[194:197], v[24:27]
	v_mfma_f32_16x16x32_bf16 v[12:15], v[56:59], v[202:205], v[12:15]
	v_mfma_f32_16x16x32_bf16 v[8:11], v[68:71], v[202:205], v[8:11]
	v_mfma_f32_16x16x32_bf16 v[48:51], v[88:91], v[160:163], v[48:51]
	v_mfma_f32_16x16x32_bf16 v[36:39], v[72:75], v[168:171], v[36:39]
	v_mfma_f32_16x16x32_bf16 v[32:35], v[88:91], v[168:171], v[32:35]
	v_mfma_f32_16x16x32_bf16 v[20:23], v[72:75], v[190:193], v[20:23]
	v_mfma_f32_16x16x32_bf16 v[16:19], v[88:91], v[190:193], v[16:19]
	v_mfma_f32_16x16x32_bf16 v[4:7], v[72:75], v[198:201], v[4:7]
	v_mfma_f32_16x16x32_bf16 v[0:3], v[88:91], v[198:201], v[0:3]
	v_mfma_f32_16x16x32_bf16 v[52:55], v[72:75], v[160:163], v[60:63]
	v_mfma_f32_16x16x32_bf16 v[48:51], v[92:95], v[164:167], v[48:51]
	v_mfma_f32_16x16x32_bf16 v[36:39], v[76:79], v[172:175], v[36:39]
	v_mfma_f32_16x16x32_bf16 v[32:35], v[92:95], v[172:175], v[32:35]
	v_mfma_f32_16x16x32_bf16 v[20:23], v[76:79], v[194:197], v[20:23]
	v_mfma_f32_16x16x32_bf16 v[16:19], v[92:95], v[194:197], v[16:19]
	v_mfma_f32_16x16x32_bf16 v[4:7], v[76:79], v[202:205], v[4:7]
	v_mfma_f32_16x16x32_bf16 v[0:3], v[92:95], v[202:205], v[0:3]
	v_mfma_f32_16x16x32_bf16 v[52:55], v[76:79], v[164:167], v[52:55]
	s_barrier
	s_add_i32 s62, 0, 0x18000
	s_add_i32 s63, 0, 0x1c000
	v_add_u32_e32 v68, s62, v181
	v_add_u32_e32 v92, s63, v181
	ds_read_b128 v[56:59], v68
	ds_read_b128 v[60:63], v68 offset:1024
	ds_read_b128 v[64:67], v68 offset:2048
	ds_read_b128 v[68:71], v68 offset:3072
	ds_read_b128 v[72:75], v92
	ds_read_b128 v[76:79], v92 offset:1024
	ds_read_b128 v[88:91], v92 offset:2048
	ds_read_b128 v[92:95], v92 offset:3072
	s_add_u32 s44, s44, 0x80000
	s_addc_u32 s45, s45, 0
	s_mov_b32 m0, s35
	v_lshl_add_u64 v[220:221], s[44:45], 0, v[182:183]
	ds_read_b128 v[160:163], v211 offset:32768
	ds_read_b128 v[164:167], v211 offset:33792
	ds_read_b128 v[168:171], v211 offset:34816
	ds_read_b128 v[172:175], v211 offset:35840
	ds_read_b128 v[190:193], v211 offset:36864
	ds_read_b128 v[194:197], v211 offset:37888
	ds_read_b128 v[198:201], v211 offset:38912
	ds_read_b128 v[202:205], v211 offset:39936
	global_load_lds_dwordx4 v[220:221], off
	v_lshl_add_u64 v[220:221], s[44:45], 0, v[184:185]
	s_mov_b32 m0, s46
	s_nop 0
	global_load_lds_dwordx4 v[220:221], off
	s_waitcnt vmcnt(8)
	s_waitcnt lgkmcnt(0)
	s_barrier
	s_waitcnt lgkmcnt(0)
	v_mfma_f32_16x16x32_bf16 v[156:159], v[56:59], v[160:163], v[156:159]
	v_mfma_f32_16x16x32_bf16 v[152:155], v[64:67], v[160:163], v[152:155]
	v_mfma_f32_16x16x32_bf16 v[140:143], v[56:59], v[168:171], v[140:143]
	v_mfma_f32_16x16x32_bf16 v[136:139], v[64:67], v[168:171], v[136:139]
	v_mfma_f32_16x16x32_bf16 v[124:127], v[56:59], v[190:193], v[124:127]
	v_mfma_f32_16x16x32_bf16 v[120:123], v[64:67], v[190:193], v[120:123]
	v_mfma_f32_16x16x32_bf16 v[108:111], v[56:59], v[198:201], v[108:111]
	v_mfma_f32_16x16x32_bf16 v[104:107], v[64:67], v[198:201], v[104:107]
	v_mfma_f32_16x16x32_bf16 v[156:159], v[60:63], v[164:167], v[156:159]
	v_mfma_f32_16x16x32_bf16 v[152:155], v[68:71], v[164:167], v[152:155]
	v_mfma_f32_16x16x32_bf16 v[140:143], v[60:63], v[172:175], v[140:143]
	v_mfma_f32_16x16x32_bf16 v[136:139], v[68:71], v[172:175], v[136:139]
	v_mfma_f32_16x16x32_bf16 v[124:127], v[60:63], v[194:197], v[124:127]
	v_mfma_f32_16x16x32_bf16 v[120:123], v[68:71], v[194:197], v[120:123]
	v_mfma_f32_16x16x32_bf16 v[108:111], v[60:63], v[202:205], v[108:111]
	v_mfma_f32_16x16x32_bf16 v[104:107], v[68:71], v[202:205], v[104:107]
	v_mfma_f32_16x16x32_bf16 v[148:151], v[72:75], v[160:163], v[148:151]
	v_mfma_f32_16x16x32_bf16 v[144:147], v[88:91], v[160:163], v[144:147]
	v_mfma_f32_16x16x32_bf16 v[132:135], v[72:75], v[168:171], v[132:135]
	v_mfma_f32_16x16x32_bf16 v[128:131], v[88:91], v[168:171], v[128:131]
	v_mfma_f32_16x16x32_bf16 v[116:119], v[72:75], v[190:193], v[116:119]
	v_mfma_f32_16x16x32_bf16 v[112:115], v[88:91], v[190:193], v[112:115]
	v_mfma_f32_16x16x32_bf16 v[100:103], v[72:75], v[198:201], v[100:103]
	v_mfma_f32_16x16x32_bf16 v[96:99], v[88:91], v[198:201], v[96:99]
	v_mfma_f32_16x16x32_bf16 v[148:151], v[76:79], v[164:167], v[148:151]
	v_mfma_f32_16x16x32_bf16 v[144:147], v[92:95], v[164:167], v[144:147]
	v_mfma_f32_16x16x32_bf16 v[132:135], v[76:79], v[172:175], v[132:135]
	v_mfma_f32_16x16x32_bf16 v[128:131], v[92:95], v[172:175], v[128:131]
	v_mfma_f32_16x16x32_bf16 v[116:119], v[76:79], v[194:197], v[116:119]
	v_mfma_f32_16x16x32_bf16 v[112:115], v[92:95], v[194:197], v[112:115]
	v_mfma_f32_16x16x32_bf16 v[100:103], v[76:79], v[202:205], v[100:103]
	v_mfma_f32_16x16x32_bf16 v[96:99], v[92:95], v[202:205], v[96:99]
	s_barrier
; #define PG8_STAGE(bufoff, gbase, voff) do { _Pragma("unroll") for (int _i = 0; _i < 2; ++_i) \
;         __builtin_amdgcn_global_load_lds((const unsigned*)((const char*)(gbase) + (voff)[_i]), (LAS unsigned*)(lds + (bufoff) + ldsw + _i * 8192), 16, 0, 0); } while (0)
; #define PG8_LDA(dst, b, h) do { _Pragma("unroll") for (int m = 0; m < 4; ++m) _Pragma("unroll") for (int k = 0; k < 2; ++k) dst[m][k] = *(const LAS bf16x8*)(lds + PG8_SA(b, h) + aoff + m * 2048 + k * 1024); } while (0)
; #define PG8_MMA(ai, bj, At, Bt) do { __builtin_amdgcn_s_setprio(1); _Pragma("unroll") for (int m = 0; m < 4; ++m) _Pragma("unroll") for (int n = 0; n < 2; ++n) _Pragma("unroll") for (int k = 0; k < 2; ++k) \
;         acc[ai][bj][m][n] = __builtin_amdgcn_mfma_f32_16x16x32_bf16(Bt[n][k], At[m][k], acc[ai][bj][m][n], 0, 0, 0); __builtin_amdgcn_s_setprio(0); } while (0)
; #define PG8_WAIT_V(n) asm volatile("s_waitcnt vmcnt(" #n ")" ::: "memory")
; #define PG8_WAIT_L(n) asm volatile("s_waitcnt lgkmcnt(" #n ")" ::: "memory")
; #define PG8_BAR __builtin_amdgcn_s_barrier()
; #define PG8_SCHED __builtin_amdgcn_sched_barrier(0)
; template <class Sched, class Epi, bool ALIGN_EPI, bool SP2>
; __device__ __forceinline__ void gemm_phase(LAS unsigned char* lds, const int K, const int lda, const int ldb, const Sched& S, const Epi& E) {
;     ...
;             PG8_LDA(At, 1, 1); PG8_STAGE(PG8_SB(1, 0), b3, voffB); PG8_STAGE(PG8_SB(1, 1), b3 + hstepB, voffB); PG8_STAGE(PG8_SA(1, 0), a3, voffA);
;             PG8_WAIT_V(8); PG8_WAIT_L(0); PG8_BAR; PG8_MMA(1, 0, At, B0); PG8_MMA(1, 1, At, B1); PG8_BAR; PG8_SCHED;
;     ...
;         }
;         if constexpr (ALIGN_EPI) { if (wr == 0) PG8_BAR; }
	s_add_i32 s44, s62, s19
	v_lshl_add_u64 v[206:207], v[206:207], 0, s[14:15]
	s_mov_b32 m0, s44
	ds_read_b128 v[160:163], v211 offset:49152
	ds_read_b128 v[164:167], v211 offset:50176
	ds_read_b128 v[168:171], v211 offset:51200
	ds_read_b128 v[172:175], v211 offset:52224
	ds_read_b128 v[190:193], v211 offset:53248
	ds_read_b128 v[194:197], v211 offset:54272
	ds_read_b128 v[198:201], v211 offset:55296
	ds_read_b128 v[202:205], v211 offset:56320
	global_load_lds_dwordx4 v[206:207], off
	s_add_i32 m0, s44, 0x2000
	s_add_u32 s42, s42, 0x80080
	v_lshl_add_u64 v[206:207], v[214:215], 0, s[14:15]
	s_addc_u32 s43, s43, 0
	s_add_i32 s44, s63, s19
	global_load_lds_dwordx4 v[206:207], off
	v_lshl_add_u64 v[206:207], s[42:43], 0, v[182:183]
	s_mov_b32 m0, s44
	s_nop 0
	global_load_lds_dwordx4 v[206:207], off
	v_lshl_add_u64 v[206:207], s[42:43], 0, v[184:185]
	s_add_i32 m0, s44, 0x2000
	s_nop 0
	global_load_lds_dwordx4 v[206:207], off
	v_lshl_add_u64 v[206:207], v[216:217], 0, s[14:15]
	s_mov_b32 m0, s48
	s_nop 0
	global_load_lds_dwordx4 v[206:207], off
	v_lshl_add_u64 v[206:207], v[218:219], 0, s[14:15]
	s_mov_b32 m0, s49
	s_nop 0
	global_load_lds_dwordx4 v[206:207], off
	s_waitcnt vmcnt(8)
	s_waitcnt lgkmcnt(0)
	s_barrier
	s_waitcnt lgkmcnt(0)
	v_mfma_f32_16x16x32_bf16 v[84:87], v[56:59], v[160:163], v[84:87]
	v_mfma_f32_16x16x32_bf16 v[80:83], v[64:67], v[160:163], v[80:83]
	v_mfma_f32_16x16x32_bf16 v[44:47], v[56:59], v[168:171], v[44:47]
	v_mfma_f32_16x16x32_bf16 v[40:43], v[64:67], v[168:171], v[40:43]
	v_mfma_f32_16x16x32_bf16 v[28:31], v[56:59], v[190:193], v[28:31]
	v_mfma_f32_16x16x32_bf16 v[24:27], v[64:67], v[190:193], v[24:27]
	v_mfma_f32_16x16x32_bf16 v[12:15], v[56:59], v[198:201], v[12:15]
	v_mfma_f32_16x16x32_bf16 v[8:11], v[64:67], v[198:201], v[8:11]
	v_mfma_f32_16x16x32_bf16 v[84:87], v[60:63], v[164:167], v[84:87]
	v_mfma_f32_16x16x32_bf16 v[80:83], v[68:71], v[164:167], v[80:83]
	v_mfma_f32_16x16x32_bf16 v[44:47], v[60:63], v[172:175], v[44:47]
	v_mfma_f32_16x16x32_bf16 v[40:43], v[68:71], v[172:175], v[40:43]
	v_mfma_f32_16x16x32_bf16 v[28:31], v[60:63], v[194:197], v[28:31]
	v_mfma_f32_16x16x32_bf16 v[24:27], v[68:71], v[194:197], v[24:27]
	v_mfma_f32_16x16x32_bf16 v[12:15], v[60:63], v[202:205], v[12:15]
	v_mfma_f32_16x16x32_bf16 v[8:11], v[68:71], v[202:205], v[8:11]
	v_mfma_f32_16x16x32_bf16 v[52:55], v[72:75], v[160:163], v[52:55]
	v_mfma_f32_16x16x32_bf16 v[48:51], v[88:91], v[160:163], v[48:51]
	v_mfma_f32_16x16x32_bf16 v[36:39], v[72:75], v[168:171], v[36:39]
	v_mfma_f32_16x16x32_bf16 v[32:35], v[88:91], v[168:171], v[32:35]
	v_mfma_f32_16x16x32_bf16 v[20:23], v[72:75], v[190:193], v[20:23]
	v_mfma_f32_16x16x32_bf16 v[16:19], v[88:91], v[190:193], v[16:19]
	v_mfma_f32_16x16x32_bf16 v[4:7], v[72:75], v[198:201], v[4:7]
	v_mfma_f32_16x16x32_bf16 v[0:3], v[88:91], v[198:201], v[0:3]
	v_mfma_f32_16x16x32_bf16 v[60:63], v[76:79], v[164:167], v[52:55]
	v_mfma_f32_16x16x32_bf16 v[48:51], v[92:95], v[164:167], v[48:51]
	v_mfma_f32_16x16x32_bf16 v[36:39], v[76:79], v[172:175], v[36:39]
	v_mfma_f32_16x16x32_bf16 v[32:35], v[92:95], v[172:175], v[32:35]
	v_mfma_f32_16x16x32_bf16 v[20:23], v[76:79], v[194:197], v[20:23]
	v_mfma_f32_16x16x32_bf16 v[16:19], v[92:95], v[194:197], v[16:19]
	v_mfma_f32_16x16x32_bf16 v[4:7], v[76:79], v[202:205], v[4:7]
	v_mfma_f32_16x16x32_bf16 v[0:3], v[92:95], v[202:205], v[0:3]
	s_barrier
	s_add_i32 s61, s61, 2
	s_add_u32 s36, s36, 0x100
	s_addc_u32 s37, s37, 0
	s_add_u32 s1, s1, 0x100
	s_addc_u32 s25, s25, 0
	s_cmp_gt_u32 s61, 29
	s_cbranch_scc0 .LBB0_945
	s_and_b64 vcc, exec, s[16:17]
	s_cbranch_vccz .LBB0_948
	s_barrier

; #define PG8_STAGE(bufoff, gbase, voff) do { _Pragma("unroll") for (int _i = 0; _i < 2; ++_i) \
;         __builtin_amdgcn_global_load_lds((const unsigned*)((const char*)(gbase) + (voff)[_i]), (LAS unsigned*)(lds + (bufoff) + ldsw + _i * 8192), 16, 0, 0); } while (0)
; #define PG8_LDA(dst, b, h) do { _Pragma("unroll") for (int m = 0; m < 4; ++m) _Pragma("unroll") for (int k = 0; k < 2; ++k) dst[m][k] = *(const LAS bf16x8*)(lds + PG8_SA(b, h) + aoff + m * 2048 + k * 1024); } while (0)
; #define PG8_LDB(dst, b, h) do { _Pragma("unroll") for (int n = 0; n < 2; ++n) _Pragma("unroll") for (int k = 0; k < 2; ++k) dst[n][k] = *(const LAS bf16x8*)(lds + PG8_SB(b, h) + boff + n * 2048 + k * 1024); } while (0)
; #define PG8_MMA(ai, bj, At, Bt) do { __builtin_amdgcn_s_setprio(1); _Pragma("unroll") for (int m = 0; m < 4; ++m) _Pragma("unroll") for (int n = 0; n < 2; ++n) _Pragma("unroll") for (int k = 0; k < 2; ++k) \
;         acc[ai][bj][m][n] = __builtin_amdgcn_mfma_f32_16x16x32_bf16(Bt[n][k], At[m][k], acc[ai][bj][m][n], 0, 0, 0); __builtin_amdgcn_s_setprio(0); } while (0)
; #define PG8_WAIT_V(n) asm volatile("s_waitcnt vmcnt(" #n ")" ::: "memory")
; #define PG8_WAIT_L(n) asm volatile("s_waitcnt lgkmcnt(" #n ")" ::: "memory")
; #define PG8_BAR __builtin_amdgcn_s_barrier()
; #define PG8_SCHED __builtin_amdgcn_sched_barrier(0)
; template <class Sched, class Epi, bool ALIGN_EPI, bool SP2>
; __device__ __forceinline__ void gemm_phase(LAS unsigned char* lds, const int K, const int lda, const int ldb, const Sched& S, const Epi& E) {
;     ...
;             const bool last = (t == nt - 2);
;             const char* a1 = cA + (size_t)(t + 1) * kstep;
;             const char* a2 = last ? nA : cA + (size_t)(t + 2) * kstep; const char* b2 = last ? nB : cB + (size_t)(t + 2) * kstep;
;             const char* a3 = a2 + kstep; const char* b3 = b2 + kstep;
;             if constexpr (SP2) {
;             PG8_LDB(B0, 0, 0); PG8_LDB(B1, 0, 1); PG8_SCHED; PG8_LDA(At, 0, 0); PG8_STAGE(PG8_SA(1, 1), a1 + hstepA, voffA);
;             PG8_WAIT_V(8); PG8_WAIT_L(0); PG8_BAR; PG8_MMA(0, 0, At, B0); PG8_MMA(0, 1, At, B1); PG8_BAR; PG8_SCHED;
;             PG8_LDA(At, 0, 1); PG8_STAGE(PG8_SB(0, 0), b2, voffB); PG8_STAGE(PG8_SB(0, 1), b2 + hstepB, voffB); PG8_STAGE(PG8_SA(0, 0), a2, voffA);
.LBB0_1037:
	ds_read_b128 v[64:67], v183
	ds_read_b128 v[68:71], v183 offset:1024
	ds_read_b128 v[72:75], v183 offset:2048
	ds_read_b128 v[76:79], v183 offset:3072
	ds_read_b128 v[144:147], v184
	ds_read_b128 v[160:163], v184 offset:1024
	ds_read_b128 v[164:167], v184 offset:2048
	ds_read_b128 v[168:171], v184 offset:3072
	s_add_u32 s42, s36, 0xfff80080
	s_addc_u32 s43, s37, -1
	s_cmp_eq_u32 s57, 28
	s_cselect_b32 s45, s27, s43
	s_cselect_b32 s44, s26, s42
	s_cselect_b32 s43, s29, s56
	s_cselect_b32 s42, s28, s25
	v_lshl_add_u64 v[216:217], s[36:37], 0, v[156:157]
	s_add_i32 m0, s33, 0xc000
	ds_read_b128 v[172:175], v185
	ds_read_b128 v[188:191], v185 offset:1024
	ds_read_b128 v[192:195], v185 offset:2048
	ds_read_b128 v[196:199], v185 offset:3072
	ds_read_b128 v[200:203], v185 offset:4096
	ds_read_b128 v[204:207], v185 offset:5120
	ds_read_b128 v[208:211], v185 offset:6144
	ds_read_b128 v[212:215], v185 offset:7168
	global_load_lds_dwordx4 v[216:217], off
	v_lshl_add_u64 v[216:217], s[36:37], 0, v[158:159]
	s_add_i32 m0, s33, 0xe000
	s_nop 0
	global_load_lds_dwordx4 v[216:217], off
	s_waitcnt vmcnt(8)
	s_waitcnt lgkmcnt(0)
	s_barrier
	s_waitcnt lgkmcnt(0)
	v_mfma_f32_16x16x32_bf16 v[140:143], v[64:67], v[172:175], v[140:143]
	v_mfma_f32_16x16x32_bf16 v[136:139], v[72:75], v[172:175], v[136:139]
	v_mfma_f32_16x16x32_bf16 v[124:127], v[64:67], v[192:195], v[124:127]
	v_mfma_f32_16x16x32_bf16 v[120:123], v[72:75], v[192:195], v[120:123]
	v_mfma_f32_16x16x32_bf16 v[108:111], v[64:67], v[200:203], v[108:111]
	v_mfma_f32_16x16x32_bf16 v[104:107], v[72:75], v[200:203], v[104:107]
	v_mfma_f32_16x16x32_bf16 v[92:95], v[64:67], v[208:211], v[92:95]
	v_mfma_f32_16x16x32_bf16 v[88:91], v[72:75], v[208:211], v[88:91]
	v_mfma_f32_16x16x32_bf16 v[140:143], v[68:71], v[188:191], v[140:143]
	v_mfma_f32_16x16x32_bf16 v[136:139], v[76:79], v[188:191], v[136:139]
	v_mfma_f32_16x16x32_bf16 v[124:127], v[68:71], v[196:199], v[124:127]
	v_mfma_f32_16x16x32_bf16 v[120:123], v[76:79], v[196:199], v[120:123]
	v_mfma_f32_16x16x32_bf16 v[108:111], v[68:71], v[204:207], v[108:111]
	v_mfma_f32_16x16x32_bf16 v[104:107], v[76:79], v[204:207], v[104:107]
	v_mfma_f32_16x16x32_bf16 v[92:95], v[68:71], v[212:215], v[92:95]
	v_mfma_f32_16x16x32_bf16 v[88:91], v[76:79], v[212:215], v[88:91]
	v_mfma_f32_16x16x32_bf16 v[132:135], v[144:147], v[172:175], v[132:135]
	v_mfma_f32_16x16x32_bf16 v[128:131], v[164:167], v[172:175], v[128:131]
	v_mfma_f32_16x16x32_bf16 v[116:119], v[144:147], v[192:195], v[116:119]
	v_mfma_f32_16x16x32_bf16 v[112:115], v[164:167], v[192:195], v[112:115]
	v_mfma_f32_16x16x32_bf16 v[100:103], v[144:147], v[200:203], v[100:103]
	v_mfma_f32_16x16x32_bf16 v[96:99], v[164:167], v[200:203], v[96:99]
	v_mfma_f32_16x16x32_bf16 v[84:87], v[144:147], v[208:211], v[84:87]
	v_mfma_f32_16x16x32_bf16 v[80:83], v[164:167], v[208:211], v[80:83]
	v_mfma_f32_16x16x32_bf16 v[132:135], v[160:163], v[188:191], v[132:135]
	v_mfma_f32_16x16x32_bf16 v[128:131], v[168:171], v[188:191], v[128:131]
	v_mfma_f32_16x16x32_bf16 v[116:119], v[160:163], v[196:199], v[116:119]
	v_mfma_f32_16x16x32_bf16 v[112:115], v[168:171], v[196:199], v[112:115]
	v_mfma_f32_16x16x32_bf16 v[100:103], v[160:163], v[204:207], v[100:103]
	v_mfma_f32_16x16x32_bf16 v[96:99], v[168:171], v[204:207], v[96:99]
	v_mfma_f32_16x16x32_bf16 v[84:87], v[160:163], v[212:215], v[84:87]
	v_mfma_f32_16x16x32_bf16 v[80:83], v[168:171], v[212:215], v[80:83]
	s_barrier
	s_add_i32 s58, s51, s21
	v_lshl_add_u64 v[216:217], s[42:43], 0, v[150:151]
	s_mov_b32 m0, s58
	ds_read_b128 v[172:175], v185 offset:16384
	ds_read_b128 v[188:191], v185 offset:17408
	ds_read_b128 v[192:195], v185 offset:18432
	ds_read_b128 v[196:199], v185 offset:19456
	ds_read_b128 v[200:203], v185 offset:20480
	ds_read_b128 v[204:207], v185 offset:21504
	ds_read_b128 v[208:211], v185 offset:22528
	ds_read_b128 v[212:215], v185 offset:23552
	global_load_lds_dwordx4 v[216:217], off
	s_add_i32 m0, s58, 0x2000
	s_add_u32 s58, s42, 0x80000
	v_lshl_add_u64 v[218:219], s[42:43], 0, v[154:155]
	s_addc_u32 s59, s43, 0
	s_add_i32 s60, s52, s21
	global_load_lds_dwordx4 v[218:219], off
	v_lshl_add_u64 v[220:221], s[58:59], 0, v[150:151]
	s_mov_b32 m0, s60
	v_lshl_add_u64 v[222:223], s[44:45], 0, v[152:153]
	global_load_lds_dwordx4 v[220:221], off
	v_lshl_add_u64 v[220:221], s[58:59], 0, v[154:155]
	s_add_i32 m0, s60, 0x2000
	s_nop 0
	global_load_lds_dwordx4 v[220:221], off
	v_lshl_add_u64 v[220:221], s[44:45], 0, v[148:149]
	s_mov_b32 m0, s33
	s_nop 0
	global_load_lds_dwordx4 v[220:221], off
	s_mov_b32 m0, s35
	s_nop 0
	global_load_lds_dwordx4 v[222:223], off
	s_waitcnt vmcnt(8)
	s_waitcnt lgkmcnt(0)
	s_barrier
; #define PG8_STAGE(bufoff, gbase, voff) do { _Pragma("unroll") for (int _i = 0; _i < 2; ++_i) \
;         __builtin_amdgcn_global_load_lds((const unsigned*)((const char*)(gbase) + (voff)[_i]), (LAS unsigned*)(lds + (bufoff) + ldsw + _i * 8192), 16, 0, 0); } while (0)
; #define PG8_LDA(dst, b, h) do { _Pragma("unroll") for (int m = 0; m < 4; ++m) _Pragma("unroll") for (int k = 0; k < 2; ++k) dst[m][k] = *(const LAS bf16x8*)(lds + PG8_SA(b, h) + aoff + m * 2048 + k * 1024); } while (0)
; #define PG8_LDB(dst, b, h) do { _Pragma("unroll") for (int n = 0; n < 2; ++n) _Pragma("unroll") for (int k = 0; k < 2; ++k) dst[n][k] = *(const LAS bf16x8*)(lds + PG8_SB(b, h) + boff + n * 2048 + k * 1024); } while (0)
; #define PG8_MMA(ai, bj, At, Bt) do { __builtin_amdgcn_s_setprio(1); _Pragma("unroll") for (int m = 0; m < 4; ++m) _Pragma("unroll") for (int n = 0; n < 2; ++n) _Pragma("unroll") for (int k = 0; k < 2; ++k) \
;         acc[ai][bj][m][n] = __builtin_amdgcn_mfma_f32_16x16x32_bf16(Bt[n][k], At[m][k], acc[ai][bj][m][n], 0, 0, 0); __builtin_amdgcn_s_setprio(0); } while (0)
; #define PG8_WAIT_V(n) asm volatile("s_waitcnt vmcnt(" #n ")" ::: "memory")
; #define PG8_WAIT_L(n) asm volatile("s_waitcnt lgkmcnt(" #n ")" ::: "memory")
; #define PG8_BAR __builtin_amdgcn_s_barrier()
; #define PG8_SCHED __builtin_amdgcn_sched_barrier(0)
; template <class Sched, class Epi, bool ALIGN_EPI, bool SP2>
; __device__ __forceinline__ void gemm_phase(LAS unsigned char* lds, const int K, const int lda, const int ldb, const Sched& S, const Epi& E) {
;     ...
;             PG8_WAIT_V(8); PG8_WAIT_L(0); PG8_BAR; PG8_MMA(1, 0, At, B0); PG8_MMA(1, 1, At, B1); PG8_BAR; PG8_SCHED;
;             PG8_LDB(B0, 1, 0); PG8_LDB(B1, 1, 1); PG8_SCHED; PG8_LDA(At, 1, 0); PG8_STAGE(PG8_SA(0, 1), a2 + hstepA, voffA);
;             PG8_WAIT_V(8); PG8_WAIT_L(0); PG8_BAR; PG8_MMA(0, 0, At, B0); PG8_MMA(0, 1, At, B1); PG8_BAR; PG8_SCHED;
	s_waitcnt lgkmcnt(0)
	v_mfma_f32_16x16x32_bf16 v[60:63], v[64:67], v[172:175], v[60:63]
	v_mfma_f32_16x16x32_bf16 v[56:59], v[72:75], v[172:175], v[56:59]
	v_mfma_f32_16x16x32_bf16 v[44:47], v[64:67], v[192:195], v[44:47]
	v_mfma_f32_16x16x32_bf16 v[40:43], v[72:75], v[192:195], v[40:43]
	v_mfma_f32_16x16x32_bf16 v[24:27], v[64:67], v[200:203], v[24:27]
	v_mfma_f32_16x16x32_bf16 v[20:23], v[72:75], v[200:203], v[20:23]
	v_mfma_f32_16x16x32_bf16 v[8:11], v[64:67], v[208:211], v[8:11]
	v_mfma_f32_16x16x32_bf16 v[0:3], v[72:75], v[208:211], v[0:3]
	v_mfma_f32_16x16x32_bf16 v[60:63], v[68:71], v[188:191], v[60:63]
	v_mfma_f32_16x16x32_bf16 v[56:59], v[76:79], v[188:191], v[56:59]
	v_mfma_f32_16x16x32_bf16 v[44:47], v[68:71], v[196:199], v[44:47]
	v_mfma_f32_16x16x32_bf16 v[40:43], v[76:79], v[196:199], v[40:43]
	v_mfma_f32_16x16x32_bf16 v[24:27], v[68:71], v[204:207], v[24:27]
	v_mfma_f32_16x16x32_bf16 v[20:23], v[76:79], v[204:207], v[20:23]
	v_mfma_f32_16x16x32_bf16 v[8:11], v[68:71], v[212:215], v[8:11]
	v_mfma_f32_16x16x32_bf16 v[0:3], v[76:79], v[212:215], v[0:3]
	v_mfma_f32_16x16x32_bf16 v[52:55], v[144:147], v[172:175], v[52:55]
	v_mfma_f32_16x16x32_bf16 v[48:51], v[164:167], v[172:175], v[48:51]
	v_mfma_f32_16x16x32_bf16 v[36:39], v[144:147], v[192:195], v[36:39]
	v_mfma_f32_16x16x32_bf16 v[32:35], v[164:167], v[192:195], v[32:35]
	v_mfma_f32_16x16x32_bf16 v[28:31], v[144:147], v[200:203], v[28:31]
	v_mfma_f32_16x16x32_bf16 v[16:19], v[164:167], v[200:203], v[16:19]
	v_mfma_f32_16x16x32_bf16 v[12:15], v[144:147], v[208:211], v[12:15]
	v_mfma_f32_16x16x32_bf16 v[4:7], v[164:167], v[208:211], v[4:7]
	v_mfma_f32_16x16x32_bf16 v[52:55], v[160:163], v[188:191], v[52:55]
	v_mfma_f32_16x16x32_bf16 v[48:51], v[168:171], v[188:191], v[48:51]
	v_mfma_f32_16x16x32_bf16 v[36:39], v[160:163], v[196:199], v[36:39]
	v_mfma_f32_16x16x32_bf16 v[32:35], v[168:171], v[196:199], v[32:35]
	v_mfma_f32_16x16x32_bf16 v[28:31], v[160:163], v[204:207], v[28:31]
	v_mfma_f32_16x16x32_bf16 v[16:19], v[168:171], v[204:207], v[16:19]
	v_mfma_f32_16x16x32_bf16 v[12:15], v[160:163], v[212:215], v[12:15]
	v_mfma_f32_16x16x32_bf16 v[4:7], v[168:171], v[212:215], v[4:7]
	s_barrier
	s_add_i32 s58, 0, 0x18000
	s_add_i32 s59, 0, 0x1c000
	v_add_u32_e32 v76, s58, v181
	v_add_u32_e32 v168, s59, v181
	ds_read_b128 v[64:67], v76
	ds_read_b128 v[68:71], v76 offset:1024
	ds_read_b128 v[72:75], v76 offset:2048
	ds_read_b128 v[76:79], v76 offset:3072
	ds_read_b128 v[144:147], v168
	ds_read_b128 v[160:163], v168 offset:1024
	ds_read_b128 v[164:167], v168 offset:2048
	ds_read_b128 v[168:171], v168 offset:3072
	s_add_u32 s44, s44, 0x80000
	s_addc_u32 s45, s45, 0
	s_mov_b32 m0, s46
	v_lshl_add_u64 v[224:225], s[44:45], 0, v[148:149]
	ds_read_b128 v[172:175], v185 offset:32768
	ds_read_b128 v[188:191], v185 offset:33792
	ds_read_b128 v[192:195], v185 offset:34816
	ds_read_b128 v[196:199], v185 offset:35840
	ds_read_b128 v[200:203], v185 offset:36864
	ds_read_b128 v[204:207], v185 offset:37888
	ds_read_b128 v[208:211], v185 offset:38912
	ds_read_b128 v[212:215], v185 offset:39936
	global_load_lds_dwordx4 v[224:225], off
	v_lshl_add_u64 v[224:225], s[44:45], 0, v[152:153]
	s_mov_b32 m0, s47
	s_nop 0
	global_load_lds_dwordx4 v[224:225], off
	s_waitcnt vmcnt(8)
	s_waitcnt lgkmcnt(0)
	s_barrier
	s_waitcnt lgkmcnt(0)
	v_mfma_f32_16x16x32_bf16 v[140:143], v[64:67], v[172:175], v[140:143]
	v_mfma_f32_16x16x32_bf16 v[136:139], v[72:75], v[172:175], v[136:139]
	v_mfma_f32_16x16x32_bf16 v[124:127], v[64:67], v[192:195], v[124:127]
	v_mfma_f32_16x16x32_bf16 v[120:123], v[72:75], v[192:195], v[120:123]
	v_mfma_f32_16x16x32_bf16 v[108:111], v[64:67], v[200:203], v[108:111]
	v_mfma_f32_16x16x32_bf16 v[104:107], v[72:75], v[200:203], v[104:107]
	v_mfma_f32_16x16x32_bf16 v[92:95], v[64:67], v[208:211], v[92:95]
	v_mfma_f32_16x16x32_bf16 v[88:91], v[72:75], v[208:211], v[88:91]
	v_mfma_f32_16x16x32_bf16 v[140:143], v[68:71], v[188:191], v[140:143]
	v_mfma_f32_16x16x32_bf16 v[136:139], v[76:79], v[188:191], v[136:139]
	v_mfma_f32_16x16x32_bf16 v[124:127], v[68:71], v[196:199], v[124:127]
	v_mfma_f32_16x16x32_bf16 v[120:123], v[76:79], v[196:199], v[120:123]
	v_mfma_f32_16x16x32_bf16 v[108:111], v[68:71], v[204:207], v[108:111]
	v_mfma_f32_16x16x32_bf16 v[104:107], v[76:79], v[204:207], v[104:107]
	v_mfma_f32_16x16x32_bf16 v[92:95], v[68:71], v[212:215], v[92:95]
	v_mfma_f32_16x16x32_bf16 v[88:91], v[76:79], v[212:215], v[88:91]
	v_mfma_f32_16x16x32_bf16 v[132:135], v[144:147], v[172:175], v[132:135]
	v_mfma_f32_16x16x32_bf16 v[128:131], v[164:167], v[172:175], v[128:131]
	v_mfma_f32_16x16x32_bf16 v[116:119], v[144:147], v[192:195], v[116:119]
	v_mfma_f32_16x16x32_bf16 v[112:115], v[164:167], v[192:195], v[112:115]
	v_mfma_f32_16x16x32_bf16 v[100:103], v[144:147], v[200:203], v[100:103]
	v_mfma_f32_16x16x32_bf16 v[96:99], v[164:167], v[200:203], v[96:99]
	v_mfma_f32_16x16x32_bf16 v[84:87], v[144:147], v[208:211], v[84:87]
	v_mfma_f32_16x16x32_bf16 v[80:83], v[164:167], v[208:211], v[80:83]
	v_mfma_f32_16x16x32_bf16 v[132:135], v[160:163], v[188:191], v[132:135]
	v_mfma_f32_16x16x32_bf16 v[128:131], v[168:171], v[188:191], v[128:131]
	v_mfma_f32_16x16x32_bf16 v[116:119], v[160:163], v[196:199], v[116:119]
	v_mfma_f32_16x16x32_bf16 v[112:115], v[168:171], v[196:199], v[112:115]
	v_mfma_f32_16x16x32_bf16 v[100:103], v[160:163], v[204:207], v[100:103]
	v_mfma_f32_16x16x32_bf16 v[96:99], v[168:171], v[204:207], v[96:99]
	v_mfma_f32_16x16x32_bf16 v[84:87], v[160:163], v[212:215], v[84:87]
	v_mfma_f32_16x16x32_bf16 v[80:83], v[168:171], v[212:215], v[80:83]
	s_barrier
; #define PG8_STAGE(bufoff, gbase, voff) do { _Pragma("unroll") for (int _i = 0; _i < 2; ++_i) \
;         __builtin_amdgcn_global_load_lds((const unsigned*)((const char*)(gbase) + (voff)[_i]), (LAS unsigned*)(lds + (bufoff) + ldsw + _i * 8192), 16, 0, 0); } while (0)
; #define PG8_LDA(dst, b, h) do { _Pragma("unroll") for (int m = 0; m < 4; ++m) _Pragma("unroll") for (int k = 0; k < 2; ++k) dst[m][k] = *(const LAS bf16x8*)(lds + PG8_SA(b, h) + aoff + m * 2048 + k * 1024); } while (0)
; #define PG8_MMA(ai, bj, At, Bt) do { __builtin_amdgcn_s_setprio(1); _Pragma("unroll") for (int m = 0; m < 4; ++m) _Pragma("unroll") for (int n = 0; n < 2; ++n) _Pragma("unroll") for (int k = 0; k < 2; ++k) \
;         acc[ai][bj][m][n] = __builtin_amdgcn_mfma_f32_16x16x32_bf16(Bt[n][k], At[m][k], acc[ai][bj][m][n], 0, 0, 0); __builtin_amdgcn_s_setprio(0); } while (0)
; #define PG8_WAIT_V(n) asm volatile("s_waitcnt vmcnt(" #n ")" ::: "memory")
; #define PG8_WAIT_L(n) asm volatile("s_waitcnt lgkmcnt(" #n ")" ::: "memory")
; #define PG8_BAR __builtin_amdgcn_s_barrier()
; #define PG8_SCHED __builtin_amdgcn_sched_barrier(0)
; template <class Sched, class Epi, bool ALIGN_EPI, bool SP2>
; __device__ __forceinline__ void gemm_phase(LAS unsigned char* lds, const int K, const int lda, const int ldb, const Sched& S, const Epi& E) {
;     ...
;             PG8_LDA(At, 1, 1); PG8_STAGE(PG8_SB(1, 0), b3, voffB); PG8_STAGE(PG8_SB(1, 1), b3 + hstepB, voffB); PG8_STAGE(PG8_SA(1, 0), a3, voffA);
;             PG8_WAIT_V(8); PG8_WAIT_L(0); PG8_BAR; PG8_MMA(1, 0, At, B0); PG8_MMA(1, 1, At, B1); PG8_BAR; PG8_SCHED;
;     ...
;         }
;         if constexpr (ALIGN_EPI) { if (wr == 0) PG8_BAR; }
	s_add_i32 s44, s58, s21
	v_lshl_add_u64 v[216:217], v[216:217], 0, s[14:15]
	s_mov_b32 m0, s44
	ds_read_b128 v[172:175], v185 offset:49152
	ds_read_b128 v[188:191], v185 offset:50176
	ds_read_b128 v[192:195], v185 offset:51200
	ds_read_b128 v[196:199], v185 offset:52224
	ds_read_b128 v[200:203], v185 offset:53248
	ds_read_b128 v[204:207], v185 offset:54272
	ds_read_b128 v[208:211], v185 offset:55296
	ds_read_b128 v[212:215], v185 offset:56320
	global_load_lds_dwordx4 v[216:217], off
	s_add_i32 m0, s44, 0x2000
	s_add_u32 s42, s42, 0x80080
	v_lshl_add_u64 v[216:217], v[218:219], 0, s[14:15]
	s_addc_u32 s43, s43, 0
	s_add_i32 s44, s59, s21
	global_load_lds_dwordx4 v[216:217], off
	v_lshl_add_u64 v[216:217], s[42:43], 0, v[150:151]
	s_mov_b32 m0, s44
	s_nop 0
	global_load_lds_dwordx4 v[216:217], off
	v_lshl_add_u64 v[216:217], s[42:43], 0, v[154:155]
	s_add_i32 m0, s44, 0x2000
	s_nop 0
	global_load_lds_dwordx4 v[216:217], off
	v_lshl_add_u64 v[216:217], v[220:221], 0, s[14:15]
	s_mov_b32 m0, s49
	s_nop 0
	global_load_lds_dwordx4 v[216:217], off
	v_lshl_add_u64 v[216:217], v[222:223], 0, s[14:15]
	s_mov_b32 m0, s50
	s_nop 0
	global_load_lds_dwordx4 v[216:217], off
	s_waitcnt vmcnt(8)
	s_waitcnt lgkmcnt(0)
	s_barrier
	s_waitcnt lgkmcnt(0)
	v_mfma_f32_16x16x32_bf16 v[60:63], v[64:67], v[172:175], v[60:63]
	v_mfma_f32_16x16x32_bf16 v[56:59], v[72:75], v[172:175], v[56:59]
	v_mfma_f32_16x16x32_bf16 v[44:47], v[64:67], v[192:195], v[44:47]
	v_mfma_f32_16x16x32_bf16 v[40:43], v[72:75], v[192:195], v[40:43]
	v_mfma_f32_16x16x32_bf16 v[24:27], v[64:67], v[200:203], v[24:27]
	v_mfma_f32_16x16x32_bf16 v[20:23], v[72:75], v[200:203], v[20:23]
	v_mfma_f32_16x16x32_bf16 v[8:11], v[64:67], v[208:211], v[8:11]
	v_mfma_f32_16x16x32_bf16 v[0:3], v[72:75], v[208:211], v[0:3]
	v_mfma_f32_16x16x32_bf16 v[60:63], v[68:71], v[188:191], v[60:63]
	v_mfma_f32_16x16x32_bf16 v[56:59], v[76:79], v[188:191], v[56:59]
	v_mfma_f32_16x16x32_bf16 v[44:47], v[68:71], v[196:199], v[44:47]
	v_mfma_f32_16x16x32_bf16 v[40:43], v[76:79], v[196:199], v[40:43]
	v_mfma_f32_16x16x32_bf16 v[24:27], v[68:71], v[204:207], v[24:27]
	v_mfma_f32_16x16x32_bf16 v[20:23], v[76:79], v[204:207], v[20:23]
	v_mfma_f32_16x16x32_bf16 v[8:11], v[68:71], v[212:215], v[8:11]
	v_mfma_f32_16x16x32_bf16 v[0:3], v[76:79], v[212:215], v[0:3]
	v_mfma_f32_16x16x32_bf16 v[52:55], v[144:147], v[172:175], v[52:55]
	v_mfma_f32_16x16x32_bf16 v[48:51], v[164:167], v[172:175], v[48:51]
	v_mfma_f32_16x16x32_bf16 v[36:39], v[144:147], v[192:195], v[36:39]
	v_mfma_f32_16x16x32_bf16 v[32:35], v[164:167], v[192:195], v[32:35]
	v_mfma_f32_16x16x32_bf16 v[28:31], v[144:147], v[200:203], v[28:31]
	v_mfma_f32_16x16x32_bf16 v[16:19], v[164:167], v[200:203], v[16:19]
	v_mfma_f32_16x16x32_bf16 v[12:15], v[144:147], v[208:211], v[12:15]
	v_mfma_f32_16x16x32_bf16 v[4:7], v[164:167], v[208:211], v[4:7]
	v_mfma_f32_16x16x32_bf16 v[52:55], v[160:163], v[188:191], v[52:55]
	v_mfma_f32_16x16x32_bf16 v[48:51], v[168:171], v[188:191], v[48:51]
	v_mfma_f32_16x16x32_bf16 v[36:39], v[160:163], v[196:199], v[36:39]
	v_mfma_f32_16x16x32_bf16 v[32:35], v[168:171], v[196:199], v[32:35]
	v_mfma_f32_16x16x32_bf16 v[28:31], v[160:163], v[204:207], v[28:31]
	v_mfma_f32_16x16x32_bf16 v[16:19], v[168:171], v[204:207], v[16:19]
	v_mfma_f32_16x16x32_bf16 v[12:15], v[160:163], v[212:215], v[12:15]
	v_mfma_f32_16x16x32_bf16 v[4:7], v[168:171], v[212:215], v[4:7]
	s_barrier
	s_add_i32 s57, s57, 2
	s_add_u32 s36, s36, 0x100
	s_addc_u32 s37, s37, 0
	s_add_u32 s25, s25, 0x100
	s_addc_u32 s56, s56, 0
	s_cmp_gt_u32 s57, 29
	s_cbranch_scc0 .LBB0_1037
	s_and_b64 vcc, exec, s[16:17]
	s_mov_b32 s56, s62
	s_cbranch_vccz .LBB0_1040
	s_barrier

; #define PG8_STAGE(bufoff, gbase, voff) do { _Pragma("unroll") for (int _i = 0; _i < 2; ++_i) \
;         __builtin_amdgcn_global_load_lds((const unsigned*)((const char*)(gbase) + (voff)[_i]), (LAS unsigned*)(lds + (bufoff) + ldsw + _i * 8192), 16, 0, 0); } while (0)
; #define PG8_LDA(dst, b, h) do { _Pragma("unroll") for (int m = 0; m < 4; ++m) _Pragma("unroll") for (int k = 0; k < 2; ++k) dst[m][k] = *(const LAS bf16x8*)(lds + PG8_SA(b, h) + aoff + m * 2048 + k * 1024); } while (0)
; #define PG8_LDB(dst, b, h) do { _Pragma("unroll") for (int n = 0; n < 2; ++n) _Pragma("unroll") for (int k = 0; k < 2; ++k) dst[n][k] = *(const LAS bf16x8*)(lds + PG8_SB(b, h) + boff + n * 2048 + k * 1024); } while (0)
; #define PG8_MMA(ai, bj, At, Bt) do { __builtin_amdgcn_s_setprio(1); _Pragma("unroll") for (int m = 0; m < 4; ++m) _Pragma("unroll") for (int n = 0; n < 2; ++n) _Pragma("unroll") for (int k = 0; k < 2; ++k) \
;         acc[ai][bj][m][n] = __builtin_amdgcn_mfma_f32_16x16x32_bf16(Bt[n][k], At[m][k], acc[ai][bj][m][n], 0, 0, 0); __builtin_amdgcn_s_setprio(0); } while (0)
; #define PG8_WAIT_V(n) asm volatile("s_waitcnt vmcnt(" #n ")" ::: "memory")
; #define PG8_WAIT_L(n) asm volatile("s_waitcnt lgkmcnt(" #n ")" ::: "memory")
; #define PG8_BAR __builtin_amdgcn_s_barrier()
; #define PG8_SCHED __builtin_amdgcn_sched_barrier(0)
; template <class Sched, class Epi, bool ALIGN_EPI, bool SP2>
; __device__ __forceinline__ void gemm_phase(LAS unsigned char* lds, const int K, const int lda, const int ldb, const Sched& S, const Epi& E) {
;     ...
;             const bool last = (t == nt - 2);
;             const char* a1 = cA + (size_t)(t + 1) * kstep;
;             const char* a2 = last ? nA : cA + (size_t)(t + 2) * kstep; const char* b2 = last ? nB : cB + (size_t)(t + 2) * kstep;
;             const char* a3 = a2 + kstep; const char* b3 = b2 + kstep;
;             if constexpr (SP2) {
;             PG8_LDB(B0, 0, 0); PG8_LDB(B1, 0, 1); PG8_SCHED; PG8_LDA(At, 0, 0); PG8_STAGE(PG8_SA(1, 1), a1 + hstepA, voffA);
;             PG8_WAIT_V(8); PG8_WAIT_L(0); PG8_BAR; PG8_MMA(0, 0, At, B0); PG8_MMA(0, 1, At, B1); PG8_BAR; PG8_SCHED;
;             PG8_LDA(At, 0, 1); PG8_STAGE(PG8_SB(0, 0), b2, voffB); PG8_STAGE(PG8_SB(0, 1), b2 + hstepB, voffB); PG8_STAGE(PG8_SA(0, 0), a2, voffA);
.LBB0_1120:
	ds_read_b128 v[96:99], v178
	ds_read_b128 v[100:103], v178 offset:1024
	ds_read_b128 v[104:107], v178 offset:2048
	ds_read_b128 v[108:111], v178 offset:3072
	ds_read_b128 v[112:115], v180
	ds_read_b128 v[116:119], v180 offset:1024
	ds_read_b128 v[120:123], v180 offset:2048
	ds_read_b128 v[124:127], v180 offset:3072
	s_add_u32 s4, s0, 0x100
	s_addc_u32 s5, s1, 0
	s_cmpk_eq_i32 s51, 0x54
	s_cselect_b32 s27, s21, s5
	s_cselect_b32 s26, s20, s4
	s_cselect_b32 s25, s23, s50
	s_cselect_b32 s24, s22, s49
	v_lshl_add_u64 v[172:173], s[0:1], 0, v[164:165]
	s_add_i32 m0, s17, 0xc000
	ds_read_b128 v[168:171], v181
	ds_read_b128 v[184:187], v181 offset:1024
	ds_read_b128 v[188:191], v181 offset:2048
	ds_read_b128 v[192:195], v181 offset:3072
	ds_read_b128 v[196:199], v181 offset:4096
	ds_read_b128 v[200:203], v181 offset:5120
	ds_read_b128 v[204:207], v181 offset:6144
	ds_read_b128 v[208:211], v181 offset:7168
	global_load_lds_dwordx4 v[172:173], off
	v_lshl_add_u64 v[172:173], s[0:1], 0, v[166:167]
	s_add_i32 m0, s17, 0xe000
	s_nop 0
	global_load_lds_dwordx4 v[172:173], off
	s_waitcnt vmcnt(8)
	s_waitcnt lgkmcnt(0)
	s_barrier
	s_waitcnt lgkmcnt(0)
	v_mfma_f32_16x16x32_bf16 v[156:159], v[96:99], v[168:171], v[156:159]
	v_mfma_f32_16x16x32_bf16 v[152:155], v[104:107], v[168:171], v[152:155]
	v_mfma_f32_16x16x32_bf16 v[144:147], v[96:99], v[188:191], v[144:147]
	v_mfma_f32_16x16x32_bf16 v[136:139], v[104:107], v[188:191], v[136:139]
	v_mfma_f32_16x16x32_bf16 v[92:95], v[96:99], v[196:199], v[92:95]
	v_mfma_f32_16x16x32_bf16 v[88:91], v[104:107], v[196:199], v[88:91]
	v_mfma_f32_16x16x32_bf16 v[80:83], v[96:99], v[204:207], v[80:83]
	v_mfma_f32_16x16x32_bf16 v[72:75], v[104:107], v[204:207], v[72:75]
	v_mfma_f32_16x16x32_bf16 v[156:159], v[100:103], v[184:187], v[156:159]
	v_mfma_f32_16x16x32_bf16 v[152:155], v[108:111], v[184:187], v[152:155]
	v_mfma_f32_16x16x32_bf16 v[144:147], v[100:103], v[192:195], v[144:147]
	v_mfma_f32_16x16x32_bf16 v[136:139], v[108:111], v[192:195], v[136:139]
	v_mfma_f32_16x16x32_bf16 v[92:95], v[100:103], v[200:203], v[92:95]
	v_mfma_f32_16x16x32_bf16 v[88:91], v[108:111], v[200:203], v[88:91]
	v_mfma_f32_16x16x32_bf16 v[80:83], v[100:103], v[208:211], v[80:83]
	v_mfma_f32_16x16x32_bf16 v[72:75], v[108:111], v[208:211], v[72:75]
	v_mfma_f32_16x16x32_bf16 v[148:151], v[112:115], v[168:171], v[148:151]
	v_mfma_f32_16x16x32_bf16 v[140:143], v[120:123], v[168:171], v[140:143]
	v_mfma_f32_16x16x32_bf16 v[132:135], v[112:115], v[188:191], v[132:135]
	v_mfma_f32_16x16x32_bf16 v[128:131], v[120:123], v[188:191], v[128:131]
	v_mfma_f32_16x16x32_bf16 v[84:87], v[112:115], v[196:199], v[84:87]
	v_mfma_f32_16x16x32_bf16 v[76:79], v[120:123], v[196:199], v[76:79]
	v_mfma_f32_16x16x32_bf16 v[68:71], v[112:115], v[204:207], v[68:71]
	v_mfma_f32_16x16x32_bf16 v[64:67], v[120:123], v[204:207], v[64:67]
	v_mfma_f32_16x16x32_bf16 v[148:151], v[116:119], v[184:187], v[148:151]
	v_mfma_f32_16x16x32_bf16 v[140:143], v[124:127], v[184:187], v[140:143]
	v_mfma_f32_16x16x32_bf16 v[132:135], v[116:119], v[192:195], v[132:135]
	v_mfma_f32_16x16x32_bf16 v[128:131], v[124:127], v[192:195], v[128:131]
	v_mfma_f32_16x16x32_bf16 v[84:87], v[116:119], v[200:203], v[84:87]
	v_mfma_f32_16x16x32_bf16 v[76:79], v[124:127], v[200:203], v[76:79]
	v_mfma_f32_16x16x32_bf16 v[68:71], v[116:119], v[208:211], v[68:71]
	v_mfma_f32_16x16x32_bf16 v[64:67], v[124:127], v[208:211], v[64:67]
	s_barrier
	s_add_i32 s0, s42, s15
	v_lshl_add_u64 v[172:173], s[24:25], 0, v[160:161]
	s_mov_b32 m0, s0
	ds_read_b128 v[168:171], v181 offset:16384
	ds_read_b128 v[184:187], v181 offset:17408
	ds_read_b128 v[188:191], v181 offset:18432
	ds_read_b128 v[192:195], v181 offset:19456
	ds_read_b128 v[196:199], v181 offset:20480
	ds_read_b128 v[200:203], v181 offset:21504
	ds_read_b128 v[204:207], v181 offset:22528
	ds_read_b128 v[208:211], v181 offset:23552
	global_load_lds_dwordx4 v[172:173], off
	s_add_i32 m0, s0, 0x2000
	s_add_u32 s0, s24, 0x160000
	v_lshl_add_u64 v[212:213], s[24:25], 0, v[162:163]
	s_addc_u32 s1, s25, 0
	s_add_i32 s52, s43, s15
	global_load_lds_dwordx4 v[212:213], off
	v_lshl_add_u64 v[214:215], s[0:1], 0, v[160:161]
	s_mov_b32 m0, s52
	v_lshl_add_u64 v[216:217], s[26:27], 0, v[162:163]
	global_load_lds_dwordx4 v[214:215], off
	v_lshl_add_u64 v[214:215], s[0:1], 0, v[162:163]
	s_add_i32 m0, s52, 0x2000
	s_nop 0
	global_load_lds_dwordx4 v[214:215], off
	v_lshl_add_u64 v[214:215], s[26:27], 0, v[160:161]
	s_mov_b32 m0, s17
	s_nop 0
	global_load_lds_dwordx4 v[214:215], off
	s_mov_b32 m0, s28
	s_nop 0
	global_load_lds_dwordx4 v[216:217], off
	s_waitcnt vmcnt(8)
	s_waitcnt lgkmcnt(0)
	s_barrier
; #define PG8_STAGE(bufoff, gbase, voff) do { _Pragma("unroll") for (int _i = 0; _i < 2; ++_i) \
;         __builtin_amdgcn_global_load_lds((const unsigned*)((const char*)(gbase) + (voff)[_i]), (LAS unsigned*)(lds + (bufoff) + ldsw + _i * 8192), 16, 0, 0); } while (0)
; #define PG8_LDA(dst, b, h) do { _Pragma("unroll") for (int m = 0; m < 4; ++m) _Pragma("unroll") for (int k = 0; k < 2; ++k) dst[m][k] = *(const LAS bf16x8*)(lds + PG8_SA(b, h) + aoff + m * 2048 + k * 1024); } while (0)
; #define PG8_LDB(dst, b, h) do { _Pragma("unroll") for (int n = 0; n < 2; ++n) _Pragma("unroll") for (int k = 0; k < 2; ++k) dst[n][k] = *(const LAS bf16x8*)(lds + PG8_SB(b, h) + boff + n * 2048 + k * 1024); } while (0)
; #define PG8_MMA(ai, bj, At, Bt) do { __builtin_amdgcn_s_setprio(1); _Pragma("unroll") for (int m = 0; m < 4; ++m) _Pragma("unroll") for (int n = 0; n < 2; ++n) _Pragma("unroll") for (int k = 0; k < 2; ++k) \
;         acc[ai][bj][m][n] = __builtin_amdgcn_mfma_f32_16x16x32_bf16(Bt[n][k], At[m][k], acc[ai][bj][m][n], 0, 0, 0); __builtin_amdgcn_s_setprio(0); } while (0)
; #define PG8_WAIT_V(n) asm volatile("s_waitcnt vmcnt(" #n ")" ::: "memory")
; #define PG8_WAIT_L(n) asm volatile("s_waitcnt lgkmcnt(" #n ")" ::: "memory")
; #define PG8_BAR __builtin_amdgcn_s_barrier()
; #define PG8_SCHED __builtin_amdgcn_sched_barrier(0)
; template <class Sched, class Epi, bool ALIGN_EPI, bool SP2>
; __device__ __forceinline__ void gemm_phase(LAS unsigned char* lds, const int K, const int lda, const int ldb, const Sched& S, const Epi& E) {
;     ...
;             PG8_WAIT_V(8); PG8_WAIT_L(0); PG8_BAR; PG8_MMA(1, 0, At, B0); PG8_MMA(1, 1, At, B1); PG8_BAR; PG8_SCHED;
;             PG8_LDB(B0, 1, 0); PG8_LDB(B1, 1, 1); PG8_SCHED; PG8_LDA(At, 1, 0); PG8_STAGE(PG8_SA(0, 1), a2 + hstepA, voffA);
;             PG8_WAIT_V(8); PG8_WAIT_L(0); PG8_BAR; PG8_MMA(0, 0, At, B0); PG8_MMA(0, 1, At, B1); PG8_BAR; PG8_SCHED;
	s_waitcnt lgkmcnt(0)
	v_mfma_f32_16x16x32_bf16 v[60:63], v[96:99], v[168:171], v[60:63]
	v_mfma_f32_16x16x32_bf16 v[56:59], v[104:107], v[168:171], v[56:59]
	v_mfma_f32_16x16x32_bf16 v[48:51], v[96:99], v[188:191], v[48:51]
	v_mfma_f32_16x16x32_bf16 v[40:43], v[104:107], v[188:191], v[40:43]
	v_mfma_f32_16x16x32_bf16 v[28:31], v[96:99], v[196:199], v[28:31]
	v_mfma_f32_16x16x32_bf16 v[24:27], v[104:107], v[196:199], v[24:27]
	v_mfma_f32_16x16x32_bf16 v[16:19], v[96:99], v[204:207], v[16:19]
	v_mfma_f32_16x16x32_bf16 v[8:11], v[104:107], v[204:207], v[8:11]
	v_mfma_f32_16x16x32_bf16 v[60:63], v[100:103], v[184:187], v[60:63]
	v_mfma_f32_16x16x32_bf16 v[56:59], v[108:111], v[184:187], v[56:59]
	v_mfma_f32_16x16x32_bf16 v[48:51], v[100:103], v[192:195], v[48:51]
	v_mfma_f32_16x16x32_bf16 v[40:43], v[108:111], v[192:195], v[40:43]
	v_mfma_f32_16x16x32_bf16 v[28:31], v[100:103], v[200:203], v[28:31]
	v_mfma_f32_16x16x32_bf16 v[24:27], v[108:111], v[200:203], v[24:27]
	v_mfma_f32_16x16x32_bf16 v[16:19], v[100:103], v[208:211], v[16:19]
	v_mfma_f32_16x16x32_bf16 v[8:11], v[108:111], v[208:211], v[8:11]
	v_mfma_f32_16x16x32_bf16 v[52:55], v[112:115], v[168:171], v[52:55]
	v_mfma_f32_16x16x32_bf16 v[44:47], v[120:123], v[168:171], v[44:47]
	v_mfma_f32_16x16x32_bf16 v[36:39], v[112:115], v[188:191], v[36:39]
	v_mfma_f32_16x16x32_bf16 v[32:35], v[120:123], v[188:191], v[32:35]
	v_mfma_f32_16x16x32_bf16 v[20:23], v[112:115], v[196:199], v[20:23]
	v_mfma_f32_16x16x32_bf16 v[12:15], v[120:123], v[196:199], v[12:15]
	v_mfma_f32_16x16x32_bf16 v[4:7], v[112:115], v[204:207], v[4:7]
	v_mfma_f32_16x16x32_bf16 v[0:3], v[120:123], v[204:207], v[0:3]
	v_mfma_f32_16x16x32_bf16 v[52:55], v[116:119], v[184:187], v[52:55]
	v_mfma_f32_16x16x32_bf16 v[44:47], v[124:127], v[184:187], v[44:47]
	v_mfma_f32_16x16x32_bf16 v[36:39], v[116:119], v[192:195], v[36:39]
	v_mfma_f32_16x16x32_bf16 v[32:35], v[124:127], v[192:195], v[32:35]
	v_mfma_f32_16x16x32_bf16 v[20:23], v[116:119], v[200:203], v[20:23]
	v_mfma_f32_16x16x32_bf16 v[12:15], v[124:127], v[200:203], v[12:15]
	v_mfma_f32_16x16x32_bf16 v[4:7], v[116:119], v[208:211], v[4:7]
	v_mfma_f32_16x16x32_bf16 v[0:3], v[124:127], v[208:211], v[0:3]
	s_barrier
	s_add_i32 s52, 0, 0x18000
	s_add_i32 s53, 0, 0x1c000
	v_add_u32_e32 v108, s52, v175
	v_add_u32_e32 v124, s53, v175
	ds_read_b128 v[96:99], v108
	ds_read_b128 v[100:103], v108 offset:1024
	ds_read_b128 v[104:107], v108 offset:2048
	ds_read_b128 v[108:111], v108 offset:3072
	ds_read_b128 v[112:115], v124
	ds_read_b128 v[116:119], v124 offset:1024
	ds_read_b128 v[120:123], v124 offset:2048
	ds_read_b128 v[124:127], v124 offset:3072
	s_add_u32 s0, s26, 0x160000
	s_addc_u32 s1, s27, 0
	s_mov_b32 m0, s29
	v_lshl_add_u64 v[218:219], s[0:1], 0, v[160:161]
	ds_read_b128 v[168:171], v181 offset:32768
	ds_read_b128 v[184:187], v181 offset:33792
	ds_read_b128 v[188:191], v181 offset:34816
	ds_read_b128 v[192:195], v181 offset:35840
	ds_read_b128 v[196:199], v181 offset:36864
	ds_read_b128 v[200:203], v181 offset:37888
	ds_read_b128 v[204:207], v181 offset:38912
	ds_read_b128 v[208:211], v181 offset:39936
	global_load_lds_dwordx4 v[218:219], off
	v_lshl_add_u64 v[218:219], s[0:1], 0, v[162:163]
	s_mov_b32 m0, s33
	s_nop 0
	global_load_lds_dwordx4 v[218:219], off
	s_waitcnt vmcnt(8)
	s_waitcnt lgkmcnt(0)
	s_barrier
	s_waitcnt lgkmcnt(0)
	v_mfma_f32_16x16x32_bf16 v[156:159], v[96:99], v[168:171], v[156:159]
	v_mfma_f32_16x16x32_bf16 v[152:155], v[104:107], v[168:171], v[152:155]
	v_mfma_f32_16x16x32_bf16 v[144:147], v[96:99], v[188:191], v[144:147]
	v_mfma_f32_16x16x32_bf16 v[136:139], v[104:107], v[188:191], v[136:139]
	v_mfma_f32_16x16x32_bf16 v[92:95], v[96:99], v[196:199], v[92:95]
	v_mfma_f32_16x16x32_bf16 v[88:91], v[104:107], v[196:199], v[88:91]
	v_mfma_f32_16x16x32_bf16 v[80:83], v[96:99], v[204:207], v[80:83]
	v_mfma_f32_16x16x32_bf16 v[72:75], v[104:107], v[204:207], v[72:75]
	v_mfma_f32_16x16x32_bf16 v[156:159], v[100:103], v[184:187], v[156:159]
	v_mfma_f32_16x16x32_bf16 v[152:155], v[108:111], v[184:187], v[152:155]
	v_mfma_f32_16x16x32_bf16 v[144:147], v[100:103], v[192:195], v[144:147]
	v_mfma_f32_16x16x32_bf16 v[136:139], v[108:111], v[192:195], v[136:139]
	v_mfma_f32_16x16x32_bf16 v[92:95], v[100:103], v[200:203], v[92:95]
	v_mfma_f32_16x16x32_bf16 v[88:91], v[108:111], v[200:203], v[88:91]
	v_mfma_f32_16x16x32_bf16 v[80:83], v[100:103], v[208:211], v[80:83]
	v_mfma_f32_16x16x32_bf16 v[72:75], v[108:111], v[208:211], v[72:75]
	v_mfma_f32_16x16x32_bf16 v[148:151], v[112:115], v[168:171], v[148:151]
	v_mfma_f32_16x16x32_bf16 v[140:143], v[120:123], v[168:171], v[140:143]
	v_mfma_f32_16x16x32_bf16 v[132:135], v[112:115], v[188:191], v[132:135]
	v_mfma_f32_16x16x32_bf16 v[128:131], v[120:123], v[188:191], v[128:131]
	v_mfma_f32_16x16x32_bf16 v[84:87], v[112:115], v[196:199], v[84:87]
	v_mfma_f32_16x16x32_bf16 v[76:79], v[120:123], v[196:199], v[76:79]
	v_mfma_f32_16x16x32_bf16 v[68:71], v[112:115], v[204:207], v[68:71]
	v_mfma_f32_16x16x32_bf16 v[64:67], v[120:123], v[204:207], v[64:67]
	v_mfma_f32_16x16x32_bf16 v[148:151], v[116:119], v[184:187], v[148:151]
	v_mfma_f32_16x16x32_bf16 v[140:143], v[124:127], v[184:187], v[140:143]
	v_mfma_f32_16x16x32_bf16 v[132:135], v[116:119], v[192:195], v[132:135]
	v_mfma_f32_16x16x32_bf16 v[128:131], v[124:127], v[192:195], v[128:131]
	v_mfma_f32_16x16x32_bf16 v[84:87], v[116:119], v[200:203], v[84:87]
	v_mfma_f32_16x16x32_bf16 v[76:79], v[124:127], v[200:203], v[76:79]
	v_mfma_f32_16x16x32_bf16 v[68:71], v[116:119], v[208:211], v[68:71]
	v_mfma_f32_16x16x32_bf16 v[64:67], v[124:127], v[208:211], v[64:67]
	s_barrier
; #define PG8_STAGE(bufoff, gbase, voff) do { _Pragma("unroll") for (int _i = 0; _i < 2; ++_i) \
;         __builtin_amdgcn_global_load_lds((const unsigned*)((const char*)(gbase) + (voff)[_i]), (LAS unsigned*)(lds + (bufoff) + ldsw + _i * 8192), 16, 0, 0); } while (0)
; #define PG8_LDA(dst, b, h) do { _Pragma("unroll") for (int m = 0; m < 4; ++m) _Pragma("unroll") for (int k = 0; k < 2; ++k) dst[m][k] = *(const LAS bf16x8*)(lds + PG8_SA(b, h) + aoff + m * 2048 + k * 1024); } while (0)
; #define PG8_MMA(ai, bj, At, Bt) do { __builtin_amdgcn_s_setprio(1); _Pragma("unroll") for (int m = 0; m < 4; ++m) _Pragma("unroll") for (int n = 0; n < 2; ++n) _Pragma("unroll") for (int k = 0; k < 2; ++k) \
;         acc[ai][bj][m][n] = __builtin_amdgcn_mfma_f32_16x16x32_bf16(Bt[n][k], At[m][k], acc[ai][bj][m][n], 0, 0, 0); __builtin_amdgcn_s_setprio(0); } while (0)
; #define PG8_WAIT_V(n) asm volatile("s_waitcnt vmcnt(" #n ")" ::: "memory")
; #define PG8_WAIT_L(n) asm volatile("s_waitcnt lgkmcnt(" #n ")" ::: "memory")
; #define PG8_BAR __builtin_amdgcn_s_barrier()
; #define PG8_SCHED __builtin_amdgcn_sched_barrier(0)
; template <class Sched, class Epi, bool ALIGN_EPI, bool SP2>
; __device__ __forceinline__ void gemm_phase(LAS unsigned char* lds, const int K, const int lda, const int ldb, const Sched& S, const Epi& E) {
;     ...
;             PG8_LDA(At, 1, 1); PG8_STAGE(PG8_SB(1, 0), b3, voffB); PG8_STAGE(PG8_SB(1, 1), b3 + hstepB, voffB); PG8_STAGE(PG8_SA(1, 0), a3, voffA);
;             PG8_WAIT_V(8); PG8_WAIT_L(0); PG8_BAR; PG8_MMA(1, 0, At, B0); PG8_MMA(1, 1, At, B1); PG8_BAR; PG8_SCHED;
;     ...
;         }
;         if constexpr (ALIGN_EPI) { if (wr == 0) PG8_BAR; }
	s_add_i32 s0, s52, s15
	v_lshl_add_u64 v[172:173], v[172:173], 0, s[10:11]
	s_mov_b32 m0, s0
	ds_read_b128 v[168:171], v181 offset:49152
	ds_read_b128 v[184:187], v181 offset:50176
	ds_read_b128 v[188:191], v181 offset:51200
	ds_read_b128 v[192:195], v181 offset:52224
	ds_read_b128 v[196:199], v181 offset:53248
	ds_read_b128 v[200:203], v181 offset:54272
	ds_read_b128 v[204:207], v181 offset:55296
	ds_read_b128 v[208:211], v181 offset:56320
	global_load_lds_dwordx4 v[172:173], off
	s_add_i32 m0, s0, 0x2000
	s_add_u32 s0, s24, 0x160080
	v_lshl_add_u64 v[172:173], v[212:213], 0, s[10:11]
	s_addc_u32 s1, s25, 0
	s_add_i32 s24, s53, s15
	global_load_lds_dwordx4 v[172:173], off
	v_lshl_add_u64 v[172:173], s[0:1], 0, v[160:161]
	s_mov_b32 m0, s24
	s_nop 0
	global_load_lds_dwordx4 v[172:173], off
	v_lshl_add_u64 v[172:173], s[0:1], 0, v[162:163]
	s_add_i32 m0, s24, 0x2000
	s_nop 0
	global_load_lds_dwordx4 v[172:173], off
	v_lshl_add_u64 v[172:173], v[214:215], 0, s[10:11]
	s_mov_b32 m0, s36
	s_nop 0
	global_load_lds_dwordx4 v[172:173], off
	v_lshl_add_u64 v[172:173], v[216:217], 0, s[10:11]
	s_mov_b32 m0, s37
	s_nop 0
	global_load_lds_dwordx4 v[172:173], off
	s_waitcnt vmcnt(8)
	s_waitcnt lgkmcnt(0)
	s_barrier
	s_waitcnt lgkmcnt(0)
	v_mfma_f32_16x16x32_bf16 v[60:63], v[96:99], v[168:171], v[60:63]
	v_mfma_f32_16x16x32_bf16 v[56:59], v[104:107], v[168:171], v[56:59]
	v_mfma_f32_16x16x32_bf16 v[48:51], v[96:99], v[188:191], v[48:51]
	v_mfma_f32_16x16x32_bf16 v[40:43], v[104:107], v[188:191], v[40:43]
	v_mfma_f32_16x16x32_bf16 v[28:31], v[96:99], v[196:199], v[28:31]
	v_mfma_f32_16x16x32_bf16 v[24:27], v[104:107], v[196:199], v[24:27]
	v_mfma_f32_16x16x32_bf16 v[16:19], v[96:99], v[204:207], v[16:19]
	v_mfma_f32_16x16x32_bf16 v[8:11], v[104:107], v[204:207], v[8:11]
	v_mfma_f32_16x16x32_bf16 v[60:63], v[100:103], v[184:187], v[60:63]
	v_mfma_f32_16x16x32_bf16 v[56:59], v[108:111], v[184:187], v[56:59]
	v_mfma_f32_16x16x32_bf16 v[48:51], v[100:103], v[192:195], v[48:51]
	v_mfma_f32_16x16x32_bf16 v[40:43], v[108:111], v[192:195], v[40:43]
	v_mfma_f32_16x16x32_bf16 v[28:31], v[100:103], v[200:203], v[28:31]
	v_mfma_f32_16x16x32_bf16 v[24:27], v[108:111], v[200:203], v[24:27]
	v_mfma_f32_16x16x32_bf16 v[16:19], v[100:103], v[208:211], v[16:19]
	v_mfma_f32_16x16x32_bf16 v[8:11], v[108:111], v[208:211], v[8:11]
	v_mfma_f32_16x16x32_bf16 v[52:55], v[112:115], v[168:171], v[52:55]
	v_mfma_f32_16x16x32_bf16 v[44:47], v[120:123], v[168:171], v[44:47]
	v_mfma_f32_16x16x32_bf16 v[36:39], v[112:115], v[188:191], v[36:39]
	v_mfma_f32_16x16x32_bf16 v[32:35], v[120:123], v[188:191], v[32:35]
	v_mfma_f32_16x16x32_bf16 v[20:23], v[112:115], v[196:199], v[20:23]
	v_mfma_f32_16x16x32_bf16 v[12:15], v[120:123], v[196:199], v[12:15]
	v_mfma_f32_16x16x32_bf16 v[4:7], v[112:115], v[204:207], v[4:7]
	v_mfma_f32_16x16x32_bf16 v[0:3], v[120:123], v[204:207], v[0:3]
	v_mfma_f32_16x16x32_bf16 v[52:55], v[116:119], v[184:187], v[52:55]
	v_mfma_f32_16x16x32_bf16 v[44:47], v[124:127], v[184:187], v[44:47]
	v_mfma_f32_16x16x32_bf16 v[36:39], v[116:119], v[192:195], v[36:39]
	v_mfma_f32_16x16x32_bf16 v[32:35], v[124:127], v[192:195], v[32:35]
	v_mfma_f32_16x16x32_bf16 v[20:23], v[116:119], v[200:203], v[20:23]
	v_mfma_f32_16x16x32_bf16 v[12:15], v[124:127], v[200:203], v[12:15]
	v_mfma_f32_16x16x32_bf16 v[4:7], v[116:119], v[208:211], v[4:7]
	v_mfma_f32_16x16x32_bf16 v[0:3], v[124:127], v[208:211], v[0:3]
	s_barrier
	s_add_i32 s51, s51, 2
	s_add_u32 s49, s49, 0x100
	s_addc_u32 s50, s50, 0
	s_cmpk_gt_u32 s51, 0x55
	s_mov_b64 s[0:1], s[4:5]
	s_cbranch_scc0 .LBB0_1120
	s_and_b64 vcc, exec, s[12:13]
	s_cbranch_vccz .LBB0_1123
	s_barrier
